# v11 + LDS-DMA loads in SGPR-base + 32-bit VGPR offset form (drops 77 v_lshl_add_u64 from load segments)
# speedup vs baseline: 1.0090x; 1.0090x over previous
.LBB0_80:
	s_add_u32 s2, s14, 0x100
	v_mov_b32_e32 v0, 0
	s_addc_u32 s8, s15, 0
	s_mov_b32 s9, -2
	v_mov_b32_e32 v1, v0
	v_mov_b32_e32 v2, v0
	v_mov_b32_e32 v3, v0
	v_mov_b32_e32 v6, v0
	s_waitcnt lgkmcnt(0)
	v_mov_b32_e32 v7, v0
	v_mov_b32_e32 v8, v0
	v_mov_b32_e32 v9, v0
	v_mov_b32_e32 v18, v0
	v_mov_b32_e32 v19, v0
	v_mov_b32_e32 v20, v0
	v_mov_b32_e32 v21, v0
	v_mov_b32_e32 v22, v0
	v_mov_b32_e32 v23, v0
	v_mov_b32_e32 v24, v0
	v_mov_b32_e32 v25, v0
	v_mov_b32_e32 v34, v0
	v_mov_b32_e32 v35, v0
	v_mov_b32_e32 v36, v0
	v_mov_b32_e32 v37, v0
	v_mov_b32_e32 v38, v0
	v_mov_b32_e32 v39, v0
	v_mov_b32_e32 v40, v0
	v_mov_b32_e32 v41, v0
	v_mov_b32_e32 v50, v0
	v_mov_b32_e32 v51, v0
	v_mov_b32_e32 v52, v0
	v_mov_b32_e32 v53, v0
	v_mov_b32_e32 v54, v0
	v_mov_b32_e32 v55, v0
	v_mov_b32_e32 v56, v0
	v_mov_b32_e32 v57, v0
	v_mov_b32_e32 v10, v0
	v_mov_b32_e32 v11, v0
	v_mov_b32_e32 v12, v0
	v_mov_b32_e32 v13, v0
	v_mov_b32_e32 v14, v0
	v_mov_b32_e32 v15, v0
	v_mov_b32_e32 v16, v0
	v_mov_b32_e32 v17, v0
	v_mov_b32_e32 v26, v0
	v_mov_b32_e32 v27, v0
	v_mov_b32_e32 v28, v0
	v_mov_b32_e32 v29, v0
	v_mov_b32_e32 v30, v0
	v_mov_b32_e32 v31, v0
	v_mov_b32_e32 v32, v0
	v_mov_b32_e32 v33, v0
	v_mov_b32_e32 v42, v0
	v_mov_b32_e32 v43, v0
	v_mov_b32_e32 v44, v0
	v_mov_b32_e32 v45, v0
	v_mov_b32_e32 v46, v0
	v_mov_b32_e32 v47, v0
	v_mov_b32_e32 v48, v0
	v_mov_b32_e32 v49, v0
	v_mov_b32_e32 v58, v0
	v_mov_b32_e32 v59, v0
	v_mov_b32_e32 v60, v0
	v_mov_b32_e32 v61, v0
	v_mov_b32_e32 v62, v0
	v_mov_b32_e32 v63, v0
	v_mov_b32_e32 v64, v0
	v_mov_b32_e32 v65, v0
	v_mov_b32_e32 v66, v0
	v_mov_b32_e32 v67, v0
	v_mov_b32_e32 v68, v0
	v_mov_b32_e32 v69, v0
	v_mov_b32_e32 v70, v0
	v_mov_b32_e32 v71, v0
	v_mov_b32_e32 v72, v0
	v_mov_b32_e32 v73, v0
	v_mov_b32_e32 v82, v0
	v_mov_b32_e32 v83, v0
	v_mov_b32_e32 v84, v0
	v_mov_b32_e32 v85, v0
	v_mov_b32_e32 v86, v0
	v_mov_b32_e32 v87, v0
	v_mov_b32_e32 v88, v0
	v_mov_b32_e32 v89, v0
	v_mov_b32_e32 v98, v0
	v_mov_b32_e32 v99, v0
	v_mov_b32_e32 v100, v0
	v_mov_b32_e32 v101, v0
	v_mov_b32_e32 v102, v0
	v_mov_b32_e32 v103, v0
	v_mov_b32_e32 v104, v0
	v_mov_b32_e32 v105, v0
	v_mov_b32_e32 v114, v0
	v_mov_b32_e32 v115, v0
	v_mov_b32_e32 v116, v0
	v_mov_b32_e32 v117, v0
	v_mov_b32_e32 v118, v0
	v_mov_b32_e32 v119, v0
	v_mov_b32_e32 v120, v0
	v_mov_b32_e32 v121, v0
	v_mov_b32_e32 v74, v0
	v_mov_b32_e32 v75, v0
	v_mov_b32_e32 v76, v0
	v_mov_b32_e32 v77, v0
	v_mov_b32_e32 v78, v0
	v_mov_b32_e32 v79, v0
	v_mov_b32_e32 v80, v0
	v_mov_b32_e32 v81, v0
	v_mov_b32_e32 v90, v0
	v_mov_b32_e32 v91, v0
	v_mov_b32_e32 v92, v0
	v_mov_b32_e32 v93, v0
	v_mov_b32_e32 v94, v0
	v_mov_b32_e32 v95, v0
	v_mov_b32_e32 v96, v0
	v_mov_b32_e32 v97, v0
	v_mov_b32_e32 v106, v0
	v_mov_b32_e32 v107, v0
	v_mov_b32_e32 v108, v0
	v_mov_b32_e32 v109, v0
	v_mov_b32_e32 v110, v0
	v_mov_b32_e32 v111, v0
	v_mov_b32_e32 v112, v0
	v_mov_b32_e32 v113, v0
	v_mov_b32_e32 v122, v0
	v_mov_b32_e32 v123, v0
	v_mov_b32_e32 v124, v0
	v_mov_b32_e32 v125, v0
	v_mov_b32_e32 v126, v0
	v_mov_b32_e32 v127, v0
	v_mov_b32_e32 v128, v0
	v_mov_b32_e32 v129, v0
	s_cmp_eq_u32 s36, 1
	s_cbranch_scc1 .LBB0_81
	s_add_u32 s14, s0, 0x100
	s_addc_u32 s15, s1, 0
	s_add_i32 s3, 0, 0x10000
	s_cmpk_eq_i32 s9, 0x7c
	s_cselect_b32 s27, s43, s15
	s_cselect_b32 s26, s42, s14
	v_add_u32_e32 v162, s3, v145
	s_cselect_b32 s23, s79, s8
	s_cselect_b32 s22, s78, s2
	s_add_i32 s4, 0, 0x14000
	ds_read_b128 v[140:143], v162
	ds_read_b128 v[148:151], v162 offset:1024
	ds_read_b128 v[172:175], v162 offset:2048
	ds_read_b128 v[190:193], v162 offset:3072
	v_add_u32_e32 v162, s4, v145
	ds_read_b128 v[194:197], v162
	ds_read_b128 v[198:201], v162 offset:1024
	ds_read_b128 v[202:205], v162 offset:2048
	ds_read_b128 v[206:209], v162 offset:3072
	s_add_i32 m0, s30, 0xc000
	ds_read_b128 v[210:213], v147
	ds_read_b128 v[214:217], v147 offset:1024
	ds_read_b128 v[218:221], v147 offset:2048
	ds_read_b128 v[222:225], v147 offset:3072
	ds_read_b128 v[226:229], v147 offset:4096
	ds_read_b128 v[230:233], v147 offset:5120
	ds_read_b128 v[234:237], v147 offset:6144
	ds_read_b128 v[238:241], v147 offset:7168
	global_load_lds_dwordx4 v136, s[0:1]
	s_add_i32 m0, s30, 0xe000
	s_nop 0
	global_load_lds_dwordx4 v138, s[0:1]
	s_waitcnt vmcnt(24)
	s_waitcnt lgkmcnt(0)
	s_barrier
	s_setprio 1
	s_waitcnt lgkmcnt(0)
	v_mfma_f32_16x16x32_bf16 v[126:129], v[140:143], v[210:213], v[126:129]
	v_mfma_f32_16x16x32_bf16 v[122:125], v[172:175], v[210:213], v[122:125]
	v_mfma_f32_16x16x32_bf16 v[110:113], v[140:143], v[218:221], v[110:113]
	v_mfma_f32_16x16x32_bf16 v[106:109], v[172:175], v[218:221], v[106:109]
	v_mfma_f32_16x16x32_bf16 v[94:97], v[140:143], v[226:229], v[94:97]
	v_mfma_f32_16x16x32_bf16 v[90:93], v[172:175], v[226:229], v[90:93]
	v_mfma_f32_16x16x32_bf16 v[78:81], v[140:143], v[234:237], v[78:81]
	v_mfma_f32_16x16x32_bf16 v[74:77], v[172:175], v[234:237], v[74:77]
	v_mfma_f32_16x16x32_bf16 v[126:129], v[148:151], v[214:217], v[126:129]
	v_mfma_f32_16x16x32_bf16 v[122:125], v[190:193], v[214:217], v[122:125]
	v_mfma_f32_16x16x32_bf16 v[110:113], v[148:151], v[222:225], v[110:113]
	v_mfma_f32_16x16x32_bf16 v[106:109], v[190:193], v[222:225], v[106:109]
	v_mfma_f32_16x16x32_bf16 v[94:97], v[148:151], v[230:233], v[94:97]
	v_mfma_f32_16x16x32_bf16 v[90:93], v[190:193], v[230:233], v[90:93]
	v_mfma_f32_16x16x32_bf16 v[78:81], v[148:151], v[238:241], v[78:81]
	v_mfma_f32_16x16x32_bf16 v[74:77], v[190:193], v[238:241], v[74:77]
	s_setprio 0
	s_setprio 1
	v_mfma_f32_16x16x32_bf16 v[118:121], v[194:197], v[210:213], v[118:121]
	v_mfma_f32_16x16x32_bf16 v[114:117], v[202:205], v[210:213], v[114:117]
	v_mfma_f32_16x16x32_bf16 v[102:105], v[194:197], v[218:221], v[102:105]
	v_mfma_f32_16x16x32_bf16 v[98:101], v[202:205], v[218:221], v[98:101]
	v_mfma_f32_16x16x32_bf16 v[86:89], v[194:197], v[226:229], v[86:89]
	v_mfma_f32_16x16x32_bf16 v[82:85], v[202:205], v[226:229], v[82:85]
	v_mfma_f32_16x16x32_bf16 v[70:73], v[194:197], v[234:237], v[70:73]
	v_mfma_f32_16x16x32_bf16 v[66:69], v[202:205], v[234:237], v[66:69]
	v_mfma_f32_16x16x32_bf16 v[118:121], v[198:201], v[214:217], v[118:121]
	v_mfma_f32_16x16x32_bf16 v[114:117], v[206:209], v[214:217], v[114:117]
	v_mfma_f32_16x16x32_bf16 v[102:105], v[198:201], v[222:225], v[102:105]
	v_mfma_f32_16x16x32_bf16 v[98:101], v[206:209], v[222:225], v[98:101]
	v_mfma_f32_16x16x32_bf16 v[86:89], v[198:201], v[230:233], v[86:89]
	v_mfma_f32_16x16x32_bf16 v[82:85], v[206:209], v[230:233], v[82:85]
	v_mfma_f32_16x16x32_bf16 v[70:73], v[198:201], v[238:241], v[70:73]
	v_mfma_f32_16x16x32_bf16 v[66:69], v[206:209], v[238:241], v[66:69]
	s_setprio 0
	s_barrier
	s_add_i32 s0, s3, s11
	v_lshl_add_u64 v[162:163], s[22:23], 0, v[4:5]
	s_mov_b32 m0, s0
	ds_read_b128 v[210:213], v147 offset:16384
	ds_read_b128 v[214:217], v147 offset:17408
	ds_read_b128 v[218:221], v147 offset:18432
	ds_read_b128 v[222:225], v147 offset:19456
	ds_read_b128 v[226:229], v147 offset:20480
	ds_read_b128 v[230:233], v147 offset:21504
	ds_read_b128 v[234:237], v147 offset:22528
	ds_read_b128 v[238:241], v147 offset:23552
	global_load_lds_dwordx4 v4, s[22:23]
	s_add_i32 m0, s0, 0x2000
	s_add_u32 s0, s22, 0x208000
	v_lshl_add_u64 v[166:167], s[22:23], 0, v[130:131]
	s_addc_u32 s1, s23, 0
	s_add_i32 s3, s4, s11
	global_load_lds_dwordx4 v130, s[22:23]
	s_mov_b32 m0, s3
	v_lshl_add_u64 v[180:181], s[26:27], 0, v[132:133]
	global_load_lds_dwordx4 v4, s[0:1]
	s_add_i32 m0, s3, 0x2000
	s_nop 0
	global_load_lds_dwordx4 v130, s[0:1]
	v_lshl_add_u64 v[176:177], s[26:27], 0, v[134:135]
	s_mov_b32 m0, s30
	s_nop 0
	global_load_lds_dwordx4 v134, s[26:27]
	s_mov_b32 m0, s31
	s_nop 0
	global_load_lds_dwordx4 v132, s[26:27]
	s_waitcnt vmcnt(24)
	s_waitcnt lgkmcnt(0)
	s_barrier
	s_setprio 1
	s_waitcnt lgkmcnt(0)
	v_mfma_f32_16x16x32_bf16 v[62:65], v[140:143], v[210:213], v[62:65]
	v_mfma_f32_16x16x32_bf16 v[58:61], v[172:175], v[210:213], v[58:61]
	v_mfma_f32_16x16x32_bf16 v[46:49], v[140:143], v[218:221], v[46:49]
	v_mfma_f32_16x16x32_bf16 v[42:45], v[172:175], v[218:221], v[42:45]
	v_mfma_f32_16x16x32_bf16 v[30:33], v[140:143], v[226:229], v[30:33]
	v_mfma_f32_16x16x32_bf16 v[26:29], v[172:175], v[226:229], v[26:29]
	v_mfma_f32_16x16x32_bf16 v[14:17], v[140:143], v[234:237], v[14:17]
	v_mfma_f32_16x16x32_bf16 v[10:13], v[172:175], v[234:237], v[10:13]
	v_mfma_f32_16x16x32_bf16 v[62:65], v[148:151], v[214:217], v[62:65]
	v_mfma_f32_16x16x32_bf16 v[58:61], v[190:193], v[214:217], v[58:61]
	v_mfma_f32_16x16x32_bf16 v[46:49], v[148:151], v[222:225], v[46:49]
	v_mfma_f32_16x16x32_bf16 v[42:45], v[190:193], v[222:225], v[42:45]
	v_mfma_f32_16x16x32_bf16 v[30:33], v[148:151], v[230:233], v[30:33]
	v_mfma_f32_16x16x32_bf16 v[26:29], v[190:193], v[230:233], v[26:29]
	v_mfma_f32_16x16x32_bf16 v[14:17], v[148:151], v[238:241], v[14:17]
	v_mfma_f32_16x16x32_bf16 v[10:13], v[190:193], v[238:241], v[10:13]
	s_setprio 0
	s_setprio 1
	v_mfma_f32_16x16x32_bf16 v[54:57], v[194:197], v[210:213], v[54:57]
	v_mfma_f32_16x16x32_bf16 v[50:53], v[202:205], v[210:213], v[50:53]
	v_mfma_f32_16x16x32_bf16 v[38:41], v[194:197], v[218:221], v[38:41]
	v_mfma_f32_16x16x32_bf16 v[34:37], v[202:205], v[218:221], v[34:37]
	v_mfma_f32_16x16x32_bf16 v[22:25], v[194:197], v[226:229], v[22:25]
	v_mfma_f32_16x16x32_bf16 v[18:21], v[202:205], v[226:229], v[18:21]
	v_mfma_f32_16x16x32_bf16 v[6:9], v[194:197], v[234:237], v[6:9]
	v_mfma_f32_16x16x32_bf16 v[0:3], v[202:205], v[234:237], v[0:3]
	v_mfma_f32_16x16x32_bf16 v[54:57], v[198:201], v[214:217], v[54:57]
	v_mfma_f32_16x16x32_bf16 v[50:53], v[206:209], v[214:217], v[50:53]
	v_mfma_f32_16x16x32_bf16 v[38:41], v[198:201], v[222:225], v[38:41]
	v_mfma_f32_16x16x32_bf16 v[34:37], v[206:209], v[222:225], v[34:37]
	v_mfma_f32_16x16x32_bf16 v[22:25], v[198:201], v[230:233], v[22:25]
	v_mfma_f32_16x16x32_bf16 v[18:21], v[206:209], v[230:233], v[18:21]
	v_mfma_f32_16x16x32_bf16 v[6:9], v[198:201], v[238:241], v[6:9]
	v_mfma_f32_16x16x32_bf16 v[0:3], v[206:209], v[238:241], v[0:3]
	s_setprio 0
	s_barrier
	s_branch .Lpeelmid_81
.LBB0_81:
	s_add_u32 s14, s0, 0x100
	s_addc_u32 s15, s1, 0
	s_add_i32 s3, 0, 0x10000
	s_cmpk_eq_i32 s9, 0x7c
	s_cselect_b32 s27, s43, s15
	s_cselect_b32 s26, s42, s14
	v_add_u32_e32 v162, s3, v145
	s_cselect_b32 s23, s79, s8
	s_cselect_b32 s22, s78, s2
	s_add_i32 s4, 0, 0x14000
	ds_read_b128 v[140:143], v162
	ds_read_b128 v[148:151], v162 offset:1024
	ds_read_b128 v[172:175], v162 offset:2048
	ds_read_b128 v[190:193], v162 offset:3072
	v_add_u32_e32 v162, s4, v145
	ds_read_b128 v[194:197], v162
	ds_read_b128 v[198:201], v162 offset:1024
	ds_read_b128 v[202:205], v162 offset:2048
	ds_read_b128 v[206:209], v162 offset:3072
	s_add_i32 m0, s30, 0xc000
	ds_read_b128 v[210:213], v147
	ds_read_b128 v[214:217], v147 offset:1024
	ds_read_b128 v[218:221], v147 offset:2048
	ds_read_b128 v[222:225], v147 offset:3072
	ds_read_b128 v[226:229], v147 offset:4096
	ds_read_b128 v[230:233], v147 offset:5120
	ds_read_b128 v[234:237], v147 offset:6144
	ds_read_b128 v[238:241], v147 offset:7168
	global_load_lds_dwordx4 v136, s[0:1]
	s_add_i32 m0, s30, 0xe000
	s_nop 0
	global_load_lds_dwordx4 v138, s[0:1]
	s_waitcnt vmcnt(8)
	s_waitcnt lgkmcnt(0)
	s_barrier
	s_setprio 1
	s_waitcnt lgkmcnt(0)
	v_mfma_f32_16x16x32_bf16 v[126:129], v[140:143], v[210:213], v[126:129]
	v_mfma_f32_16x16x32_bf16 v[122:125], v[172:175], v[210:213], v[122:125]
	v_mfma_f32_16x16x32_bf16 v[110:113], v[140:143], v[218:221], v[110:113]
	v_mfma_f32_16x16x32_bf16 v[106:109], v[172:175], v[218:221], v[106:109]
	v_mfma_f32_16x16x32_bf16 v[94:97], v[140:143], v[226:229], v[94:97]
	v_mfma_f32_16x16x32_bf16 v[90:93], v[172:175], v[226:229], v[90:93]
	v_mfma_f32_16x16x32_bf16 v[78:81], v[140:143], v[234:237], v[78:81]
	v_mfma_f32_16x16x32_bf16 v[74:77], v[172:175], v[234:237], v[74:77]
	v_mfma_f32_16x16x32_bf16 v[126:129], v[148:151], v[214:217], v[126:129]
	v_mfma_f32_16x16x32_bf16 v[122:125], v[190:193], v[214:217], v[122:125]
	v_mfma_f32_16x16x32_bf16 v[110:113], v[148:151], v[222:225], v[110:113]
	v_mfma_f32_16x16x32_bf16 v[106:109], v[190:193], v[222:225], v[106:109]
	v_mfma_f32_16x16x32_bf16 v[94:97], v[148:151], v[230:233], v[94:97]
	v_mfma_f32_16x16x32_bf16 v[90:93], v[190:193], v[230:233], v[90:93]
	v_mfma_f32_16x16x32_bf16 v[78:81], v[148:151], v[238:241], v[78:81]
	v_mfma_f32_16x16x32_bf16 v[74:77], v[190:193], v[238:241], v[74:77]
	s_setprio 0
	s_setprio 1
	v_mfma_f32_16x16x32_bf16 v[118:121], v[194:197], v[210:213], v[118:121]
	v_mfma_f32_16x16x32_bf16 v[114:117], v[202:205], v[210:213], v[114:117]
	v_mfma_f32_16x16x32_bf16 v[102:105], v[194:197], v[218:221], v[102:105]
	v_mfma_f32_16x16x32_bf16 v[98:101], v[202:205], v[218:221], v[98:101]
	v_mfma_f32_16x16x32_bf16 v[86:89], v[194:197], v[226:229], v[86:89]
	v_mfma_f32_16x16x32_bf16 v[82:85], v[202:205], v[226:229], v[82:85]
	v_mfma_f32_16x16x32_bf16 v[70:73], v[194:197], v[234:237], v[70:73]
	v_mfma_f32_16x16x32_bf16 v[66:69], v[202:205], v[234:237], v[66:69]
	v_mfma_f32_16x16x32_bf16 v[118:121], v[198:201], v[214:217], v[118:121]
	v_mfma_f32_16x16x32_bf16 v[114:117], v[206:209], v[214:217], v[114:117]
	v_mfma_f32_16x16x32_bf16 v[102:105], v[198:201], v[222:225], v[102:105]
	v_mfma_f32_16x16x32_bf16 v[98:101], v[206:209], v[222:225], v[98:101]
	v_mfma_f32_16x16x32_bf16 v[86:89], v[198:201], v[230:233], v[86:89]
	v_mfma_f32_16x16x32_bf16 v[82:85], v[206:209], v[230:233], v[82:85]
	v_mfma_f32_16x16x32_bf16 v[70:73], v[198:201], v[238:241], v[70:73]
	v_mfma_f32_16x16x32_bf16 v[66:69], v[206:209], v[238:241], v[66:69]
	s_setprio 0
	s_barrier
	s_add_i32 s0, s3, s11
	v_lshl_add_u64 v[162:163], s[22:23], 0, v[4:5]
	s_mov_b32 m0, s0
	ds_read_b128 v[210:213], v147 offset:16384
	ds_read_b128 v[214:217], v147 offset:17408
	ds_read_b128 v[218:221], v147 offset:18432
	ds_read_b128 v[222:225], v147 offset:19456
	ds_read_b128 v[226:229], v147 offset:20480
	ds_read_b128 v[230:233], v147 offset:21504
	ds_read_b128 v[234:237], v147 offset:22528
	ds_read_b128 v[238:241], v147 offset:23552
	global_load_lds_dwordx4 v4, s[22:23]
	s_add_i32 m0, s0, 0x2000
	s_add_u32 s0, s22, 0x208000
	v_lshl_add_u64 v[166:167], s[22:23], 0, v[130:131]
	s_addc_u32 s1, s23, 0
	s_add_i32 s3, s4, s11
	global_load_lds_dwordx4 v130, s[22:23]
	s_mov_b32 m0, s3
	v_lshl_add_u64 v[180:181], s[26:27], 0, v[132:133]
	global_load_lds_dwordx4 v4, s[0:1]
	s_add_i32 m0, s3, 0x2000
	s_nop 0
	global_load_lds_dwordx4 v130, s[0:1]
	v_lshl_add_u64 v[176:177], s[26:27], 0, v[134:135]
	s_mov_b32 m0, s30
	s_nop 0
	global_load_lds_dwordx4 v134, s[26:27]
	s_mov_b32 m0, s31
	s_nop 0
	global_load_lds_dwordx4 v132, s[26:27]
	s_waitcnt vmcnt(8)
	s_waitcnt lgkmcnt(0)
	s_barrier
	s_setprio 1
	s_waitcnt lgkmcnt(0)
	v_mfma_f32_16x16x32_bf16 v[62:65], v[140:143], v[210:213], v[62:65]
	v_mfma_f32_16x16x32_bf16 v[58:61], v[172:175], v[210:213], v[58:61]
	v_mfma_f32_16x16x32_bf16 v[46:49], v[140:143], v[218:221], v[46:49]
	v_mfma_f32_16x16x32_bf16 v[42:45], v[172:175], v[218:221], v[42:45]
	v_mfma_f32_16x16x32_bf16 v[30:33], v[140:143], v[226:229], v[30:33]
	v_mfma_f32_16x16x32_bf16 v[26:29], v[172:175], v[226:229], v[26:29]
	v_mfma_f32_16x16x32_bf16 v[14:17], v[140:143], v[234:237], v[14:17]
	v_mfma_f32_16x16x32_bf16 v[10:13], v[172:175], v[234:237], v[10:13]
	v_mfma_f32_16x16x32_bf16 v[62:65], v[148:151], v[214:217], v[62:65]
	v_mfma_f32_16x16x32_bf16 v[58:61], v[190:193], v[214:217], v[58:61]
	v_mfma_f32_16x16x32_bf16 v[46:49], v[148:151], v[222:225], v[46:49]
	v_mfma_f32_16x16x32_bf16 v[42:45], v[190:193], v[222:225], v[42:45]
	v_mfma_f32_16x16x32_bf16 v[30:33], v[148:151], v[230:233], v[30:33]
	v_mfma_f32_16x16x32_bf16 v[26:29], v[190:193], v[230:233], v[26:29]
	v_mfma_f32_16x16x32_bf16 v[14:17], v[148:151], v[238:241], v[14:17]
	v_mfma_f32_16x16x32_bf16 v[10:13], v[190:193], v[238:241], v[10:13]
	s_setprio 0
	s_setprio 1
	v_mfma_f32_16x16x32_bf16 v[54:57], v[194:197], v[210:213], v[54:57]
	v_mfma_f32_16x16x32_bf16 v[50:53], v[202:205], v[210:213], v[50:53]
	v_mfma_f32_16x16x32_bf16 v[38:41], v[194:197], v[218:221], v[38:41]
	v_mfma_f32_16x16x32_bf16 v[34:37], v[202:205], v[218:221], v[34:37]
	v_mfma_f32_16x16x32_bf16 v[22:25], v[194:197], v[226:229], v[22:25]
	v_mfma_f32_16x16x32_bf16 v[18:21], v[202:205], v[226:229], v[18:21]
	v_mfma_f32_16x16x32_bf16 v[6:9], v[194:197], v[234:237], v[6:9]
	v_mfma_f32_16x16x32_bf16 v[0:3], v[202:205], v[234:237], v[0:3]
	v_mfma_f32_16x16x32_bf16 v[54:57], v[198:201], v[214:217], v[54:57]
	v_mfma_f32_16x16x32_bf16 v[50:53], v[206:209], v[214:217], v[50:53]
	v_mfma_f32_16x16x32_bf16 v[38:41], v[198:201], v[222:225], v[38:41]
	v_mfma_f32_16x16x32_bf16 v[34:37], v[206:209], v[222:225], v[34:37]
	v_mfma_f32_16x16x32_bf16 v[22:25], v[198:201], v[230:233], v[22:25]
	v_mfma_f32_16x16x32_bf16 v[18:21], v[206:209], v[230:233], v[18:21]
	v_mfma_f32_16x16x32_bf16 v[6:9], v[198:201], v[238:241], v[6:9]
	v_mfma_f32_16x16x32_bf16 v[0:3], v[206:209], v[238:241], v[0:3]
	s_setprio 0
	s_barrier
.Lpeelmid_81:
	s_add_i32 s3, 0, 0x18000
	v_add_u32_e32 v164, s3, v145
	s_add_i32 s4, 0, 0x1c000
	ds_read_b128 v[140:143], v164
	ds_read_b128 v[148:151], v164 offset:1024
	ds_read_b128 v[172:175], v164 offset:2048
	ds_read_b128 v[190:193], v164 offset:3072
	v_add_u32_e32 v164, s4, v145
	ds_read_b128 v[194:197], v164
	ds_read_b128 v[198:201], v164 offset:1024
	ds_read_b128 v[202:205], v164 offset:2048
	ds_read_b128 v[206:209], v164 offset:3072
	s_add_u32 s0, s26, 0x208000
	s_addc_u32 s1, s27, 0
	s_mov_b32 m0, s34
	ds_read_b128 v[210:213], v147 offset:32768
	ds_read_b128 v[214:217], v147 offset:33792
	ds_read_b128 v[218:221], v147 offset:34816
	ds_read_b128 v[222:225], v147 offset:35840
	ds_read_b128 v[226:229], v147 offset:36864
	ds_read_b128 v[230:233], v147 offset:37888
	ds_read_b128 v[234:237], v147 offset:38912
	ds_read_b128 v[238:241], v147 offset:39936
	global_load_lds_dwordx4 v134, s[0:1]
	v_lshl_add_u64 v[242:243], s[0:1], 0, v[132:133]
	s_mov_b32 m0, s35
	s_nop 0
	global_load_lds_dwordx4 v132, s[0:1]
	s_waitcnt vmcnt(8)
	s_waitcnt lgkmcnt(0)
	s_barrier
	s_setprio 1
	s_waitcnt lgkmcnt(0)
	v_mfma_f32_16x16x32_bf16 v[126:129], v[140:143], v[210:213], v[126:129]
	v_mfma_f32_16x16x32_bf16 v[122:125], v[172:175], v[210:213], v[122:125]
	v_mfma_f32_16x16x32_bf16 v[110:113], v[140:143], v[218:221], v[110:113]
	v_mfma_f32_16x16x32_bf16 v[106:109], v[172:175], v[218:221], v[106:109]
	v_mfma_f32_16x16x32_bf16 v[94:97], v[140:143], v[226:229], v[94:97]
	v_mfma_f32_16x16x32_bf16 v[90:93], v[172:175], v[226:229], v[90:93]
	v_mfma_f32_16x16x32_bf16 v[78:81], v[140:143], v[234:237], v[78:81]
	v_mfma_f32_16x16x32_bf16 v[74:77], v[172:175], v[234:237], v[74:77]
	v_mfma_f32_16x16x32_bf16 v[126:129], v[148:151], v[214:217], v[126:129]
	v_mfma_f32_16x16x32_bf16 v[122:125], v[190:193], v[214:217], v[122:125]
	v_mfma_f32_16x16x32_bf16 v[110:113], v[148:151], v[222:225], v[110:113]
	v_mfma_f32_16x16x32_bf16 v[106:109], v[190:193], v[222:225], v[106:109]
	v_mfma_f32_16x16x32_bf16 v[94:97], v[148:151], v[230:233], v[94:97]
	v_mfma_f32_16x16x32_bf16 v[90:93], v[190:193], v[230:233], v[90:93]
	v_mfma_f32_16x16x32_bf16 v[78:81], v[148:151], v[238:241], v[78:81]
	v_mfma_f32_16x16x32_bf16 v[74:77], v[190:193], v[238:241], v[74:77]
	s_setprio 0
	s_setprio 1
	v_mfma_f32_16x16x32_bf16 v[118:121], v[194:197], v[210:213], v[118:121]
	v_mfma_f32_16x16x32_bf16 v[114:117], v[202:205], v[210:213], v[114:117]
	v_mfma_f32_16x16x32_bf16 v[102:105], v[194:197], v[218:221], v[102:105]
	v_mfma_f32_16x16x32_bf16 v[98:101], v[202:205], v[218:221], v[98:101]
	v_mfma_f32_16x16x32_bf16 v[86:89], v[194:197], v[226:229], v[86:89]
	v_mfma_f32_16x16x32_bf16 v[82:85], v[202:205], v[226:229], v[82:85]
	v_mfma_f32_16x16x32_bf16 v[70:73], v[194:197], v[234:237], v[70:73]
	v_mfma_f32_16x16x32_bf16 v[66:69], v[202:205], v[234:237], v[66:69]
	v_mfma_f32_16x16x32_bf16 v[118:121], v[198:201], v[214:217], v[118:121]
	v_mfma_f32_16x16x32_bf16 v[114:117], v[206:209], v[214:217], v[114:117]
	v_mfma_f32_16x16x32_bf16 v[102:105], v[198:201], v[222:225], v[102:105]
	v_mfma_f32_16x16x32_bf16 v[98:101], v[206:209], v[222:225], v[98:101]
	v_mfma_f32_16x16x32_bf16 v[86:89], v[198:201], v[230:233], v[86:89]
	v_mfma_f32_16x16x32_bf16 v[82:85], v[206:209], v[230:233], v[82:85]
	v_mfma_f32_16x16x32_bf16 v[70:73], v[198:201], v[238:241], v[70:73]
	v_mfma_f32_16x16x32_bf16 v[66:69], v[206:209], v[238:241], v[66:69]
	s_setprio 0
	s_barrier
	s_add_i32 s0, s3, s11
	v_lshl_add_u64 v[162:163], v[162:163], 0, s[70:71]
	s_mov_b32 m0, s0
	ds_read_b128 v[210:213], v147 offset:49152
	ds_read_b128 v[214:217], v147 offset:50176
	ds_read_b128 v[218:221], v147 offset:51200
	ds_read_b128 v[222:225], v147 offset:52224
	ds_read_b128 v[226:229], v147 offset:53248
	ds_read_b128 v[230:233], v147 offset:54272
	ds_read_b128 v[234:237], v147 offset:55296
	ds_read_b128 v[238:241], v147 offset:56320
	global_load_lds_dwordx4 v[162:163], off
	s_add_i32 m0, s0, 0x2000
	s_add_u32 s0, s22, 0x208080
	v_lshl_add_u64 v[162:163], v[166:167], 0, s[70:71]
	s_addc_u32 s1, s23, 0
	s_add_i32 s3, s4, s11
	global_load_lds_dwordx4 v[162:163], off
	s_mov_b32 m0, s3
	s_nop 0
	global_load_lds_dwordx4 v4, s[0:1]
	s_add_i32 m0, s3, 0x2000
	s_nop 0
	global_load_lds_dwordx4 v130, s[0:1]
	v_lshl_add_u64 v[162:163], v[176:177], 0, s[70:71]
	s_mov_b32 m0, s51
	s_nop 0
	global_load_lds_dwordx4 v[162:163], off
	v_lshl_add_u64 v[162:163], v[180:181], 0, s[70:71]
	s_mov_b32 m0, s52
	s_nop 0
	global_load_lds_dwordx4 v[162:163], off
	s_waitcnt vmcnt(8)
	s_waitcnt lgkmcnt(0)
	s_barrier
	s_setprio 1
	s_waitcnt lgkmcnt(0)
	v_mfma_f32_16x16x32_bf16 v[62:65], v[140:143], v[210:213], v[62:65]
	v_mfma_f32_16x16x32_bf16 v[58:61], v[172:175], v[210:213], v[58:61]
	v_mfma_f32_16x16x32_bf16 v[46:49], v[140:143], v[218:221], v[46:49]
	v_mfma_f32_16x16x32_bf16 v[42:45], v[172:175], v[218:221], v[42:45]
	v_mfma_f32_16x16x32_bf16 v[30:33], v[140:143], v[226:229], v[30:33]
	v_mfma_f32_16x16x32_bf16 v[26:29], v[172:175], v[226:229], v[26:29]
	v_mfma_f32_16x16x32_bf16 v[14:17], v[140:143], v[234:237], v[14:17]
	v_mfma_f32_16x16x32_bf16 v[10:13], v[172:175], v[234:237], v[10:13]
	v_mfma_f32_16x16x32_bf16 v[62:65], v[148:151], v[214:217], v[62:65]
	v_mfma_f32_16x16x32_bf16 v[58:61], v[190:193], v[214:217], v[58:61]
	v_mfma_f32_16x16x32_bf16 v[46:49], v[148:151], v[222:225], v[46:49]
	v_mfma_f32_16x16x32_bf16 v[42:45], v[190:193], v[222:225], v[42:45]
	v_mfma_f32_16x16x32_bf16 v[30:33], v[148:151], v[230:233], v[30:33]
	v_mfma_f32_16x16x32_bf16 v[26:29], v[190:193], v[230:233], v[26:29]
	v_mfma_f32_16x16x32_bf16 v[14:17], v[148:151], v[238:241], v[14:17]
	v_mfma_f32_16x16x32_bf16 v[10:13], v[190:193], v[238:241], v[10:13]
	s_setprio 0
	s_setprio 1
	v_mfma_f32_16x16x32_bf16 v[54:57], v[194:197], v[210:213], v[54:57]
	v_mfma_f32_16x16x32_bf16 v[50:53], v[202:205], v[210:213], v[50:53]
	v_mfma_f32_16x16x32_bf16 v[38:41], v[194:197], v[218:221], v[38:41]
	v_mfma_f32_16x16x32_bf16 v[34:37], v[202:205], v[218:221], v[34:37]
	v_mfma_f32_16x16x32_bf16 v[22:25], v[194:197], v[226:229], v[22:25]
	v_mfma_f32_16x16x32_bf16 v[18:21], v[202:205], v[226:229], v[18:21]
	v_mfma_f32_16x16x32_bf16 v[6:9], v[194:197], v[234:237], v[6:9]
	v_mfma_f32_16x16x32_bf16 v[0:3], v[202:205], v[234:237], v[0:3]
	v_mfma_f32_16x16x32_bf16 v[54:57], v[198:201], v[214:217], v[54:57]
	v_mfma_f32_16x16x32_bf16 v[50:53], v[206:209], v[214:217], v[50:53]
	v_mfma_f32_16x16x32_bf16 v[38:41], v[198:201], v[222:225], v[38:41]
	v_mfma_f32_16x16x32_bf16 v[34:37], v[206:209], v[222:225], v[34:37]
	v_mfma_f32_16x16x32_bf16 v[22:25], v[198:201], v[230:233], v[22:25]
	v_mfma_f32_16x16x32_bf16 v[18:21], v[206:209], v[230:233], v[18:21]
	v_mfma_f32_16x16x32_bf16 v[6:9], v[198:201], v[238:241], v[6:9]
	v_mfma_f32_16x16x32_bf16 v[0:3], v[206:209], v[238:241], v[0:3]
	s_setprio 0
	s_barrier
	s_add_i32 s9, s9, 2
	s_add_u32 s2, s2, 0x100
	s_addc_u32 s8, s8, 0
	s_cmpk_gt_u32 s9, 0x7d
	s_mov_b64 s[0:1], s[14:15]
	s_cbranch_scc0 .LBB0_81
	s_and_b64 vcc, exec, s[48:49]
	s_cbranch_vccz .LBB0_84
	s_barrier

.LBB0_123:
	s_ashr_i32 s3, s51, 24
	s_lshl_b32 s2, s51, 8
	s_andn2_b32 s3, s3, 63
	s_add_i32 s2, s3, s2
	s_ashr_i32 s3, s2, 31
	s_lshl_b64 s[2:3], s[2:3], 12
	s_add_u32 s48, s11, s2
	s_addc_u32 s49, s26, s3
	s_and_b64 s[2:3], s[38:39], exec
	s_cselect_b32 s2, s49, s1
	s_cselect_b32 s8, s48, s0
	s_ashr_i32 s47, s46, 31
	s_lshl_b64 s[4:5], s[46:47], 20
	v_readlane_b32 s6, v254, 1
	v_readlane_b32 s7, v254, 2
	s_add_u32 s78, s6, s4
	s_addc_u32 s79, s7, s5
	s_and_b64 s[4:5], s[38:39], exec
	s_cselect_b32 s10, s79, s15
	s_cselect_b32 s24, s78, s14
	s_add_u32 s22, s0, 0x80080
	s_addc_u32 s23, s1, 0
	s_add_u32 s9, s14, 0x100
	v_mov_b32_e32 v0, 0
	s_addc_u32 s25, s15, 0
	s_mov_b32 s28, -2
	v_mov_b32_e32 v1, v0
	v_mov_b32_e32 v2, v0
	v_mov_b32_e32 v3, v0
	v_mov_b32_e32 v6, v0
	v_mov_b32_e32 v7, v0
	v_mov_b32_e32 v8, v0
	v_mov_b32_e32 v9, v0
	v_mov_b32_e32 v10, v0
	v_mov_b32_e32 v11, v0
	v_mov_b32_e32 v12, v0
	v_mov_b32_e32 v13, v0
	v_mov_b32_e32 v14, v0
	v_mov_b32_e32 v15, v0
	v_mov_b32_e32 v16, v0
	v_mov_b32_e32 v17, v0
	v_mov_b32_e32 v18, v0
	v_mov_b32_e32 v19, v0
	v_mov_b32_e32 v20, v0
	v_mov_b32_e32 v21, v0
	v_mov_b32_e32 v22, v0
	v_mov_b32_e32 v23, v0
	v_mov_b32_e32 v24, v0
	v_mov_b32_e32 v25, v0
	v_mov_b32_e32 v26, v0
	v_mov_b32_e32 v27, v0
	v_mov_b32_e32 v28, v0
	v_mov_b32_e32 v29, v0
	v_mov_b32_e32 v30, v0
	v_mov_b32_e32 v31, v0
	v_mov_b32_e32 v32, v0
	v_mov_b32_e32 v33, v0
	v_mov_b32_e32 v58, v0
	v_mov_b32_e32 v59, v0
	v_mov_b32_e32 v60, v0
	v_mov_b32_e32 v61, v0
	v_mov_b32_e32 v62, v0
	v_mov_b32_e32 v63, v0
	v_mov_b32_e32 v64, v0
	v_mov_b32_e32 v65, v0
	v_mov_b32_e32 v74, v0
	v_mov_b32_e32 v75, v0
	v_mov_b32_e32 v76, v0
	v_mov_b32_e32 v77, v0
	v_mov_b32_e32 v78, v0
	v_mov_b32_e32 v79, v0
	v_mov_b32_e32 v80, v0
	v_mov_b32_e32 v81, v0
	v_mov_b32_e32 v82, v0
	v_mov_b32_e32 v83, v0
	v_mov_b32_e32 v84, v0
	v_mov_b32_e32 v85, v0
	v_mov_b32_e32 v86, v0
	v_mov_b32_e32 v87, v0
	v_mov_b32_e32 v88, v0
	v_mov_b32_e32 v89, v0
	v_mov_b32_e32 v90, v0
	v_mov_b32_e32 v91, v0
	v_mov_b32_e32 v92, v0
	v_mov_b32_e32 v93, v0
	v_mov_b32_e32 v94, v0
	v_mov_b32_e32 v95, v0
	v_mov_b32_e32 v96, v0
	v_mov_b32_e32 v97, v0
	v_mov_b32_e32 v34, v0
	v_mov_b32_e32 v35, v0
	v_mov_b32_e32 v36, v0
	v_mov_b32_e32 v37, v0
	v_mov_b32_e32 v38, v0
	v_mov_b32_e32 v39, v0
	v_mov_b32_e32 v40, v0
	v_mov_b32_e32 v41, v0
	v_mov_b32_e32 v42, v0
	v_mov_b32_e32 v43, v0
	v_mov_b32_e32 v44, v0
	v_mov_b32_e32 v45, v0
	v_mov_b32_e32 v46, v0
	v_mov_b32_e32 v47, v0
	v_mov_b32_e32 v48, v0
	v_mov_b32_e32 v49, v0
	v_mov_b32_e32 v50, v0
	v_mov_b32_e32 v51, v0
	v_mov_b32_e32 v52, v0
	v_mov_b32_e32 v53, v0
	v_mov_b32_e32 v54, v0
	v_mov_b32_e32 v55, v0
	v_mov_b32_e32 v56, v0
	v_mov_b32_e32 v57, v0
	v_mov_b32_e32 v66, v0
	v_mov_b32_e32 v67, v0
	v_mov_b32_e32 v68, v0
	v_mov_b32_e32 v69, v0
	v_mov_b32_e32 v70, v0
	v_mov_b32_e32 v71, v0
	v_mov_b32_e32 v72, v0
	v_mov_b32_e32 v73, v0
	v_mov_b32_e32 v98, v0
	v_mov_b32_e32 v99, v0
	v_mov_b32_e32 v100, v0
	v_mov_b32_e32 v101, v0
	v_mov_b32_e32 v102, v0
	v_mov_b32_e32 v103, v0
	v_mov_b32_e32 v104, v0
	v_mov_b32_e32 v105, v0
	v_mov_b32_e32 v106, v0
	v_mov_b32_e32 v107, v0
	v_mov_b32_e32 v108, v0
	v_mov_b32_e32 v109, v0
	v_mov_b32_e32 v110, v0
	v_mov_b32_e32 v111, v0
	v_mov_b32_e32 v112, v0
	v_mov_b32_e32 v113, v0
	v_mov_b32_e32 v114, v0
	v_mov_b32_e32 v115, v0
	v_mov_b32_e32 v116, v0
	v_mov_b32_e32 v117, v0
	v_mov_b32_e32 v118, v0
	v_mov_b32_e32 v119, v0
	v_mov_b32_e32 v120, v0
	v_mov_b32_e32 v121, v0
	v_mov_b32_e32 v122, v0
	v_mov_b32_e32 v123, v0
	v_mov_b32_e32 v124, v0
	v_mov_b32_e32 v125, v0
	v_mov_b32_e32 v126, v0
	v_mov_b32_e32 v127, v0
	v_mov_b32_e32 v128, v0
	v_mov_b32_e32 v129, v0
	s_cmp_eq_u32 s50, 1
	s_cbranch_scc1 .LBB0_124
	s_add_u32 s0, s22, 0xfff80080
	s_addc_u32 s1, s23, -1
	s_add_i32 s3, 0, 0x10000
	s_cmp_eq_u32 s28, 28
	s_cselect_b32 s15, s2, s1
	s_cselect_b32 s14, s8, s0
	v_add_u32_e32 v162, s3, v141
	s_cselect_b32 s1, s10, s25
	s_cselect_b32 s0, s24, s9
	s_add_i32 s6, 0, 0x14000
	ds_read_b128 v[144:147], v162
	ds_read_b128 v[148:151], v162 offset:1024
	ds_read_b128 v[172:175], v162 offset:2048
	ds_read_b128 v[190:193], v162 offset:3072
	v_add_u32_e32 v162, s6, v141
	ds_read_b128 v[194:197], v162
	ds_read_b128 v[198:201], v162 offset:1024
	ds_read_b128 v[202:205], v162 offset:2048
	ds_read_b128 v[206:209], v162 offset:3072
	s_add_i32 m0, s30, 0xc000
	ds_read_b128 v[210:213], v143
	ds_read_b128 v[214:217], v143 offset:1024
	ds_read_b128 v[218:221], v143 offset:2048
	ds_read_b128 v[222:225], v143 offset:3072
	ds_read_b128 v[226:229], v143 offset:4096
	ds_read_b128 v[230:233], v143 offset:5120
	ds_read_b128 v[234:237], v143 offset:6144
	ds_read_b128 v[238:241], v143 offset:7168
	global_load_lds_dwordx4 v136, s[22:23]
	s_add_i32 m0, s30, 0xe000
	s_nop 0
	global_load_lds_dwordx4 v138, s[22:23]
	s_waitcnt vmcnt(24)
	s_waitcnt lgkmcnt(0)
	s_barrier
	s_setprio 1
	s_waitcnt lgkmcnt(0)
	v_mfma_f32_16x16x32_bf16 v[126:129], v[144:147], v[210:213], v[126:129]
	v_mfma_f32_16x16x32_bf16 v[122:125], v[172:175], v[210:213], v[122:125]
	v_mfma_f32_16x16x32_bf16 v[118:121], v[144:147], v[218:221], v[118:121]
	v_mfma_f32_16x16x32_bf16 v[114:117], v[172:175], v[218:221], v[114:117]
	v_mfma_f32_16x16x32_bf16 v[110:113], v[144:147], v[226:229], v[110:113]
	v_mfma_f32_16x16x32_bf16 v[106:109], v[172:175], v[226:229], v[106:109]
	v_mfma_f32_16x16x32_bf16 v[102:105], v[144:147], v[234:237], v[102:105]
	v_mfma_f32_16x16x32_bf16 v[98:101], v[172:175], v[234:237], v[98:101]
	v_mfma_f32_16x16x32_bf16 v[126:129], v[148:151], v[214:217], v[126:129]
	v_mfma_f32_16x16x32_bf16 v[122:125], v[190:193], v[214:217], v[122:125]
	v_mfma_f32_16x16x32_bf16 v[118:121], v[148:151], v[222:225], v[118:121]
	v_mfma_f32_16x16x32_bf16 v[114:117], v[190:193], v[222:225], v[114:117]
	v_mfma_f32_16x16x32_bf16 v[110:113], v[148:151], v[230:233], v[110:113]
	v_mfma_f32_16x16x32_bf16 v[106:109], v[190:193], v[230:233], v[106:109]
	v_mfma_f32_16x16x32_bf16 v[102:105], v[148:151], v[238:241], v[102:105]
	v_mfma_f32_16x16x32_bf16 v[98:101], v[190:193], v[238:241], v[98:101]
	s_setprio 0
	s_setprio 1
	v_mfma_f32_16x16x32_bf16 v[70:73], v[194:197], v[210:213], v[70:73]
	v_mfma_f32_16x16x32_bf16 v[66:69], v[202:205], v[210:213], v[66:69]
	v_mfma_f32_16x16x32_bf16 v[54:57], v[194:197], v[218:221], v[54:57]
	v_mfma_f32_16x16x32_bf16 v[50:53], v[202:205], v[218:221], v[50:53]
	v_mfma_f32_16x16x32_bf16 v[46:49], v[194:197], v[226:229], v[46:49]
	v_mfma_f32_16x16x32_bf16 v[42:45], v[202:205], v[226:229], v[42:45]
	v_mfma_f32_16x16x32_bf16 v[38:41], v[194:197], v[234:237], v[38:41]
	v_mfma_f32_16x16x32_bf16 v[34:37], v[202:205], v[234:237], v[34:37]
	v_mfma_f32_16x16x32_bf16 v[70:73], v[198:201], v[214:217], v[70:73]
	v_mfma_f32_16x16x32_bf16 v[66:69], v[206:209], v[214:217], v[66:69]
	v_mfma_f32_16x16x32_bf16 v[54:57], v[198:201], v[222:225], v[54:57]
	v_mfma_f32_16x16x32_bf16 v[50:53], v[206:209], v[222:225], v[50:53]
	v_mfma_f32_16x16x32_bf16 v[46:49], v[198:201], v[230:233], v[46:49]
	v_mfma_f32_16x16x32_bf16 v[42:45], v[206:209], v[230:233], v[42:45]
	v_mfma_f32_16x16x32_bf16 v[38:41], v[198:201], v[238:241], v[38:41]
	v_mfma_f32_16x16x32_bf16 v[34:37], v[206:209], v[238:241], v[34:37]
	s_setprio 0
	s_barrier
	s_add_i32 s3, s3, s27
	v_lshl_add_u64 v[162:163], s[0:1], 0, v[4:5]
	s_mov_b32 m0, s3
	ds_read_b128 v[210:213], v143 offset:16384
	ds_read_b128 v[214:217], v143 offset:17408
	ds_read_b128 v[218:221], v143 offset:18432
	ds_read_b128 v[222:225], v143 offset:19456
	ds_read_b128 v[226:229], v143 offset:20480
	ds_read_b128 v[230:233], v143 offset:21504
	ds_read_b128 v[234:237], v143 offset:22528
	ds_read_b128 v[238:241], v143 offset:23552
	global_load_lds_dwordx4 v4, s[0:1]
	s_add_i32 m0, s3, 0x2000
	s_add_u32 s4, s0, 0x80000
	v_lshl_add_u64 v[166:167], s[0:1], 0, v[130:131]
	s_addc_u32 s5, s1, 0
	s_add_i32 s3, s6, s27
	global_load_lds_dwordx4 v130, s[0:1]
	s_mov_b32 m0, s3
	v_lshl_add_u64 v[180:181], s[14:15], 0, v[132:133]
	global_load_lds_dwordx4 v4, s[4:5]
	s_add_i32 m0, s3, 0x2000
	s_nop 0
	global_load_lds_dwordx4 v130, s[4:5]
	v_lshl_add_u64 v[176:177], s[14:15], 0, v[134:135]
	s_mov_b32 m0, s30
	s_nop 0
	global_load_lds_dwordx4 v134, s[14:15]
	s_mov_b32 m0, s31
	s_nop 0
	global_load_lds_dwordx4 v132, s[14:15]
	s_waitcnt vmcnt(24)
	s_waitcnt lgkmcnt(0)
	s_barrier
	s_setprio 1
	s_waitcnt lgkmcnt(0)
	v_mfma_f32_16x16x32_bf16 v[94:97], v[144:147], v[210:213], v[94:97]
	v_mfma_f32_16x16x32_bf16 v[90:93], v[172:175], v[210:213], v[90:93]
	v_mfma_f32_16x16x32_bf16 v[86:89], v[144:147], v[218:221], v[86:89]
	v_mfma_f32_16x16x32_bf16 v[82:85], v[172:175], v[218:221], v[82:85]
	v_mfma_f32_16x16x32_bf16 v[78:81], v[144:147], v[226:229], v[78:81]
	v_mfma_f32_16x16x32_bf16 v[74:77], v[172:175], v[226:229], v[74:77]
	v_mfma_f32_16x16x32_bf16 v[62:65], v[144:147], v[234:237], v[62:65]
	v_mfma_f32_16x16x32_bf16 v[58:61], v[172:175], v[234:237], v[58:61]
	v_mfma_f32_16x16x32_bf16 v[94:97], v[148:151], v[214:217], v[94:97]
	v_mfma_f32_16x16x32_bf16 v[90:93], v[190:193], v[214:217], v[90:93]
	v_mfma_f32_16x16x32_bf16 v[86:89], v[148:151], v[222:225], v[86:89]
	v_mfma_f32_16x16x32_bf16 v[82:85], v[190:193], v[222:225], v[82:85]
	v_mfma_f32_16x16x32_bf16 v[78:81], v[148:151], v[230:233], v[78:81]
	v_mfma_f32_16x16x32_bf16 v[74:77], v[190:193], v[230:233], v[74:77]
	v_mfma_f32_16x16x32_bf16 v[62:65], v[148:151], v[238:241], v[62:65]
	v_mfma_f32_16x16x32_bf16 v[58:61], v[190:193], v[238:241], v[58:61]
	s_setprio 0
	s_setprio 1
	v_mfma_f32_16x16x32_bf16 v[30:33], v[194:197], v[210:213], v[30:33]
	v_mfma_f32_16x16x32_bf16 v[26:29], v[202:205], v[210:213], v[26:29]
	v_mfma_f32_16x16x32_bf16 v[22:25], v[194:197], v[218:221], v[22:25]
	v_mfma_f32_16x16x32_bf16 v[18:21], v[202:205], v[218:221], v[18:21]
	v_mfma_f32_16x16x32_bf16 v[14:17], v[194:197], v[226:229], v[14:17]
	v_mfma_f32_16x16x32_bf16 v[10:13], v[202:205], v[226:229], v[10:13]
	v_mfma_f32_16x16x32_bf16 v[6:9], v[194:197], v[234:237], v[6:9]
	v_mfma_f32_16x16x32_bf16 v[0:3], v[202:205], v[234:237], v[0:3]
	v_mfma_f32_16x16x32_bf16 v[30:33], v[198:201], v[214:217], v[30:33]
	v_mfma_f32_16x16x32_bf16 v[26:29], v[206:209], v[214:217], v[26:29]
	v_mfma_f32_16x16x32_bf16 v[22:25], v[198:201], v[222:225], v[22:25]
	v_mfma_f32_16x16x32_bf16 v[18:21], v[206:209], v[222:225], v[18:21]
	v_mfma_f32_16x16x32_bf16 v[14:17], v[198:201], v[230:233], v[14:17]
	v_mfma_f32_16x16x32_bf16 v[10:13], v[206:209], v[230:233], v[10:13]
	v_mfma_f32_16x16x32_bf16 v[6:9], v[198:201], v[238:241], v[6:9]
	v_mfma_f32_16x16x32_bf16 v[0:3], v[206:209], v[238:241], v[0:3]
	s_setprio 0
	s_barrier
	s_branch .Lpeelmid_124
.LBB0_124:
	s_add_u32 s0, s22, 0xfff80080
	s_addc_u32 s1, s23, -1
	s_add_i32 s3, 0, 0x10000
	s_cmp_eq_u32 s28, 28
	s_cselect_b32 s15, s2, s1
	s_cselect_b32 s14, s8, s0
	v_add_u32_e32 v162, s3, v141
	s_cselect_b32 s1, s10, s25
	s_cselect_b32 s0, s24, s9
	s_add_i32 s6, 0, 0x14000
	ds_read_b128 v[144:147], v162
	ds_read_b128 v[148:151], v162 offset:1024
	ds_read_b128 v[172:175], v162 offset:2048
	ds_read_b128 v[190:193], v162 offset:3072
	v_add_u32_e32 v162, s6, v141
	ds_read_b128 v[194:197], v162
	ds_read_b128 v[198:201], v162 offset:1024
	ds_read_b128 v[202:205], v162 offset:2048
	ds_read_b128 v[206:209], v162 offset:3072
	s_add_i32 m0, s30, 0xc000
	ds_read_b128 v[210:213], v143
	ds_read_b128 v[214:217], v143 offset:1024
	ds_read_b128 v[218:221], v143 offset:2048
	ds_read_b128 v[222:225], v143 offset:3072
	ds_read_b128 v[226:229], v143 offset:4096
	ds_read_b128 v[230:233], v143 offset:5120
	ds_read_b128 v[234:237], v143 offset:6144
	ds_read_b128 v[238:241], v143 offset:7168
	global_load_lds_dwordx4 v136, s[22:23]
	s_add_i32 m0, s30, 0xe000
	s_nop 0
	global_load_lds_dwordx4 v138, s[22:23]
	s_waitcnt vmcnt(8)
	s_waitcnt lgkmcnt(0)
	s_barrier
	s_setprio 1
	s_waitcnt lgkmcnt(0)
	v_mfma_f32_16x16x32_bf16 v[126:129], v[144:147], v[210:213], v[126:129]
	v_mfma_f32_16x16x32_bf16 v[122:125], v[172:175], v[210:213], v[122:125]
	v_mfma_f32_16x16x32_bf16 v[118:121], v[144:147], v[218:221], v[118:121]
	v_mfma_f32_16x16x32_bf16 v[114:117], v[172:175], v[218:221], v[114:117]
	v_mfma_f32_16x16x32_bf16 v[110:113], v[144:147], v[226:229], v[110:113]
	v_mfma_f32_16x16x32_bf16 v[106:109], v[172:175], v[226:229], v[106:109]
	v_mfma_f32_16x16x32_bf16 v[102:105], v[144:147], v[234:237], v[102:105]
	v_mfma_f32_16x16x32_bf16 v[98:101], v[172:175], v[234:237], v[98:101]
	v_mfma_f32_16x16x32_bf16 v[126:129], v[148:151], v[214:217], v[126:129]
	v_mfma_f32_16x16x32_bf16 v[122:125], v[190:193], v[214:217], v[122:125]
	v_mfma_f32_16x16x32_bf16 v[118:121], v[148:151], v[222:225], v[118:121]
	v_mfma_f32_16x16x32_bf16 v[114:117], v[190:193], v[222:225], v[114:117]
	v_mfma_f32_16x16x32_bf16 v[110:113], v[148:151], v[230:233], v[110:113]
	v_mfma_f32_16x16x32_bf16 v[106:109], v[190:193], v[230:233], v[106:109]
	v_mfma_f32_16x16x32_bf16 v[102:105], v[148:151], v[238:241], v[102:105]
	v_mfma_f32_16x16x32_bf16 v[98:101], v[190:193], v[238:241], v[98:101]
	s_setprio 0
	s_setprio 1
	v_mfma_f32_16x16x32_bf16 v[70:73], v[194:197], v[210:213], v[70:73]
	v_mfma_f32_16x16x32_bf16 v[66:69], v[202:205], v[210:213], v[66:69]
	v_mfma_f32_16x16x32_bf16 v[54:57], v[194:197], v[218:221], v[54:57]
	v_mfma_f32_16x16x32_bf16 v[50:53], v[202:205], v[218:221], v[50:53]
	v_mfma_f32_16x16x32_bf16 v[46:49], v[194:197], v[226:229], v[46:49]
	v_mfma_f32_16x16x32_bf16 v[42:45], v[202:205], v[226:229], v[42:45]
	v_mfma_f32_16x16x32_bf16 v[38:41], v[194:197], v[234:237], v[38:41]
	v_mfma_f32_16x16x32_bf16 v[34:37], v[202:205], v[234:237], v[34:37]
	v_mfma_f32_16x16x32_bf16 v[70:73], v[198:201], v[214:217], v[70:73]
	v_mfma_f32_16x16x32_bf16 v[66:69], v[206:209], v[214:217], v[66:69]
	v_mfma_f32_16x16x32_bf16 v[54:57], v[198:201], v[222:225], v[54:57]
	v_mfma_f32_16x16x32_bf16 v[50:53], v[206:209], v[222:225], v[50:53]
	v_mfma_f32_16x16x32_bf16 v[46:49], v[198:201], v[230:233], v[46:49]
	v_mfma_f32_16x16x32_bf16 v[42:45], v[206:209], v[230:233], v[42:45]
	v_mfma_f32_16x16x32_bf16 v[38:41], v[198:201], v[238:241], v[38:41]
	v_mfma_f32_16x16x32_bf16 v[34:37], v[206:209], v[238:241], v[34:37]
	s_setprio 0
	s_barrier
	s_add_i32 s3, s3, s27
	v_lshl_add_u64 v[162:163], s[0:1], 0, v[4:5]
	s_mov_b32 m0, s3
	ds_read_b128 v[210:213], v143 offset:16384
	ds_read_b128 v[214:217], v143 offset:17408
	ds_read_b128 v[218:221], v143 offset:18432
	ds_read_b128 v[222:225], v143 offset:19456
	ds_read_b128 v[226:229], v143 offset:20480
	ds_read_b128 v[230:233], v143 offset:21504
	ds_read_b128 v[234:237], v143 offset:22528
	ds_read_b128 v[238:241], v143 offset:23552
	global_load_lds_dwordx4 v4, s[0:1]
	s_add_i32 m0, s3, 0x2000
	s_add_u32 s4, s0, 0x80000
	v_lshl_add_u64 v[166:167], s[0:1], 0, v[130:131]
	s_addc_u32 s5, s1, 0
	s_add_i32 s3, s6, s27
	global_load_lds_dwordx4 v130, s[0:1]
	s_mov_b32 m0, s3
	v_lshl_add_u64 v[180:181], s[14:15], 0, v[132:133]
	global_load_lds_dwordx4 v4, s[4:5]
	s_add_i32 m0, s3, 0x2000
	s_nop 0
	global_load_lds_dwordx4 v130, s[4:5]
	v_lshl_add_u64 v[176:177], s[14:15], 0, v[134:135]
	s_mov_b32 m0, s30
	s_nop 0
	global_load_lds_dwordx4 v134, s[14:15]
	s_mov_b32 m0, s31
	s_nop 0
	global_load_lds_dwordx4 v132, s[14:15]
	s_waitcnt vmcnt(8)
	s_waitcnt lgkmcnt(0)
	s_barrier
	s_setprio 1
	s_waitcnt lgkmcnt(0)
	v_mfma_f32_16x16x32_bf16 v[94:97], v[144:147], v[210:213], v[94:97]
	v_mfma_f32_16x16x32_bf16 v[90:93], v[172:175], v[210:213], v[90:93]
	v_mfma_f32_16x16x32_bf16 v[86:89], v[144:147], v[218:221], v[86:89]
	v_mfma_f32_16x16x32_bf16 v[82:85], v[172:175], v[218:221], v[82:85]
	v_mfma_f32_16x16x32_bf16 v[78:81], v[144:147], v[226:229], v[78:81]
	v_mfma_f32_16x16x32_bf16 v[74:77], v[172:175], v[226:229], v[74:77]
	v_mfma_f32_16x16x32_bf16 v[62:65], v[144:147], v[234:237], v[62:65]
	v_mfma_f32_16x16x32_bf16 v[58:61], v[172:175], v[234:237], v[58:61]
	v_mfma_f32_16x16x32_bf16 v[94:97], v[148:151], v[214:217], v[94:97]
	v_mfma_f32_16x16x32_bf16 v[90:93], v[190:193], v[214:217], v[90:93]
	v_mfma_f32_16x16x32_bf16 v[86:89], v[148:151], v[222:225], v[86:89]
	v_mfma_f32_16x16x32_bf16 v[82:85], v[190:193], v[222:225], v[82:85]
	v_mfma_f32_16x16x32_bf16 v[78:81], v[148:151], v[230:233], v[78:81]
	v_mfma_f32_16x16x32_bf16 v[74:77], v[190:193], v[230:233], v[74:77]
	v_mfma_f32_16x16x32_bf16 v[62:65], v[148:151], v[238:241], v[62:65]
	v_mfma_f32_16x16x32_bf16 v[58:61], v[190:193], v[238:241], v[58:61]
	s_setprio 0
	s_setprio 1
	v_mfma_f32_16x16x32_bf16 v[30:33], v[194:197], v[210:213], v[30:33]
	v_mfma_f32_16x16x32_bf16 v[26:29], v[202:205], v[210:213], v[26:29]
	v_mfma_f32_16x16x32_bf16 v[22:25], v[194:197], v[218:221], v[22:25]
	v_mfma_f32_16x16x32_bf16 v[18:21], v[202:205], v[218:221], v[18:21]
	v_mfma_f32_16x16x32_bf16 v[14:17], v[194:197], v[226:229], v[14:17]
	v_mfma_f32_16x16x32_bf16 v[10:13], v[202:205], v[226:229], v[10:13]
	v_mfma_f32_16x16x32_bf16 v[6:9], v[194:197], v[234:237], v[6:9]
	v_mfma_f32_16x16x32_bf16 v[0:3], v[202:205], v[234:237], v[0:3]
	v_mfma_f32_16x16x32_bf16 v[30:33], v[198:201], v[214:217], v[30:33]
	v_mfma_f32_16x16x32_bf16 v[26:29], v[206:209], v[214:217], v[26:29]
	v_mfma_f32_16x16x32_bf16 v[22:25], v[198:201], v[222:225], v[22:25]
	v_mfma_f32_16x16x32_bf16 v[18:21], v[206:209], v[222:225], v[18:21]
	v_mfma_f32_16x16x32_bf16 v[14:17], v[198:201], v[230:233], v[14:17]
	v_mfma_f32_16x16x32_bf16 v[10:13], v[206:209], v[230:233], v[10:13]
	v_mfma_f32_16x16x32_bf16 v[6:9], v[198:201], v[238:241], v[6:9]
	v_mfma_f32_16x16x32_bf16 v[0:3], v[206:209], v[238:241], v[0:3]
	s_setprio 0
	s_barrier
.Lpeelmid_124:
	s_add_i32 s3, 0, 0x18000
	v_add_u32_e32 v164, s3, v141
	s_add_i32 s6, 0, 0x1c000
	ds_read_b128 v[144:147], v164
	ds_read_b128 v[148:151], v164 offset:1024
	ds_read_b128 v[172:175], v164 offset:2048
	ds_read_b128 v[190:193], v164 offset:3072
	v_add_u32_e32 v164, s6, v141
	ds_read_b128 v[194:197], v164
	ds_read_b128 v[198:201], v164 offset:1024
	ds_read_b128 v[202:205], v164 offset:2048
	ds_read_b128 v[206:209], v164 offset:3072
	s_add_u32 s4, s14, 0x80000
	s_addc_u32 s5, s15, 0
	s_mov_b32 m0, s34
	ds_read_b128 v[210:213], v143 offset:32768
	ds_read_b128 v[214:217], v143 offset:33792
	ds_read_b128 v[218:221], v143 offset:34816
	ds_read_b128 v[222:225], v143 offset:35840
	ds_read_b128 v[226:229], v143 offset:36864
	ds_read_b128 v[230:233], v143 offset:37888
	ds_read_b128 v[234:237], v143 offset:38912
	ds_read_b128 v[238:241], v143 offset:39936
	global_load_lds_dwordx4 v134, s[4:5]
	v_lshl_add_u64 v[242:243], s[4:5], 0, v[132:133]
	s_mov_b32 m0, s35
	s_nop 0
	global_load_lds_dwordx4 v132, s[4:5]
	s_waitcnt vmcnt(8)
	s_waitcnt lgkmcnt(0)
	s_barrier
	s_setprio 1
	s_waitcnt lgkmcnt(0)
	v_mfma_f32_16x16x32_bf16 v[126:129], v[144:147], v[210:213], v[126:129]
	v_mfma_f32_16x16x32_bf16 v[122:125], v[172:175], v[210:213], v[122:125]
	v_mfma_f32_16x16x32_bf16 v[118:121], v[144:147], v[218:221], v[118:121]
	v_mfma_f32_16x16x32_bf16 v[114:117], v[172:175], v[218:221], v[114:117]
	v_mfma_f32_16x16x32_bf16 v[110:113], v[144:147], v[226:229], v[110:113]
	v_mfma_f32_16x16x32_bf16 v[106:109], v[172:175], v[226:229], v[106:109]
	v_mfma_f32_16x16x32_bf16 v[102:105], v[144:147], v[234:237], v[102:105]
	v_mfma_f32_16x16x32_bf16 v[98:101], v[172:175], v[234:237], v[98:101]
	v_mfma_f32_16x16x32_bf16 v[126:129], v[148:151], v[214:217], v[126:129]
	v_mfma_f32_16x16x32_bf16 v[122:125], v[190:193], v[214:217], v[122:125]
	v_mfma_f32_16x16x32_bf16 v[118:121], v[148:151], v[222:225], v[118:121]
	v_mfma_f32_16x16x32_bf16 v[114:117], v[190:193], v[222:225], v[114:117]
	v_mfma_f32_16x16x32_bf16 v[110:113], v[148:151], v[230:233], v[110:113]
	v_mfma_f32_16x16x32_bf16 v[106:109], v[190:193], v[230:233], v[106:109]
	v_mfma_f32_16x16x32_bf16 v[102:105], v[148:151], v[238:241], v[102:105]
	v_mfma_f32_16x16x32_bf16 v[98:101], v[190:193], v[238:241], v[98:101]
	s_setprio 0
	s_setprio 1
	v_mfma_f32_16x16x32_bf16 v[70:73], v[194:197], v[210:213], v[70:73]
	v_mfma_f32_16x16x32_bf16 v[66:69], v[202:205], v[210:213], v[66:69]
	v_mfma_f32_16x16x32_bf16 v[54:57], v[194:197], v[218:221], v[54:57]
	v_mfma_f32_16x16x32_bf16 v[50:53], v[202:205], v[218:221], v[50:53]
	v_mfma_f32_16x16x32_bf16 v[46:49], v[194:197], v[226:229], v[46:49]
	v_mfma_f32_16x16x32_bf16 v[42:45], v[202:205], v[226:229], v[42:45]
	v_mfma_f32_16x16x32_bf16 v[38:41], v[194:197], v[234:237], v[38:41]
	v_mfma_f32_16x16x32_bf16 v[34:37], v[202:205], v[234:237], v[34:37]
	v_mfma_f32_16x16x32_bf16 v[70:73], v[198:201], v[214:217], v[70:73]
	v_mfma_f32_16x16x32_bf16 v[66:69], v[206:209], v[214:217], v[66:69]
	v_mfma_f32_16x16x32_bf16 v[54:57], v[198:201], v[222:225], v[54:57]
	v_mfma_f32_16x16x32_bf16 v[50:53], v[206:209], v[222:225], v[50:53]
	v_mfma_f32_16x16x32_bf16 v[46:49], v[198:201], v[230:233], v[46:49]
	v_mfma_f32_16x16x32_bf16 v[42:45], v[206:209], v[230:233], v[42:45]
	v_mfma_f32_16x16x32_bf16 v[38:41], v[198:201], v[238:241], v[38:41]
	v_mfma_f32_16x16x32_bf16 v[34:37], v[206:209], v[238:241], v[34:37]
	s_setprio 0
	s_barrier
	s_add_i32 s3, s3, s27
	v_lshl_add_u64 v[162:163], v[162:163], 0, s[70:71]
	s_mov_b32 m0, s3
	ds_read_b128 v[210:213], v143 offset:49152
	ds_read_b128 v[214:217], v143 offset:50176
	ds_read_b128 v[218:221], v143 offset:51200
	ds_read_b128 v[222:225], v143 offset:52224
	ds_read_b128 v[226:229], v143 offset:53248
	ds_read_b128 v[230:233], v143 offset:54272
	ds_read_b128 v[234:237], v143 offset:55296
	ds_read_b128 v[238:241], v143 offset:56320
	global_load_lds_dwordx4 v[162:163], off
	s_add_i32 m0, s3, 0x2000
	s_add_u32 s0, s0, 0x80080
	v_lshl_add_u64 v[162:163], v[166:167], 0, s[70:71]
	s_addc_u32 s1, s1, 0
	s_add_i32 s3, s6, s27
	global_load_lds_dwordx4 v[162:163], off
	s_mov_b32 m0, s3
	s_nop 0
	global_load_lds_dwordx4 v4, s[0:1]
	s_add_i32 m0, s3, 0x2000
	s_nop 0
	global_load_lds_dwordx4 v130, s[0:1]
	v_lshl_add_u64 v[162:163], v[176:177], 0, s[70:71]
	s_mov_b32 m0, s36
	s_nop 0
	global_load_lds_dwordx4 v[162:163], off
	v_lshl_add_u64 v[162:163], v[180:181], 0, s[70:71]
	s_mov_b32 m0, s37
	s_nop 0
	global_load_lds_dwordx4 v[162:163], off
	s_waitcnt vmcnt(8)
	s_waitcnt lgkmcnt(0)
	s_barrier
	s_setprio 1
	s_waitcnt lgkmcnt(0)
	v_mfma_f32_16x16x32_bf16 v[94:97], v[144:147], v[210:213], v[94:97]
	v_mfma_f32_16x16x32_bf16 v[90:93], v[172:175], v[210:213], v[90:93]
	v_mfma_f32_16x16x32_bf16 v[86:89], v[144:147], v[218:221], v[86:89]
	v_mfma_f32_16x16x32_bf16 v[82:85], v[172:175], v[218:221], v[82:85]
	v_mfma_f32_16x16x32_bf16 v[78:81], v[144:147], v[226:229], v[78:81]
	v_mfma_f32_16x16x32_bf16 v[74:77], v[172:175], v[226:229], v[74:77]
	v_mfma_f32_16x16x32_bf16 v[62:65], v[144:147], v[234:237], v[62:65]
	v_mfma_f32_16x16x32_bf16 v[58:61], v[172:175], v[234:237], v[58:61]
	v_mfma_f32_16x16x32_bf16 v[94:97], v[148:151], v[214:217], v[94:97]
	v_mfma_f32_16x16x32_bf16 v[90:93], v[190:193], v[214:217], v[90:93]
	v_mfma_f32_16x16x32_bf16 v[86:89], v[148:151], v[222:225], v[86:89]
	v_mfma_f32_16x16x32_bf16 v[82:85], v[190:193], v[222:225], v[82:85]
	v_mfma_f32_16x16x32_bf16 v[78:81], v[148:151], v[230:233], v[78:81]
	v_mfma_f32_16x16x32_bf16 v[74:77], v[190:193], v[230:233], v[74:77]
	v_mfma_f32_16x16x32_bf16 v[62:65], v[148:151], v[238:241], v[62:65]
	v_mfma_f32_16x16x32_bf16 v[58:61], v[190:193], v[238:241], v[58:61]
	s_setprio 0
	s_setprio 1
	v_mfma_f32_16x16x32_bf16 v[30:33], v[194:197], v[210:213], v[30:33]
	v_mfma_f32_16x16x32_bf16 v[26:29], v[202:205], v[210:213], v[26:29]
	v_mfma_f32_16x16x32_bf16 v[22:25], v[194:197], v[218:221], v[22:25]
	v_mfma_f32_16x16x32_bf16 v[18:21], v[202:205], v[218:221], v[18:21]
	v_mfma_f32_16x16x32_bf16 v[14:17], v[194:197], v[226:229], v[14:17]
	v_mfma_f32_16x16x32_bf16 v[10:13], v[202:205], v[226:229], v[10:13]
	v_mfma_f32_16x16x32_bf16 v[6:9], v[194:197], v[234:237], v[6:9]
	v_mfma_f32_16x16x32_bf16 v[0:3], v[202:205], v[234:237], v[0:3]
	v_mfma_f32_16x16x32_bf16 v[30:33], v[198:201], v[214:217], v[30:33]
	v_mfma_f32_16x16x32_bf16 v[26:29], v[206:209], v[214:217], v[26:29]
	v_mfma_f32_16x16x32_bf16 v[22:25], v[198:201], v[222:225], v[22:25]
	v_mfma_f32_16x16x32_bf16 v[18:21], v[206:209], v[222:225], v[18:21]
	v_mfma_f32_16x16x32_bf16 v[14:17], v[198:201], v[230:233], v[14:17]
	v_mfma_f32_16x16x32_bf16 v[10:13], v[206:209], v[230:233], v[10:13]
	v_mfma_f32_16x16x32_bf16 v[6:9], v[198:201], v[238:241], v[6:9]
	v_mfma_f32_16x16x32_bf16 v[0:3], v[206:209], v[238:241], v[0:3]
	s_setprio 0
	s_barrier
	s_add_i32 s28, s28, 2
	s_add_u32 s22, s22, 0x100
	s_addc_u32 s23, s23, 0
	s_add_u32 s9, s9, 0x100
	s_addc_u32 s25, s25, 0
	s_cmp_gt_u32 s28, 29
	s_cbranch_scc0 .LBB0_124
	s_and_b64 vcc, exec, s[42:43]
	s_cbranch_vccz .LBB0_127
	s_barrier

.LBB0_162:
	s_ashr_i32 s49, s48, 31
	s_lshl_b64 s[2:3], s[48:49], 20
	v_readlane_b32 s4, v253, 61
	v_readlane_b32 s5, v253, 62
	s_add_u32 s82, s4, s2
	s_addc_u32 s83, s5, s3
	s_and_b64 s[2:3], s[42:43], exec
	s_cselect_b32 s2, s83, s1
	s_cselect_b32 s8, s82, s0
	s_add_u32 s22, s14, 0x80080
	s_addc_u32 s23, s15, 0
	s_add_u32 s9, s0, 0x100
	v_mov_b32_e32 v0, 0
	s_addc_u32 s10, s1, 0
	s_mov_b32 s24, -2
	v_mov_b32_e32 v1, v0
	v_mov_b32_e32 v2, v0
	v_mov_b32_e32 v3, v0
	v_mov_b32_e32 v6, v0
	s_waitcnt lgkmcnt(0)
	v_mov_b32_e32 v7, v0
	v_mov_b32_e32 v8, v0
	v_mov_b32_e32 v9, v0
	v_mov_b32_e32 v18, v0
	v_mov_b32_e32 v19, v0
	v_mov_b32_e32 v20, v0
	v_mov_b32_e32 v21, v0
	v_mov_b32_e32 v22, v0
	v_mov_b32_e32 v23, v0
	v_mov_b32_e32 v24, v0
	v_mov_b32_e32 v25, v0
	v_mov_b32_e32 v34, v0
	v_mov_b32_e32 v35, v0
	v_mov_b32_e32 v36, v0
	v_mov_b32_e32 v37, v0
	v_mov_b32_e32 v38, v0
	v_mov_b32_e32 v39, v0
	v_mov_b32_e32 v40, v0
	v_mov_b32_e32 v41, v0
	v_mov_b32_e32 v50, v0
	v_mov_b32_e32 v51, v0
	v_mov_b32_e32 v52, v0
	v_mov_b32_e32 v53, v0
	v_mov_b32_e32 v54, v0
	v_mov_b32_e32 v55, v0
	v_mov_b32_e32 v56, v0
	v_mov_b32_e32 v57, v0
	v_mov_b32_e32 v10, v0
	v_mov_b32_e32 v11, v0
	v_mov_b32_e32 v12, v0
	v_mov_b32_e32 v13, v0
	v_mov_b32_e32 v14, v0
	v_mov_b32_e32 v15, v0
	v_mov_b32_e32 v16, v0
	v_mov_b32_e32 v17, v0
	v_mov_b32_e32 v26, v0
	v_mov_b32_e32 v27, v0
	v_mov_b32_e32 v28, v0
	v_mov_b32_e32 v29, v0
	v_mov_b32_e32 v30, v0
	v_mov_b32_e32 v31, v0
	v_mov_b32_e32 v32, v0
	v_mov_b32_e32 v33, v0
	v_mov_b32_e32 v42, v0
	v_mov_b32_e32 v43, v0
	v_mov_b32_e32 v44, v0
	v_mov_b32_e32 v45, v0
	v_mov_b32_e32 v46, v0
	v_mov_b32_e32 v47, v0
	v_mov_b32_e32 v48, v0
	v_mov_b32_e32 v49, v0
	v_mov_b32_e32 v58, v0
	v_mov_b32_e32 v59, v0
	v_mov_b32_e32 v60, v0
	v_mov_b32_e32 v61, v0
	v_mov_b32_e32 v62, v0
	v_mov_b32_e32 v63, v0
	v_mov_b32_e32 v64, v0
	v_mov_b32_e32 v65, v0
	v_mov_b32_e32 v66, v0
	v_mov_b32_e32 v67, v0
	v_mov_b32_e32 v68, v0
	v_mov_b32_e32 v69, v0
	v_mov_b32_e32 v70, v0
	v_mov_b32_e32 v71, v0
	v_mov_b32_e32 v72, v0
	v_mov_b32_e32 v73, v0
	v_mov_b32_e32 v82, v0
	v_mov_b32_e32 v83, v0
	v_mov_b32_e32 v84, v0
	v_mov_b32_e32 v85, v0
	v_mov_b32_e32 v86, v0
	v_mov_b32_e32 v87, v0
	v_mov_b32_e32 v88, v0
	v_mov_b32_e32 v89, v0
	v_mov_b32_e32 v98, v0
	v_mov_b32_e32 v99, v0
	v_mov_b32_e32 v100, v0
	v_mov_b32_e32 v101, v0
	v_mov_b32_e32 v102, v0
	v_mov_b32_e32 v103, v0
	v_mov_b32_e32 v104, v0
	v_mov_b32_e32 v105, v0
	v_mov_b32_e32 v114, v0
	v_mov_b32_e32 v115, v0
	v_mov_b32_e32 v116, v0
	v_mov_b32_e32 v117, v0
	v_mov_b32_e32 v118, v0
	v_mov_b32_e32 v119, v0
	v_mov_b32_e32 v120, v0
	v_mov_b32_e32 v121, v0
	v_mov_b32_e32 v74, v0
	v_mov_b32_e32 v75, v0
	v_mov_b32_e32 v76, v0
	v_mov_b32_e32 v77, v0
	v_mov_b32_e32 v78, v0
	v_mov_b32_e32 v79, v0
	v_mov_b32_e32 v80, v0
	v_mov_b32_e32 v81, v0
	v_mov_b32_e32 v90, v0
	v_mov_b32_e32 v91, v0
	v_mov_b32_e32 v92, v0
	v_mov_b32_e32 v93, v0
	v_mov_b32_e32 v94, v0
	v_mov_b32_e32 v95, v0
	v_mov_b32_e32 v96, v0
	v_mov_b32_e32 v97, v0
	v_mov_b32_e32 v106, v0
	v_mov_b32_e32 v107, v0
	v_mov_b32_e32 v108, v0
	v_mov_b32_e32 v109, v0
	v_mov_b32_e32 v110, v0
	v_mov_b32_e32 v111, v0
	v_mov_b32_e32 v112, v0
	v_mov_b32_e32 v113, v0
	v_mov_b32_e32 v122, v0
	v_mov_b32_e32 v123, v0
	v_mov_b32_e32 v124, v0
	v_mov_b32_e32 v125, v0
	v_mov_b32_e32 v126, v0
	v_mov_b32_e32 v127, v0
	v_mov_b32_e32 v128, v0
	v_mov_b32_e32 v129, v0
	s_cmp_eq_u32 s37, 1
	s_cbranch_scc1 .LBB0_163
	s_add_u32 s0, s22, 0xfff80080
	s_addc_u32 s1, s23, -1
	s_add_i32 s3, 0, 0x10000
	s_cmp_eq_u32 s24, 28
	s_cselect_b32 s15, s79, s1
	s_cselect_b32 s14, s78, s0
	v_add_u32_e32 v162, s3, v145
	s_cselect_b32 s1, s2, s10
	s_cselect_b32 s0, s8, s9
	s_add_i32 s6, 0, 0x14000
	ds_read_b128 v[140:143], v162
	ds_read_b128 v[148:151], v162 offset:1024
	ds_read_b128 v[172:175], v162 offset:2048
	ds_read_b128 v[190:193], v162 offset:3072
	v_add_u32_e32 v162, s6, v145
	ds_read_b128 v[194:197], v162
	ds_read_b128 v[198:201], v162 offset:1024
	ds_read_b128 v[202:205], v162 offset:2048
	ds_read_b128 v[206:209], v162 offset:3072
	s_add_i32 m0, s26, 0xc000
	ds_read_b128 v[210:213], v147
	ds_read_b128 v[214:217], v147 offset:1024
	ds_read_b128 v[218:221], v147 offset:2048
	ds_read_b128 v[222:225], v147 offset:3072
	ds_read_b128 v[226:229], v147 offset:4096
	ds_read_b128 v[230:233], v147 offset:5120
	ds_read_b128 v[234:237], v147 offset:6144
	ds_read_b128 v[238:241], v147 offset:7168
	global_load_lds_dwordx4 v136, s[22:23]
	s_add_i32 m0, s26, 0xe000
	s_nop 0
	global_load_lds_dwordx4 v138, s[22:23]
	s_waitcnt vmcnt(24)
	s_waitcnt lgkmcnt(0)
	s_barrier
	s_setprio 1
	s_waitcnt lgkmcnt(0)
	v_mfma_f32_16x16x32_bf16 v[126:129], v[140:143], v[210:213], v[126:129]
	v_mfma_f32_16x16x32_bf16 v[122:125], v[172:175], v[210:213], v[122:125]
	v_mfma_f32_16x16x32_bf16 v[110:113], v[140:143], v[218:221], v[110:113]
	v_mfma_f32_16x16x32_bf16 v[106:109], v[172:175], v[218:221], v[106:109]
	v_mfma_f32_16x16x32_bf16 v[94:97], v[140:143], v[226:229], v[94:97]
	v_mfma_f32_16x16x32_bf16 v[90:93], v[172:175], v[226:229], v[90:93]
	v_mfma_f32_16x16x32_bf16 v[78:81], v[140:143], v[234:237], v[78:81]
	v_mfma_f32_16x16x32_bf16 v[74:77], v[172:175], v[234:237], v[74:77]
	v_mfma_f32_16x16x32_bf16 v[126:129], v[148:151], v[214:217], v[126:129]
	v_mfma_f32_16x16x32_bf16 v[122:125], v[190:193], v[214:217], v[122:125]
	v_mfma_f32_16x16x32_bf16 v[110:113], v[148:151], v[222:225], v[110:113]
	v_mfma_f32_16x16x32_bf16 v[106:109], v[190:193], v[222:225], v[106:109]
	v_mfma_f32_16x16x32_bf16 v[94:97], v[148:151], v[230:233], v[94:97]
	v_mfma_f32_16x16x32_bf16 v[90:93], v[190:193], v[230:233], v[90:93]
	v_mfma_f32_16x16x32_bf16 v[78:81], v[148:151], v[238:241], v[78:81]
	v_mfma_f32_16x16x32_bf16 v[74:77], v[190:193], v[238:241], v[74:77]
	s_setprio 0
	s_setprio 1
	v_mfma_f32_16x16x32_bf16 v[118:121], v[194:197], v[210:213], v[118:121]
	v_mfma_f32_16x16x32_bf16 v[114:117], v[202:205], v[210:213], v[114:117]
	v_mfma_f32_16x16x32_bf16 v[102:105], v[194:197], v[218:221], v[102:105]
	v_mfma_f32_16x16x32_bf16 v[98:101], v[202:205], v[218:221], v[98:101]
	v_mfma_f32_16x16x32_bf16 v[86:89], v[194:197], v[226:229], v[86:89]
	v_mfma_f32_16x16x32_bf16 v[82:85], v[202:205], v[226:229], v[82:85]
	v_mfma_f32_16x16x32_bf16 v[70:73], v[194:197], v[234:237], v[70:73]
	v_mfma_f32_16x16x32_bf16 v[66:69], v[202:205], v[234:237], v[66:69]
	v_mfma_f32_16x16x32_bf16 v[118:121], v[198:201], v[214:217], v[118:121]
	v_mfma_f32_16x16x32_bf16 v[114:117], v[206:209], v[214:217], v[114:117]
	v_mfma_f32_16x16x32_bf16 v[102:105], v[198:201], v[222:225], v[102:105]
	v_mfma_f32_16x16x32_bf16 v[98:101], v[206:209], v[222:225], v[98:101]
	v_mfma_f32_16x16x32_bf16 v[86:89], v[198:201], v[230:233], v[86:89]
	v_mfma_f32_16x16x32_bf16 v[82:85], v[206:209], v[230:233], v[82:85]
	v_mfma_f32_16x16x32_bf16 v[70:73], v[198:201], v[238:241], v[70:73]
	v_mfma_f32_16x16x32_bf16 v[66:69], v[206:209], v[238:241], v[66:69]
	s_setprio 0
	s_barrier
	s_add_i32 s3, s3, s11
	v_lshl_add_u64 v[162:163], s[0:1], 0, v[4:5]
	s_mov_b32 m0, s3
	ds_read_b128 v[210:213], v147 offset:16384
	ds_read_b128 v[214:217], v147 offset:17408
	ds_read_b128 v[218:221], v147 offset:18432
	ds_read_b128 v[222:225], v147 offset:19456
	ds_read_b128 v[226:229], v147 offset:20480
	ds_read_b128 v[230:233], v147 offset:21504
	ds_read_b128 v[234:237], v147 offset:22528
	ds_read_b128 v[238:241], v147 offset:23552
	global_load_lds_dwordx4 v4, s[0:1]
	s_add_i32 m0, s3, 0x2000
	s_add_u32 s4, s0, 0x80000
	v_lshl_add_u64 v[166:167], s[0:1], 0, v[130:131]
	s_addc_u32 s5, s1, 0
	s_add_i32 s3, s6, s11
	global_load_lds_dwordx4 v130, s[0:1]
	s_mov_b32 m0, s3
	v_lshl_add_u64 v[180:181], s[14:15], 0, v[132:133]
	global_load_lds_dwordx4 v4, s[4:5]
	s_add_i32 m0, s3, 0x2000
	s_nop 0
	global_load_lds_dwordx4 v130, s[4:5]
	v_lshl_add_u64 v[176:177], s[14:15], 0, v[134:135]
	s_mov_b32 m0, s26
	s_nop 0
	global_load_lds_dwordx4 v134, s[14:15]
	s_mov_b32 m0, s27
	s_nop 0
	global_load_lds_dwordx4 v132, s[14:15]
	s_waitcnt vmcnt(24)
	s_waitcnt lgkmcnt(0)
	s_barrier
	s_setprio 1
	s_waitcnt lgkmcnt(0)
	v_mfma_f32_16x16x32_bf16 v[62:65], v[140:143], v[210:213], v[62:65]
	v_mfma_f32_16x16x32_bf16 v[58:61], v[172:175], v[210:213], v[58:61]
	v_mfma_f32_16x16x32_bf16 v[46:49], v[140:143], v[218:221], v[46:49]
	v_mfma_f32_16x16x32_bf16 v[42:45], v[172:175], v[218:221], v[42:45]
	v_mfma_f32_16x16x32_bf16 v[30:33], v[140:143], v[226:229], v[30:33]
	v_mfma_f32_16x16x32_bf16 v[26:29], v[172:175], v[226:229], v[26:29]
	v_mfma_f32_16x16x32_bf16 v[14:17], v[140:143], v[234:237], v[14:17]
	v_mfma_f32_16x16x32_bf16 v[10:13], v[172:175], v[234:237], v[10:13]
	v_mfma_f32_16x16x32_bf16 v[62:65], v[148:151], v[214:217], v[62:65]
	v_mfma_f32_16x16x32_bf16 v[58:61], v[190:193], v[214:217], v[58:61]
	v_mfma_f32_16x16x32_bf16 v[46:49], v[148:151], v[222:225], v[46:49]
	v_mfma_f32_16x16x32_bf16 v[42:45], v[190:193], v[222:225], v[42:45]
	v_mfma_f32_16x16x32_bf16 v[30:33], v[148:151], v[230:233], v[30:33]
	v_mfma_f32_16x16x32_bf16 v[26:29], v[190:193], v[230:233], v[26:29]
	v_mfma_f32_16x16x32_bf16 v[14:17], v[148:151], v[238:241], v[14:17]
	v_mfma_f32_16x16x32_bf16 v[10:13], v[190:193], v[238:241], v[10:13]
	s_setprio 0
	s_setprio 1
	v_mfma_f32_16x16x32_bf16 v[54:57], v[194:197], v[210:213], v[54:57]
	v_mfma_f32_16x16x32_bf16 v[50:53], v[202:205], v[210:213], v[50:53]
	v_mfma_f32_16x16x32_bf16 v[38:41], v[194:197], v[218:221], v[38:41]
	v_mfma_f32_16x16x32_bf16 v[34:37], v[202:205], v[218:221], v[34:37]
	v_mfma_f32_16x16x32_bf16 v[22:25], v[194:197], v[226:229], v[22:25]
	v_mfma_f32_16x16x32_bf16 v[18:21], v[202:205], v[226:229], v[18:21]
	v_mfma_f32_16x16x32_bf16 v[6:9], v[194:197], v[234:237], v[6:9]
	v_mfma_f32_16x16x32_bf16 v[0:3], v[202:205], v[234:237], v[0:3]
	v_mfma_f32_16x16x32_bf16 v[54:57], v[198:201], v[214:217], v[54:57]
	v_mfma_f32_16x16x32_bf16 v[50:53], v[206:209], v[214:217], v[50:53]
	v_mfma_f32_16x16x32_bf16 v[38:41], v[198:201], v[222:225], v[38:41]
	v_mfma_f32_16x16x32_bf16 v[34:37], v[206:209], v[222:225], v[34:37]
	v_mfma_f32_16x16x32_bf16 v[22:25], v[198:201], v[230:233], v[22:25]
	v_mfma_f32_16x16x32_bf16 v[18:21], v[206:209], v[230:233], v[18:21]
	v_mfma_f32_16x16x32_bf16 v[6:9], v[198:201], v[238:241], v[6:9]
	v_mfma_f32_16x16x32_bf16 v[0:3], v[206:209], v[238:241], v[0:3]
	s_setprio 0
	s_barrier
	s_branch .Lpeelmid_163
.LBB0_163:
	s_add_u32 s0, s22, 0xfff80080
	s_addc_u32 s1, s23, -1
	s_add_i32 s3, 0, 0x10000
	s_cmp_eq_u32 s24, 28
	s_cselect_b32 s15, s79, s1
	s_cselect_b32 s14, s78, s0
	v_add_u32_e32 v162, s3, v145
	s_cselect_b32 s1, s2, s10
	s_cselect_b32 s0, s8, s9
	s_add_i32 s6, 0, 0x14000
	ds_read_b128 v[140:143], v162
	ds_read_b128 v[148:151], v162 offset:1024
	ds_read_b128 v[172:175], v162 offset:2048
	ds_read_b128 v[190:193], v162 offset:3072
	v_add_u32_e32 v162, s6, v145
	ds_read_b128 v[194:197], v162
	ds_read_b128 v[198:201], v162 offset:1024
	ds_read_b128 v[202:205], v162 offset:2048
	ds_read_b128 v[206:209], v162 offset:3072
	s_add_i32 m0, s26, 0xc000
	ds_read_b128 v[210:213], v147
	ds_read_b128 v[214:217], v147 offset:1024
	ds_read_b128 v[218:221], v147 offset:2048
	ds_read_b128 v[222:225], v147 offset:3072
	ds_read_b128 v[226:229], v147 offset:4096
	ds_read_b128 v[230:233], v147 offset:5120
	ds_read_b128 v[234:237], v147 offset:6144
	ds_read_b128 v[238:241], v147 offset:7168
	global_load_lds_dwordx4 v136, s[22:23]
	s_add_i32 m0, s26, 0xe000
	s_nop 0
	global_load_lds_dwordx4 v138, s[22:23]
	s_waitcnt vmcnt(8)
	s_waitcnt lgkmcnt(0)
	s_barrier
	s_setprio 1
	s_waitcnt lgkmcnt(0)
	v_mfma_f32_16x16x32_bf16 v[126:129], v[140:143], v[210:213], v[126:129]
	v_mfma_f32_16x16x32_bf16 v[122:125], v[172:175], v[210:213], v[122:125]
	v_mfma_f32_16x16x32_bf16 v[110:113], v[140:143], v[218:221], v[110:113]
	v_mfma_f32_16x16x32_bf16 v[106:109], v[172:175], v[218:221], v[106:109]
	v_mfma_f32_16x16x32_bf16 v[94:97], v[140:143], v[226:229], v[94:97]
	v_mfma_f32_16x16x32_bf16 v[90:93], v[172:175], v[226:229], v[90:93]
	v_mfma_f32_16x16x32_bf16 v[78:81], v[140:143], v[234:237], v[78:81]
	v_mfma_f32_16x16x32_bf16 v[74:77], v[172:175], v[234:237], v[74:77]
	v_mfma_f32_16x16x32_bf16 v[126:129], v[148:151], v[214:217], v[126:129]
	v_mfma_f32_16x16x32_bf16 v[122:125], v[190:193], v[214:217], v[122:125]
	v_mfma_f32_16x16x32_bf16 v[110:113], v[148:151], v[222:225], v[110:113]
	v_mfma_f32_16x16x32_bf16 v[106:109], v[190:193], v[222:225], v[106:109]
	v_mfma_f32_16x16x32_bf16 v[94:97], v[148:151], v[230:233], v[94:97]
	v_mfma_f32_16x16x32_bf16 v[90:93], v[190:193], v[230:233], v[90:93]
	v_mfma_f32_16x16x32_bf16 v[78:81], v[148:151], v[238:241], v[78:81]
	v_mfma_f32_16x16x32_bf16 v[74:77], v[190:193], v[238:241], v[74:77]
	s_setprio 0
	s_setprio 1
	v_mfma_f32_16x16x32_bf16 v[118:121], v[194:197], v[210:213], v[118:121]
	v_mfma_f32_16x16x32_bf16 v[114:117], v[202:205], v[210:213], v[114:117]
	v_mfma_f32_16x16x32_bf16 v[102:105], v[194:197], v[218:221], v[102:105]
	v_mfma_f32_16x16x32_bf16 v[98:101], v[202:205], v[218:221], v[98:101]
	v_mfma_f32_16x16x32_bf16 v[86:89], v[194:197], v[226:229], v[86:89]
	v_mfma_f32_16x16x32_bf16 v[82:85], v[202:205], v[226:229], v[82:85]
	v_mfma_f32_16x16x32_bf16 v[70:73], v[194:197], v[234:237], v[70:73]
	v_mfma_f32_16x16x32_bf16 v[66:69], v[202:205], v[234:237], v[66:69]
	v_mfma_f32_16x16x32_bf16 v[118:121], v[198:201], v[214:217], v[118:121]
	v_mfma_f32_16x16x32_bf16 v[114:117], v[206:209], v[214:217], v[114:117]
	v_mfma_f32_16x16x32_bf16 v[102:105], v[198:201], v[222:225], v[102:105]
	v_mfma_f32_16x16x32_bf16 v[98:101], v[206:209], v[222:225], v[98:101]
	v_mfma_f32_16x16x32_bf16 v[86:89], v[198:201], v[230:233], v[86:89]
	v_mfma_f32_16x16x32_bf16 v[82:85], v[206:209], v[230:233], v[82:85]
	v_mfma_f32_16x16x32_bf16 v[70:73], v[198:201], v[238:241], v[70:73]
	v_mfma_f32_16x16x32_bf16 v[66:69], v[206:209], v[238:241], v[66:69]
	s_setprio 0
	s_barrier
	s_add_i32 s3, s3, s11
	v_lshl_add_u64 v[162:163], s[0:1], 0, v[4:5]
	s_mov_b32 m0, s3
	ds_read_b128 v[210:213], v147 offset:16384
	ds_read_b128 v[214:217], v147 offset:17408
	ds_read_b128 v[218:221], v147 offset:18432
	ds_read_b128 v[222:225], v147 offset:19456
	ds_read_b128 v[226:229], v147 offset:20480
	ds_read_b128 v[230:233], v147 offset:21504
	ds_read_b128 v[234:237], v147 offset:22528
	ds_read_b128 v[238:241], v147 offset:23552
	global_load_lds_dwordx4 v4, s[0:1]
	s_add_i32 m0, s3, 0x2000
	s_add_u32 s4, s0, 0x80000
	v_lshl_add_u64 v[166:167], s[0:1], 0, v[130:131]
	s_addc_u32 s5, s1, 0
	s_add_i32 s3, s6, s11
	global_load_lds_dwordx4 v130, s[0:1]
	s_mov_b32 m0, s3
	v_lshl_add_u64 v[180:181], s[14:15], 0, v[132:133]
	global_load_lds_dwordx4 v4, s[4:5]
	s_add_i32 m0, s3, 0x2000
	s_nop 0
	global_load_lds_dwordx4 v130, s[4:5]
	v_lshl_add_u64 v[176:177], s[14:15], 0, v[134:135]
	s_mov_b32 m0, s26
	s_nop 0
	global_load_lds_dwordx4 v134, s[14:15]
	s_mov_b32 m0, s27
	s_nop 0
	global_load_lds_dwordx4 v132, s[14:15]
	s_waitcnt vmcnt(8)
	s_waitcnt lgkmcnt(0)
	s_barrier
	s_setprio 1
	s_waitcnt lgkmcnt(0)
	v_mfma_f32_16x16x32_bf16 v[62:65], v[140:143], v[210:213], v[62:65]
	v_mfma_f32_16x16x32_bf16 v[58:61], v[172:175], v[210:213], v[58:61]
	v_mfma_f32_16x16x32_bf16 v[46:49], v[140:143], v[218:221], v[46:49]
	v_mfma_f32_16x16x32_bf16 v[42:45], v[172:175], v[218:221], v[42:45]
	v_mfma_f32_16x16x32_bf16 v[30:33], v[140:143], v[226:229], v[30:33]
	v_mfma_f32_16x16x32_bf16 v[26:29], v[172:175], v[226:229], v[26:29]
	v_mfma_f32_16x16x32_bf16 v[14:17], v[140:143], v[234:237], v[14:17]
	v_mfma_f32_16x16x32_bf16 v[10:13], v[172:175], v[234:237], v[10:13]
	v_mfma_f32_16x16x32_bf16 v[62:65], v[148:151], v[214:217], v[62:65]
	v_mfma_f32_16x16x32_bf16 v[58:61], v[190:193], v[214:217], v[58:61]
	v_mfma_f32_16x16x32_bf16 v[46:49], v[148:151], v[222:225], v[46:49]
	v_mfma_f32_16x16x32_bf16 v[42:45], v[190:193], v[222:225], v[42:45]
	v_mfma_f32_16x16x32_bf16 v[30:33], v[148:151], v[230:233], v[30:33]
	v_mfma_f32_16x16x32_bf16 v[26:29], v[190:193], v[230:233], v[26:29]
	v_mfma_f32_16x16x32_bf16 v[14:17], v[148:151], v[238:241], v[14:17]
	v_mfma_f32_16x16x32_bf16 v[10:13], v[190:193], v[238:241], v[10:13]
	s_setprio 0
	s_setprio 1
	v_mfma_f32_16x16x32_bf16 v[54:57], v[194:197], v[210:213], v[54:57]
	v_mfma_f32_16x16x32_bf16 v[50:53], v[202:205], v[210:213], v[50:53]
	v_mfma_f32_16x16x32_bf16 v[38:41], v[194:197], v[218:221], v[38:41]
	v_mfma_f32_16x16x32_bf16 v[34:37], v[202:205], v[218:221], v[34:37]
	v_mfma_f32_16x16x32_bf16 v[22:25], v[194:197], v[226:229], v[22:25]
	v_mfma_f32_16x16x32_bf16 v[18:21], v[202:205], v[226:229], v[18:21]
	v_mfma_f32_16x16x32_bf16 v[6:9], v[194:197], v[234:237], v[6:9]
	v_mfma_f32_16x16x32_bf16 v[0:3], v[202:205], v[234:237], v[0:3]
	v_mfma_f32_16x16x32_bf16 v[54:57], v[198:201], v[214:217], v[54:57]
	v_mfma_f32_16x16x32_bf16 v[50:53], v[206:209], v[214:217], v[50:53]
	v_mfma_f32_16x16x32_bf16 v[38:41], v[198:201], v[222:225], v[38:41]
	v_mfma_f32_16x16x32_bf16 v[34:37], v[206:209], v[222:225], v[34:37]
	v_mfma_f32_16x16x32_bf16 v[22:25], v[198:201], v[230:233], v[22:25]
	v_mfma_f32_16x16x32_bf16 v[18:21], v[206:209], v[230:233], v[18:21]
	v_mfma_f32_16x16x32_bf16 v[6:9], v[198:201], v[238:241], v[6:9]
	v_mfma_f32_16x16x32_bf16 v[0:3], v[206:209], v[238:241], v[0:3]
	s_setprio 0
	s_barrier
.Lpeelmid_163:
	s_add_i32 s3, 0, 0x18000
	v_add_u32_e32 v164, s3, v145
	s_add_i32 s6, 0, 0x1c000
	ds_read_b128 v[140:143], v164
	ds_read_b128 v[148:151], v164 offset:1024
	ds_read_b128 v[172:175], v164 offset:2048
	ds_read_b128 v[190:193], v164 offset:3072
	v_add_u32_e32 v164, s6, v145
	ds_read_b128 v[194:197], v164
	ds_read_b128 v[198:201], v164 offset:1024
	ds_read_b128 v[202:205], v164 offset:2048
	ds_read_b128 v[206:209], v164 offset:3072
	s_add_u32 s4, s14, 0x80000
	s_addc_u32 s5, s15, 0
	s_mov_b32 m0, s30
	ds_read_b128 v[210:213], v147 offset:32768
	ds_read_b128 v[214:217], v147 offset:33792
	ds_read_b128 v[218:221], v147 offset:34816
	ds_read_b128 v[222:225], v147 offset:35840
	ds_read_b128 v[226:229], v147 offset:36864
	ds_read_b128 v[230:233], v147 offset:37888
	ds_read_b128 v[234:237], v147 offset:38912
	ds_read_b128 v[238:241], v147 offset:39936
	global_load_lds_dwordx4 v134, s[4:5]
	v_lshl_add_u64 v[242:243], s[4:5], 0, v[132:133]
	s_mov_b32 m0, s31
	s_nop 0
	global_load_lds_dwordx4 v132, s[4:5]
	s_waitcnt vmcnt(8)
	s_waitcnt lgkmcnt(0)
	s_barrier
	s_setprio 1
	s_waitcnt lgkmcnt(0)
	v_mfma_f32_16x16x32_bf16 v[126:129], v[140:143], v[210:213], v[126:129]
	v_mfma_f32_16x16x32_bf16 v[122:125], v[172:175], v[210:213], v[122:125]
	v_mfma_f32_16x16x32_bf16 v[110:113], v[140:143], v[218:221], v[110:113]
	v_mfma_f32_16x16x32_bf16 v[106:109], v[172:175], v[218:221], v[106:109]
	v_mfma_f32_16x16x32_bf16 v[94:97], v[140:143], v[226:229], v[94:97]
	v_mfma_f32_16x16x32_bf16 v[90:93], v[172:175], v[226:229], v[90:93]
	v_mfma_f32_16x16x32_bf16 v[78:81], v[140:143], v[234:237], v[78:81]
	v_mfma_f32_16x16x32_bf16 v[74:77], v[172:175], v[234:237], v[74:77]
	v_mfma_f32_16x16x32_bf16 v[126:129], v[148:151], v[214:217], v[126:129]
	v_mfma_f32_16x16x32_bf16 v[122:125], v[190:193], v[214:217], v[122:125]
	v_mfma_f32_16x16x32_bf16 v[110:113], v[148:151], v[222:225], v[110:113]
	v_mfma_f32_16x16x32_bf16 v[106:109], v[190:193], v[222:225], v[106:109]
	v_mfma_f32_16x16x32_bf16 v[94:97], v[148:151], v[230:233], v[94:97]
	v_mfma_f32_16x16x32_bf16 v[90:93], v[190:193], v[230:233], v[90:93]
	v_mfma_f32_16x16x32_bf16 v[78:81], v[148:151], v[238:241], v[78:81]
	v_mfma_f32_16x16x32_bf16 v[74:77], v[190:193], v[238:241], v[74:77]
	s_setprio 0
	s_setprio 1
	v_mfma_f32_16x16x32_bf16 v[118:121], v[194:197], v[210:213], v[118:121]
	v_mfma_f32_16x16x32_bf16 v[114:117], v[202:205], v[210:213], v[114:117]
	v_mfma_f32_16x16x32_bf16 v[102:105], v[194:197], v[218:221], v[102:105]
	v_mfma_f32_16x16x32_bf16 v[98:101], v[202:205], v[218:221], v[98:101]
	v_mfma_f32_16x16x32_bf16 v[86:89], v[194:197], v[226:229], v[86:89]
	v_mfma_f32_16x16x32_bf16 v[82:85], v[202:205], v[226:229], v[82:85]
	v_mfma_f32_16x16x32_bf16 v[70:73], v[194:197], v[234:237], v[70:73]
	v_mfma_f32_16x16x32_bf16 v[66:69], v[202:205], v[234:237], v[66:69]
	v_mfma_f32_16x16x32_bf16 v[118:121], v[198:201], v[214:217], v[118:121]
	v_mfma_f32_16x16x32_bf16 v[114:117], v[206:209], v[214:217], v[114:117]
	v_mfma_f32_16x16x32_bf16 v[102:105], v[198:201], v[222:225], v[102:105]
	v_mfma_f32_16x16x32_bf16 v[98:101], v[206:209], v[222:225], v[98:101]
	v_mfma_f32_16x16x32_bf16 v[86:89], v[198:201], v[230:233], v[86:89]
	v_mfma_f32_16x16x32_bf16 v[82:85], v[206:209], v[230:233], v[82:85]
	v_mfma_f32_16x16x32_bf16 v[70:73], v[198:201], v[238:241], v[70:73]
	v_mfma_f32_16x16x32_bf16 v[66:69], v[206:209], v[238:241], v[66:69]
	s_setprio 0
	s_barrier
	s_add_i32 s3, s3, s11
	v_lshl_add_u64 v[162:163], v[162:163], 0, s[70:71]
	s_mov_b32 m0, s3
	ds_read_b128 v[210:213], v147 offset:49152
	ds_read_b128 v[214:217], v147 offset:50176
	ds_read_b128 v[218:221], v147 offset:51200
	ds_read_b128 v[222:225], v147 offset:52224
	ds_read_b128 v[226:229], v147 offset:53248
	ds_read_b128 v[230:233], v147 offset:54272
	ds_read_b128 v[234:237], v147 offset:55296
	ds_read_b128 v[238:241], v147 offset:56320
	global_load_lds_dwordx4 v[162:163], off
	s_add_i32 m0, s3, 0x2000
	s_add_u32 s0, s0, 0x80080
	v_lshl_add_u64 v[162:163], v[166:167], 0, s[70:71]
	s_addc_u32 s1, s1, 0
	s_add_i32 s3, s6, s11
	global_load_lds_dwordx4 v[162:163], off
	s_mov_b32 m0, s3
	s_nop 0
	global_load_lds_dwordx4 v4, s[0:1]
	s_add_i32 m0, s3, 0x2000
	s_nop 0
	global_load_lds_dwordx4 v130, s[0:1]
	v_lshl_add_u64 v[162:163], v[176:177], 0, s[70:71]
	s_mov_b32 m0, s35
	s_nop 0
	global_load_lds_dwordx4 v[162:163], off
	v_lshl_add_u64 v[162:163], v[180:181], 0, s[70:71]
	s_mov_b32 m0, s36
	s_nop 0
	global_load_lds_dwordx4 v[162:163], off
	s_waitcnt vmcnt(8)
	s_waitcnt lgkmcnt(0)
	s_barrier
	s_setprio 1
	s_waitcnt lgkmcnt(0)
	v_mfma_f32_16x16x32_bf16 v[62:65], v[140:143], v[210:213], v[62:65]
	v_mfma_f32_16x16x32_bf16 v[58:61], v[172:175], v[210:213], v[58:61]
	v_mfma_f32_16x16x32_bf16 v[46:49], v[140:143], v[218:221], v[46:49]
	v_mfma_f32_16x16x32_bf16 v[42:45], v[172:175], v[218:221], v[42:45]
	v_mfma_f32_16x16x32_bf16 v[30:33], v[140:143], v[226:229], v[30:33]
	v_mfma_f32_16x16x32_bf16 v[26:29], v[172:175], v[226:229], v[26:29]
	v_mfma_f32_16x16x32_bf16 v[14:17], v[140:143], v[234:237], v[14:17]
	v_mfma_f32_16x16x32_bf16 v[10:13], v[172:175], v[234:237], v[10:13]
	v_mfma_f32_16x16x32_bf16 v[62:65], v[148:151], v[214:217], v[62:65]
	v_mfma_f32_16x16x32_bf16 v[58:61], v[190:193], v[214:217], v[58:61]
	v_mfma_f32_16x16x32_bf16 v[46:49], v[148:151], v[222:225], v[46:49]
	v_mfma_f32_16x16x32_bf16 v[42:45], v[190:193], v[222:225], v[42:45]
	v_mfma_f32_16x16x32_bf16 v[30:33], v[148:151], v[230:233], v[30:33]
	v_mfma_f32_16x16x32_bf16 v[26:29], v[190:193], v[230:233], v[26:29]
	v_mfma_f32_16x16x32_bf16 v[14:17], v[148:151], v[238:241], v[14:17]
	v_mfma_f32_16x16x32_bf16 v[10:13], v[190:193], v[238:241], v[10:13]
	s_setprio 0
	s_setprio 1
	v_mfma_f32_16x16x32_bf16 v[54:57], v[194:197], v[210:213], v[54:57]
	v_mfma_f32_16x16x32_bf16 v[50:53], v[202:205], v[210:213], v[50:53]
	v_mfma_f32_16x16x32_bf16 v[38:41], v[194:197], v[218:221], v[38:41]
	v_mfma_f32_16x16x32_bf16 v[34:37], v[202:205], v[218:221], v[34:37]
	v_mfma_f32_16x16x32_bf16 v[22:25], v[194:197], v[226:229], v[22:25]
	v_mfma_f32_16x16x32_bf16 v[18:21], v[202:205], v[226:229], v[18:21]
	v_mfma_f32_16x16x32_bf16 v[6:9], v[194:197], v[234:237], v[6:9]
	v_mfma_f32_16x16x32_bf16 v[0:3], v[202:205], v[234:237], v[0:3]
	v_mfma_f32_16x16x32_bf16 v[54:57], v[198:201], v[214:217], v[54:57]
	v_mfma_f32_16x16x32_bf16 v[50:53], v[206:209], v[214:217], v[50:53]
	v_mfma_f32_16x16x32_bf16 v[38:41], v[198:201], v[222:225], v[38:41]
	v_mfma_f32_16x16x32_bf16 v[34:37], v[206:209], v[222:225], v[34:37]
	v_mfma_f32_16x16x32_bf16 v[22:25], v[198:201], v[230:233], v[22:25]
	v_mfma_f32_16x16x32_bf16 v[18:21], v[206:209], v[230:233], v[18:21]
	v_mfma_f32_16x16x32_bf16 v[6:9], v[198:201], v[238:241], v[6:9]
	v_mfma_f32_16x16x32_bf16 v[0:3], v[206:209], v[238:241], v[0:3]
	s_setprio 0
	s_barrier
	s_add_i32 s24, s24, 2
	s_add_u32 s22, s22, 0x100
	s_addc_u32 s23, s23, 0
	s_add_u32 s9, s9, 0x100
	s_addc_u32 s10, s10, 0
	s_cmp_gt_u32 s24, 29
	s_cbranch_scc0 .LBB0_163
	s_and_b64 vcc, exec, s[46:47]
	s_cbranch_vccz .LBB0_166
	s_barrier

.LBB0_204:
	s_ashr_i32 s49, s48, 31
	s_lshl_b64 s[2:3], s[48:49], 19
	v_readlane_b32 s4, v253, 17
	v_readlane_b32 s5, v253, 18
	s_add_u32 s84, s4, s2
	s_addc_u32 s85, s5, s3
	s_and_b64 s[2:3], s[42:43], exec
	s_cselect_b32 s2, s85, s15
	s_cselect_b32 s8, s84, s14
	s_add_u32 s22, s0, 0x40080
	s_addc_u32 s23, s1, 0
	s_add_u32 s9, s14, 0x100
	v_mov_b32_e32 v0, 0
	s_addc_u32 s10, s15, 0
	s_mov_b32 s24, -2
	v_mov_b32_e32 v1, v0
	v_mov_b32_e32 v2, v0
	v_mov_b32_e32 v3, v0
	v_mov_b32_e32 v6, v0
	v_mov_b32_e32 v7, v0
	v_mov_b32_e32 v8, v0
	v_mov_b32_e32 v9, v0
	v_mov_b32_e32 v10, v0
	v_mov_b32_e32 v11, v0
	v_mov_b32_e32 v12, v0
	v_mov_b32_e32 v13, v0
	v_mov_b32_e32 v14, v0
	v_mov_b32_e32 v15, v0
	v_mov_b32_e32 v16, v0
	v_mov_b32_e32 v17, v0
	v_mov_b32_e32 v18, v0
	v_mov_b32_e32 v19, v0
	v_mov_b32_e32 v20, v0
	v_mov_b32_e32 v21, v0
	v_mov_b32_e32 v22, v0
	v_mov_b32_e32 v23, v0
	v_mov_b32_e32 v24, v0
	v_mov_b32_e32 v25, v0
	v_mov_b32_e32 v26, v0
	v_mov_b32_e32 v27, v0
	v_mov_b32_e32 v28, v0
	v_mov_b32_e32 v29, v0
	v_mov_b32_e32 v30, v0
	v_mov_b32_e32 v31, v0
	v_mov_b32_e32 v32, v0
	v_mov_b32_e32 v33, v0
	v_mov_b32_e32 v66, v0
	v_mov_b32_e32 v67, v0
	v_mov_b32_e32 v68, v0
	v_mov_b32_e32 v69, v0
	v_mov_b32_e32 v70, v0
	v_mov_b32_e32 v71, v0
	v_mov_b32_e32 v72, v0
	v_mov_b32_e32 v73, v0
	v_mov_b32_e32 v74, v0
	v_mov_b32_e32 v75, v0
	v_mov_b32_e32 v76, v0
	v_mov_b32_e32 v77, v0
	v_mov_b32_e32 v78, v0
	v_mov_b32_e32 v79, v0
	v_mov_b32_e32 v80, v0
	v_mov_b32_e32 v81, v0
	v_mov_b32_e32 v82, v0
	v_mov_b32_e32 v83, v0
	v_mov_b32_e32 v84, v0
	v_mov_b32_e32 v85, v0
	v_mov_b32_e32 v86, v0
	v_mov_b32_e32 v87, v0
	v_mov_b32_e32 v88, v0
	v_mov_b32_e32 v89, v0
	v_mov_b32_e32 v90, v0
	v_mov_b32_e32 v91, v0
	v_mov_b32_e32 v92, v0
	v_mov_b32_e32 v93, v0
	v_mov_b32_e32 v94, v0
	v_mov_b32_e32 v95, v0
	v_mov_b32_e32 v96, v0
	v_mov_b32_e32 v97, v0
	v_mov_b32_e32 v34, v0
	v_mov_b32_e32 v35, v0
	v_mov_b32_e32 v36, v0
	v_mov_b32_e32 v37, v0
	v_mov_b32_e32 v38, v0
	v_mov_b32_e32 v39, v0
	v_mov_b32_e32 v40, v0
	v_mov_b32_e32 v41, v0
	v_mov_b32_e32 v42, v0
	v_mov_b32_e32 v43, v0
	v_mov_b32_e32 v44, v0
	v_mov_b32_e32 v45, v0
	v_mov_b32_e32 v46, v0
	v_mov_b32_e32 v47, v0
	v_mov_b32_e32 v48, v0
	v_mov_b32_e32 v49, v0
	v_mov_b32_e32 v50, v0
	v_mov_b32_e32 v51, v0
	v_mov_b32_e32 v52, v0
	v_mov_b32_e32 v53, v0
	v_mov_b32_e32 v54, v0
	v_mov_b32_e32 v55, v0
	v_mov_b32_e32 v56, v0
	v_mov_b32_e32 v57, v0
	v_mov_b32_e32 v58, v0
	v_mov_b32_e32 v59, v0
	v_mov_b32_e32 v60, v0
	v_mov_b32_e32 v61, v0
	v_mov_b32_e32 v62, v0
	v_mov_b32_e32 v63, v0
	v_mov_b32_e32 v64, v0
	v_mov_b32_e32 v65, v0
	v_mov_b32_e32 v98, v0
	v_mov_b32_e32 v99, v0
	v_mov_b32_e32 v100, v0
	v_mov_b32_e32 v101, v0
	v_mov_b32_e32 v102, v0
	v_mov_b32_e32 v103, v0
	v_mov_b32_e32 v104, v0
	v_mov_b32_e32 v105, v0
	v_mov_b32_e32 v106, v0
	v_mov_b32_e32 v107, v0
	v_mov_b32_e32 v108, v0
	v_mov_b32_e32 v109, v0
	v_mov_b32_e32 v110, v0
	v_mov_b32_e32 v111, v0
	v_mov_b32_e32 v112, v0
	v_mov_b32_e32 v113, v0
	v_mov_b32_e32 v114, v0
	v_mov_b32_e32 v115, v0
	v_mov_b32_e32 v116, v0
	v_mov_b32_e32 v117, v0
	v_mov_b32_e32 v118, v0
	v_mov_b32_e32 v119, v0
	v_mov_b32_e32 v120, v0
	v_mov_b32_e32 v121, v0
	v_mov_b32_e32 v122, v0
	v_mov_b32_e32 v123, v0
	v_mov_b32_e32 v124, v0
	v_mov_b32_e32 v125, v0
	v_mov_b32_e32 v126, v0
	v_mov_b32_e32 v127, v0
	v_mov_b32_e32 v128, v0
	v_mov_b32_e32 v129, v0
	s_cmp_eq_u32 s37, 1
	s_cbranch_scc1 .LBB0_205
	s_add_u32 s0, s22, 0xfffc0080
	s_addc_u32 s1, s23, -1
	s_add_i32 s3, 0, 0x10000
	s_cmp_eq_u32 s24, 12
	s_cselect_b32 s15, s83, s1
	s_cselect_b32 s14, s82, s0
	v_add_u32_e32 v144, s3, v168
	s_cselect_b32 s1, s2, s10
	s_cselect_b32 s0, s8, s9
	s_add_i32 s6, 0, 0x14000
	ds_read_b128 v[140:143], v144
	ds_read_b128 v[174:177], v144 offset:1024
	ds_read_b128 v[190:193], v144 offset:2048
	ds_read_b128 v[194:197], v144 offset:3072
	v_add_u32_e32 v144, s6, v168
	ds_read_b128 v[198:201], v144
	ds_read_b128 v[202:205], v144 offset:1024
	ds_read_b128 v[206:209], v144 offset:2048
	ds_read_b128 v[210:213], v144 offset:3072
	s_add_i32 m0, s27, 0xc000
	ds_read_b128 v[214:217], v172
	ds_read_b128 v[218:221], v172 offset:1024
	ds_read_b128 v[222:225], v172 offset:2048
	ds_read_b128 v[226:229], v172 offset:3072
	ds_read_b128 v[230:233], v172 offset:4096
	ds_read_b128 v[234:237], v172 offset:5120
	ds_read_b128 v[238:241], v172 offset:6144
	ds_read_b128 v[242:245], v172 offset:7168
	global_load_lds_dwordx4 v136, s[22:23]
	s_add_i32 m0, s27, 0xe000
	s_nop 0
	global_load_lds_dwordx4 v138, s[22:23]
	s_waitcnt vmcnt(24)
	s_waitcnt lgkmcnt(0)
	s_barrier
	s_setprio 1
	s_waitcnt lgkmcnt(0)
	v_mfma_f32_16x16x32_bf16 v[126:129], v[140:143], v[214:217], v[126:129]
	v_mfma_f32_16x16x32_bf16 v[122:125], v[190:193], v[214:217], v[122:125]
	v_mfma_f32_16x16x32_bf16 v[118:121], v[140:143], v[222:225], v[118:121]
	v_mfma_f32_16x16x32_bf16 v[114:117], v[190:193], v[222:225], v[114:117]
	v_mfma_f32_16x16x32_bf16 v[110:113], v[140:143], v[230:233], v[110:113]
	v_mfma_f32_16x16x32_bf16 v[106:109], v[190:193], v[230:233], v[106:109]
	v_mfma_f32_16x16x32_bf16 v[102:105], v[140:143], v[238:241], v[102:105]
	v_mfma_f32_16x16x32_bf16 v[98:101], v[190:193], v[238:241], v[98:101]
	v_mfma_f32_16x16x32_bf16 v[126:129], v[174:177], v[218:221], v[126:129]
	v_mfma_f32_16x16x32_bf16 v[122:125], v[194:197], v[218:221], v[122:125]
	v_mfma_f32_16x16x32_bf16 v[118:121], v[174:177], v[226:229], v[118:121]
	v_mfma_f32_16x16x32_bf16 v[114:117], v[194:197], v[226:229], v[114:117]
	v_mfma_f32_16x16x32_bf16 v[110:113], v[174:177], v[234:237], v[110:113]
	v_mfma_f32_16x16x32_bf16 v[106:109], v[194:197], v[234:237], v[106:109]
	v_mfma_f32_16x16x32_bf16 v[102:105], v[174:177], v[242:245], v[102:105]
	v_mfma_f32_16x16x32_bf16 v[98:101], v[194:197], v[242:245], v[98:101]
	s_setprio 0
	s_setprio 1
	v_mfma_f32_16x16x32_bf16 v[62:65], v[198:201], v[214:217], v[62:65]
	v_mfma_f32_16x16x32_bf16 v[58:61], v[206:209], v[214:217], v[58:61]
	v_mfma_f32_16x16x32_bf16 v[54:57], v[198:201], v[222:225], v[54:57]
	v_mfma_f32_16x16x32_bf16 v[50:53], v[206:209], v[222:225], v[50:53]
	v_mfma_f32_16x16x32_bf16 v[46:49], v[198:201], v[230:233], v[46:49]
	v_mfma_f32_16x16x32_bf16 v[42:45], v[206:209], v[230:233], v[42:45]
	v_mfma_f32_16x16x32_bf16 v[38:41], v[198:201], v[238:241], v[38:41]
	v_mfma_f32_16x16x32_bf16 v[34:37], v[206:209], v[238:241], v[34:37]
	v_mfma_f32_16x16x32_bf16 v[62:65], v[202:205], v[218:221], v[62:65]
	v_mfma_f32_16x16x32_bf16 v[58:61], v[210:213], v[218:221], v[58:61]
	v_mfma_f32_16x16x32_bf16 v[54:57], v[202:205], v[226:229], v[54:57]
	v_mfma_f32_16x16x32_bf16 v[50:53], v[210:213], v[226:229], v[50:53]
	v_mfma_f32_16x16x32_bf16 v[46:49], v[202:205], v[234:237], v[46:49]
	v_mfma_f32_16x16x32_bf16 v[42:45], v[210:213], v[234:237], v[42:45]
	v_mfma_f32_16x16x32_bf16 v[38:41], v[202:205], v[242:245], v[38:41]
	v_mfma_f32_16x16x32_bf16 v[34:37], v[210:213], v[242:245], v[34:37]
	s_setprio 0
	s_barrier
	s_add_i32 s3, s3, s26
	v_lshl_add_u64 v[144:145], s[0:1], 0, v[4:5]
	s_mov_b32 m0, s3
	ds_read_b128 v[214:217], v172 offset:16384
	ds_read_b128 v[218:221], v172 offset:17408
	ds_read_b128 v[222:225], v172 offset:18432
	ds_read_b128 v[226:229], v172 offset:19456
	ds_read_b128 v[230:233], v172 offset:20480
	ds_read_b128 v[234:237], v172 offset:21504
	ds_read_b128 v[238:241], v172 offset:22528
	ds_read_b128 v[242:245], v172 offset:23552
	global_load_lds_dwordx4 v4, s[0:1]
	s_add_i32 m0, s3, 0x2000
	s_add_u32 s4, s0, 0x40000
	v_lshl_add_u64 v[246:247], s[0:1], 0, v[134:135]
	s_addc_u32 s5, s1, 0
	s_add_i32 s3, s6, s26
	global_load_lds_dwordx4 v134, s[0:1]
	s_mov_b32 m0, s3
	v_lshl_add_u64 v[250:251], s[14:15], 0, v[132:133]
	global_load_lds_dwordx4 v4, s[4:5]
	s_add_i32 m0, s3, 0x2000
	s_nop 0
	global_load_lds_dwordx4 v134, s[4:5]
	v_lshl_add_u64 v[248:249], s[14:15], 0, v[130:131]
	s_mov_b32 m0, s27
	s_nop 0
	global_load_lds_dwordx4 v130, s[14:15]
	s_mov_b32 m0, s30
	s_nop 0
	global_load_lds_dwordx4 v132, s[14:15]
	s_waitcnt vmcnt(24)
	s_waitcnt lgkmcnt(0)
	s_barrier
	s_setprio 1
	s_waitcnt lgkmcnt(0)
	v_mfma_f32_16x16x32_bf16 v[94:97], v[140:143], v[214:217], v[94:97]
	v_mfma_f32_16x16x32_bf16 v[90:93], v[190:193], v[214:217], v[90:93]
	v_mfma_f32_16x16x32_bf16 v[86:89], v[140:143], v[222:225], v[86:89]
	v_mfma_f32_16x16x32_bf16 v[82:85], v[190:193], v[222:225], v[82:85]
	v_mfma_f32_16x16x32_bf16 v[78:81], v[140:143], v[230:233], v[78:81]
	v_mfma_f32_16x16x32_bf16 v[74:77], v[190:193], v[230:233], v[74:77]
	v_mfma_f32_16x16x32_bf16 v[70:73], v[140:143], v[238:241], v[70:73]
	v_mfma_f32_16x16x32_bf16 v[66:69], v[190:193], v[238:241], v[66:69]
	v_mfma_f32_16x16x32_bf16 v[94:97], v[174:177], v[218:221], v[94:97]
	v_mfma_f32_16x16x32_bf16 v[90:93], v[194:197], v[218:221], v[90:93]
	v_mfma_f32_16x16x32_bf16 v[86:89], v[174:177], v[226:229], v[86:89]
	v_mfma_f32_16x16x32_bf16 v[82:85], v[194:197], v[226:229], v[82:85]
	v_mfma_f32_16x16x32_bf16 v[78:81], v[174:177], v[234:237], v[78:81]
	v_mfma_f32_16x16x32_bf16 v[74:77], v[194:197], v[234:237], v[74:77]
	v_mfma_f32_16x16x32_bf16 v[70:73], v[174:177], v[242:245], v[70:73]
	v_mfma_f32_16x16x32_bf16 v[66:69], v[194:197], v[242:245], v[66:69]
	s_setprio 0
	s_setprio 1
	v_mfma_f32_16x16x32_bf16 v[30:33], v[198:201], v[214:217], v[30:33]
	v_mfma_f32_16x16x32_bf16 v[26:29], v[206:209], v[214:217], v[26:29]
	v_mfma_f32_16x16x32_bf16 v[22:25], v[198:201], v[222:225], v[22:25]
	v_mfma_f32_16x16x32_bf16 v[18:21], v[206:209], v[222:225], v[18:21]
	v_mfma_f32_16x16x32_bf16 v[14:17], v[198:201], v[230:233], v[14:17]
	v_mfma_f32_16x16x32_bf16 v[10:13], v[206:209], v[230:233], v[10:13]
	v_mfma_f32_16x16x32_bf16 v[6:9], v[198:201], v[238:241], v[6:9]
	v_mfma_f32_16x16x32_bf16 v[0:3], v[206:209], v[238:241], v[0:3]
	v_mfma_f32_16x16x32_bf16 v[30:33], v[202:205], v[218:221], v[30:33]
	v_mfma_f32_16x16x32_bf16 v[26:29], v[210:213], v[218:221], v[26:29]
	v_mfma_f32_16x16x32_bf16 v[22:25], v[202:205], v[226:229], v[22:25]
	v_mfma_f32_16x16x32_bf16 v[18:21], v[210:213], v[226:229], v[18:21]
	v_mfma_f32_16x16x32_bf16 v[14:17], v[202:205], v[234:237], v[14:17]
	v_mfma_f32_16x16x32_bf16 v[10:13], v[210:213], v[234:237], v[10:13]
	v_mfma_f32_16x16x32_bf16 v[6:9], v[202:205], v[242:245], v[6:9]
	v_mfma_f32_16x16x32_bf16 v[0:3], v[210:213], v[242:245], v[0:3]
	s_setprio 0
	s_barrier
	s_branch .Lpeelmid_205
.LBB0_205:
	s_add_u32 s0, s22, 0xfffc0080
	s_addc_u32 s1, s23, -1
	s_add_i32 s3, 0, 0x10000
	s_cmp_eq_u32 s24, 12
	s_cselect_b32 s15, s83, s1
	s_cselect_b32 s14, s82, s0
	v_add_u32_e32 v144, s3, v168
	s_cselect_b32 s1, s2, s10
	s_cselect_b32 s0, s8, s9
	s_add_i32 s6, 0, 0x14000
	ds_read_b128 v[140:143], v144
	ds_read_b128 v[174:177], v144 offset:1024
	ds_read_b128 v[190:193], v144 offset:2048
	ds_read_b128 v[194:197], v144 offset:3072
	v_add_u32_e32 v144, s6, v168
	ds_read_b128 v[198:201], v144
	ds_read_b128 v[202:205], v144 offset:1024
	ds_read_b128 v[206:209], v144 offset:2048
	ds_read_b128 v[210:213], v144 offset:3072
	s_add_i32 m0, s27, 0xc000
	ds_read_b128 v[214:217], v172
	ds_read_b128 v[218:221], v172 offset:1024
	ds_read_b128 v[222:225], v172 offset:2048
	ds_read_b128 v[226:229], v172 offset:3072
	ds_read_b128 v[230:233], v172 offset:4096
	ds_read_b128 v[234:237], v172 offset:5120
	ds_read_b128 v[238:241], v172 offset:6144
	ds_read_b128 v[242:245], v172 offset:7168
	global_load_lds_dwordx4 v136, s[22:23]
	s_add_i32 m0, s27, 0xe000
	s_nop 0
	global_load_lds_dwordx4 v138, s[22:23]
	s_waitcnt vmcnt(8)
	s_waitcnt lgkmcnt(0)
	s_barrier
	s_setprio 1
	s_waitcnt lgkmcnt(0)
	v_mfma_f32_16x16x32_bf16 v[126:129], v[140:143], v[214:217], v[126:129]
	v_mfma_f32_16x16x32_bf16 v[122:125], v[190:193], v[214:217], v[122:125]
	v_mfma_f32_16x16x32_bf16 v[118:121], v[140:143], v[222:225], v[118:121]
	v_mfma_f32_16x16x32_bf16 v[114:117], v[190:193], v[222:225], v[114:117]
	v_mfma_f32_16x16x32_bf16 v[110:113], v[140:143], v[230:233], v[110:113]
	v_mfma_f32_16x16x32_bf16 v[106:109], v[190:193], v[230:233], v[106:109]
	v_mfma_f32_16x16x32_bf16 v[102:105], v[140:143], v[238:241], v[102:105]
	v_mfma_f32_16x16x32_bf16 v[98:101], v[190:193], v[238:241], v[98:101]
	v_mfma_f32_16x16x32_bf16 v[126:129], v[174:177], v[218:221], v[126:129]
	v_mfma_f32_16x16x32_bf16 v[122:125], v[194:197], v[218:221], v[122:125]
	v_mfma_f32_16x16x32_bf16 v[118:121], v[174:177], v[226:229], v[118:121]
	v_mfma_f32_16x16x32_bf16 v[114:117], v[194:197], v[226:229], v[114:117]
	v_mfma_f32_16x16x32_bf16 v[110:113], v[174:177], v[234:237], v[110:113]
	v_mfma_f32_16x16x32_bf16 v[106:109], v[194:197], v[234:237], v[106:109]
	v_mfma_f32_16x16x32_bf16 v[102:105], v[174:177], v[242:245], v[102:105]
	v_mfma_f32_16x16x32_bf16 v[98:101], v[194:197], v[242:245], v[98:101]
	s_setprio 0
	s_setprio 1
	v_mfma_f32_16x16x32_bf16 v[62:65], v[198:201], v[214:217], v[62:65]
	v_mfma_f32_16x16x32_bf16 v[58:61], v[206:209], v[214:217], v[58:61]
	v_mfma_f32_16x16x32_bf16 v[54:57], v[198:201], v[222:225], v[54:57]
	v_mfma_f32_16x16x32_bf16 v[50:53], v[206:209], v[222:225], v[50:53]
	v_mfma_f32_16x16x32_bf16 v[46:49], v[198:201], v[230:233], v[46:49]
	v_mfma_f32_16x16x32_bf16 v[42:45], v[206:209], v[230:233], v[42:45]
	v_mfma_f32_16x16x32_bf16 v[38:41], v[198:201], v[238:241], v[38:41]
	v_mfma_f32_16x16x32_bf16 v[34:37], v[206:209], v[238:241], v[34:37]
	v_mfma_f32_16x16x32_bf16 v[62:65], v[202:205], v[218:221], v[62:65]
	v_mfma_f32_16x16x32_bf16 v[58:61], v[210:213], v[218:221], v[58:61]
	v_mfma_f32_16x16x32_bf16 v[54:57], v[202:205], v[226:229], v[54:57]
	v_mfma_f32_16x16x32_bf16 v[50:53], v[210:213], v[226:229], v[50:53]
	v_mfma_f32_16x16x32_bf16 v[46:49], v[202:205], v[234:237], v[46:49]
	v_mfma_f32_16x16x32_bf16 v[42:45], v[210:213], v[234:237], v[42:45]
	v_mfma_f32_16x16x32_bf16 v[38:41], v[202:205], v[242:245], v[38:41]
	v_mfma_f32_16x16x32_bf16 v[34:37], v[210:213], v[242:245], v[34:37]
	s_setprio 0
	s_barrier
	s_add_i32 s3, s3, s26
	v_lshl_add_u64 v[144:145], s[0:1], 0, v[4:5]
	s_mov_b32 m0, s3
	ds_read_b128 v[214:217], v172 offset:16384
	ds_read_b128 v[218:221], v172 offset:17408
	ds_read_b128 v[222:225], v172 offset:18432
	ds_read_b128 v[226:229], v172 offset:19456
	ds_read_b128 v[230:233], v172 offset:20480
	ds_read_b128 v[234:237], v172 offset:21504
	ds_read_b128 v[238:241], v172 offset:22528
	ds_read_b128 v[242:245], v172 offset:23552
	global_load_lds_dwordx4 v4, s[0:1]
	s_add_i32 m0, s3, 0x2000
	s_add_u32 s4, s0, 0x40000
	v_lshl_add_u64 v[246:247], s[0:1], 0, v[134:135]
	s_addc_u32 s5, s1, 0
	s_add_i32 s3, s6, s26
	global_load_lds_dwordx4 v134, s[0:1]
	s_mov_b32 m0, s3
	v_lshl_add_u64 v[250:251], s[14:15], 0, v[132:133]
	global_load_lds_dwordx4 v4, s[4:5]
	s_add_i32 m0, s3, 0x2000
	s_nop 0
	global_load_lds_dwordx4 v134, s[4:5]
	v_lshl_add_u64 v[248:249], s[14:15], 0, v[130:131]
	s_mov_b32 m0, s27
	s_nop 0
	global_load_lds_dwordx4 v130, s[14:15]
	s_mov_b32 m0, s30
	s_nop 0
	global_load_lds_dwordx4 v132, s[14:15]
	s_waitcnt vmcnt(8)
	s_waitcnt lgkmcnt(0)
	s_barrier
	s_setprio 1
	s_waitcnt lgkmcnt(0)
	v_mfma_f32_16x16x32_bf16 v[94:97], v[140:143], v[214:217], v[94:97]
	v_mfma_f32_16x16x32_bf16 v[90:93], v[190:193], v[214:217], v[90:93]
	v_mfma_f32_16x16x32_bf16 v[86:89], v[140:143], v[222:225], v[86:89]
	v_mfma_f32_16x16x32_bf16 v[82:85], v[190:193], v[222:225], v[82:85]
	v_mfma_f32_16x16x32_bf16 v[78:81], v[140:143], v[230:233], v[78:81]
	v_mfma_f32_16x16x32_bf16 v[74:77], v[190:193], v[230:233], v[74:77]
	v_mfma_f32_16x16x32_bf16 v[70:73], v[140:143], v[238:241], v[70:73]
	v_mfma_f32_16x16x32_bf16 v[66:69], v[190:193], v[238:241], v[66:69]
	v_mfma_f32_16x16x32_bf16 v[94:97], v[174:177], v[218:221], v[94:97]
	v_mfma_f32_16x16x32_bf16 v[90:93], v[194:197], v[218:221], v[90:93]
	v_mfma_f32_16x16x32_bf16 v[86:89], v[174:177], v[226:229], v[86:89]
	v_mfma_f32_16x16x32_bf16 v[82:85], v[194:197], v[226:229], v[82:85]
	v_mfma_f32_16x16x32_bf16 v[78:81], v[174:177], v[234:237], v[78:81]
	v_mfma_f32_16x16x32_bf16 v[74:77], v[194:197], v[234:237], v[74:77]
	v_mfma_f32_16x16x32_bf16 v[70:73], v[174:177], v[242:245], v[70:73]
	v_mfma_f32_16x16x32_bf16 v[66:69], v[194:197], v[242:245], v[66:69]
	s_setprio 0
	s_setprio 1
	v_mfma_f32_16x16x32_bf16 v[30:33], v[198:201], v[214:217], v[30:33]
	v_mfma_f32_16x16x32_bf16 v[26:29], v[206:209], v[214:217], v[26:29]
	v_mfma_f32_16x16x32_bf16 v[22:25], v[198:201], v[222:225], v[22:25]
	v_mfma_f32_16x16x32_bf16 v[18:21], v[206:209], v[222:225], v[18:21]
	v_mfma_f32_16x16x32_bf16 v[14:17], v[198:201], v[230:233], v[14:17]
	v_mfma_f32_16x16x32_bf16 v[10:13], v[206:209], v[230:233], v[10:13]
	v_mfma_f32_16x16x32_bf16 v[6:9], v[198:201], v[238:241], v[6:9]
	v_mfma_f32_16x16x32_bf16 v[0:3], v[206:209], v[238:241], v[0:3]
	v_mfma_f32_16x16x32_bf16 v[30:33], v[202:205], v[218:221], v[30:33]
	v_mfma_f32_16x16x32_bf16 v[26:29], v[210:213], v[218:221], v[26:29]
	v_mfma_f32_16x16x32_bf16 v[22:25], v[202:205], v[226:229], v[22:25]
	v_mfma_f32_16x16x32_bf16 v[18:21], v[210:213], v[226:229], v[18:21]
	v_mfma_f32_16x16x32_bf16 v[14:17], v[202:205], v[234:237], v[14:17]
	v_mfma_f32_16x16x32_bf16 v[10:13], v[210:213], v[234:237], v[10:13]
	v_mfma_f32_16x16x32_bf16 v[6:9], v[202:205], v[242:245], v[6:9]
	v_mfma_f32_16x16x32_bf16 v[0:3], v[210:213], v[242:245], v[0:3]
	s_setprio 0
	s_barrier
.Lpeelmid_205:
	s_add_i32 s3, 0, 0x18000
	v_add_u32_e32 v173, s3, v168
	s_add_i32 s6, 0, 0x1c000
	ds_read_b128 v[140:143], v173
	ds_read_b128 v[174:177], v173 offset:1024
	ds_read_b128 v[190:193], v173 offset:2048
	ds_read_b128 v[194:197], v173 offset:3072
	v_add_u32_e32 v173, s6, v168
	ds_read_b128 v[198:201], v173
	ds_read_b128 v[202:205], v173 offset:1024
	ds_read_b128 v[206:209], v173 offset:2048
	ds_read_b128 v[210:213], v173 offset:3072
	s_add_u32 s4, s14, 0x40000
	s_addc_u32 s5, s15, 0
	s_mov_b32 m0, s31
	ds_read_b128 v[214:217], v172 offset:32768
	ds_read_b128 v[218:221], v172 offset:33792
	ds_read_b128 v[222:225], v172 offset:34816
	ds_read_b128 v[226:229], v172 offset:35840
	ds_read_b128 v[230:233], v172 offset:36864
	ds_read_b128 v[234:237], v172 offset:37888
	ds_read_b128 v[238:241], v172 offset:38912
	ds_read_b128 v[242:245], v172 offset:39936
	global_load_lds_dwordx4 v130, s[4:5]
	v_lshl_add_u64 v[180:181], s[4:5], 0, v[132:133]
	s_mov_b32 m0, s34
	s_nop 0
	global_load_lds_dwordx4 v132, s[4:5]
	s_waitcnt vmcnt(8)
	s_waitcnt lgkmcnt(0)
	s_barrier
	s_setprio 1
	s_waitcnt lgkmcnt(0)
	v_mfma_f32_16x16x32_bf16 v[126:129], v[140:143], v[214:217], v[126:129]
	v_mfma_f32_16x16x32_bf16 v[122:125], v[190:193], v[214:217], v[122:125]
	v_mfma_f32_16x16x32_bf16 v[118:121], v[140:143], v[222:225], v[118:121]
	v_mfma_f32_16x16x32_bf16 v[114:117], v[190:193], v[222:225], v[114:117]
	v_mfma_f32_16x16x32_bf16 v[110:113], v[140:143], v[230:233], v[110:113]
	v_mfma_f32_16x16x32_bf16 v[106:109], v[190:193], v[230:233], v[106:109]
	v_mfma_f32_16x16x32_bf16 v[102:105], v[140:143], v[238:241], v[102:105]
	v_mfma_f32_16x16x32_bf16 v[98:101], v[190:193], v[238:241], v[98:101]
	v_mfma_f32_16x16x32_bf16 v[126:129], v[174:177], v[218:221], v[126:129]
	v_mfma_f32_16x16x32_bf16 v[122:125], v[194:197], v[218:221], v[122:125]
	v_mfma_f32_16x16x32_bf16 v[118:121], v[174:177], v[226:229], v[118:121]
	v_mfma_f32_16x16x32_bf16 v[114:117], v[194:197], v[226:229], v[114:117]
	v_mfma_f32_16x16x32_bf16 v[110:113], v[174:177], v[234:237], v[110:113]
	v_mfma_f32_16x16x32_bf16 v[106:109], v[194:197], v[234:237], v[106:109]
	v_mfma_f32_16x16x32_bf16 v[102:105], v[174:177], v[242:245], v[102:105]
	v_mfma_f32_16x16x32_bf16 v[98:101], v[194:197], v[242:245], v[98:101]
	s_setprio 0
	s_setprio 1
	v_mfma_f32_16x16x32_bf16 v[62:65], v[198:201], v[214:217], v[62:65]
	v_mfma_f32_16x16x32_bf16 v[58:61], v[206:209], v[214:217], v[58:61]
	v_mfma_f32_16x16x32_bf16 v[54:57], v[198:201], v[222:225], v[54:57]
	v_mfma_f32_16x16x32_bf16 v[50:53], v[206:209], v[222:225], v[50:53]
	v_mfma_f32_16x16x32_bf16 v[46:49], v[198:201], v[230:233], v[46:49]
	v_mfma_f32_16x16x32_bf16 v[42:45], v[206:209], v[230:233], v[42:45]
	v_mfma_f32_16x16x32_bf16 v[38:41], v[198:201], v[238:241], v[38:41]
	v_mfma_f32_16x16x32_bf16 v[34:37], v[206:209], v[238:241], v[34:37]
	v_mfma_f32_16x16x32_bf16 v[62:65], v[202:205], v[218:221], v[62:65]
	v_mfma_f32_16x16x32_bf16 v[58:61], v[210:213], v[218:221], v[58:61]
	v_mfma_f32_16x16x32_bf16 v[54:57], v[202:205], v[226:229], v[54:57]
	v_mfma_f32_16x16x32_bf16 v[50:53], v[210:213], v[226:229], v[50:53]
	v_mfma_f32_16x16x32_bf16 v[46:49], v[202:205], v[234:237], v[46:49]
	v_mfma_f32_16x16x32_bf16 v[42:45], v[210:213], v[234:237], v[42:45]
	v_mfma_f32_16x16x32_bf16 v[38:41], v[202:205], v[242:245], v[38:41]
	v_mfma_f32_16x16x32_bf16 v[34:37], v[210:213], v[242:245], v[34:37]
	s_setprio 0
	s_barrier
	s_add_i32 s3, s3, s26
	v_lshl_add_u64 v[144:145], v[144:145], 0, s[70:71]
	s_mov_b32 m0, s3
	ds_read_b128 v[214:217], v172 offset:49152
	ds_read_b128 v[218:221], v172 offset:50176
	ds_read_b128 v[222:225], v172 offset:51200
	ds_read_b128 v[226:229], v172 offset:52224
	ds_read_b128 v[230:233], v172 offset:53248
	ds_read_b128 v[234:237], v172 offset:54272
	ds_read_b128 v[238:241], v172 offset:55296
	ds_read_b128 v[242:245], v172 offset:56320
	global_load_lds_dwordx4 v[144:145], off
	s_add_i32 m0, s3, 0x2000
	s_add_u32 s0, s0, 0x40080
	v_lshl_add_u64 v[144:145], v[246:247], 0, s[70:71]
	s_addc_u32 s1, s1, 0
	s_add_i32 s3, s6, s26
	global_load_lds_dwordx4 v[144:145], off
	s_mov_b32 m0, s3
	s_nop 0
	global_load_lds_dwordx4 v4, s[0:1]
	s_add_i32 m0, s3, 0x2000
	s_nop 0
	global_load_lds_dwordx4 v134, s[0:1]
	v_lshl_add_u64 v[144:145], v[248:249], 0, s[70:71]
	s_mov_b32 m0, s35
	s_nop 0
	global_load_lds_dwordx4 v[144:145], off
	v_lshl_add_u64 v[144:145], v[250:251], 0, s[70:71]
	s_mov_b32 m0, s36
	s_nop 0
	global_load_lds_dwordx4 v[144:145], off
	s_waitcnt vmcnt(8)
	s_waitcnt lgkmcnt(0)
	s_barrier
	s_setprio 1
	s_waitcnt lgkmcnt(0)
	v_mfma_f32_16x16x32_bf16 v[94:97], v[140:143], v[214:217], v[94:97]
	v_mfma_f32_16x16x32_bf16 v[90:93], v[190:193], v[214:217], v[90:93]
	v_mfma_f32_16x16x32_bf16 v[86:89], v[140:143], v[222:225], v[86:89]
	v_mfma_f32_16x16x32_bf16 v[82:85], v[190:193], v[222:225], v[82:85]
	v_mfma_f32_16x16x32_bf16 v[78:81], v[140:143], v[230:233], v[78:81]
	v_mfma_f32_16x16x32_bf16 v[74:77], v[190:193], v[230:233], v[74:77]
	v_mfma_f32_16x16x32_bf16 v[70:73], v[140:143], v[238:241], v[70:73]
	v_mfma_f32_16x16x32_bf16 v[66:69], v[190:193], v[238:241], v[66:69]
	v_mfma_f32_16x16x32_bf16 v[94:97], v[174:177], v[218:221], v[94:97]
	v_mfma_f32_16x16x32_bf16 v[90:93], v[194:197], v[218:221], v[90:93]
	v_mfma_f32_16x16x32_bf16 v[86:89], v[174:177], v[226:229], v[86:89]
	v_mfma_f32_16x16x32_bf16 v[82:85], v[194:197], v[226:229], v[82:85]
	v_mfma_f32_16x16x32_bf16 v[78:81], v[174:177], v[234:237], v[78:81]
	v_mfma_f32_16x16x32_bf16 v[74:77], v[194:197], v[234:237], v[74:77]
	v_mfma_f32_16x16x32_bf16 v[70:73], v[174:177], v[242:245], v[70:73]
	v_mfma_f32_16x16x32_bf16 v[66:69], v[194:197], v[242:245], v[66:69]
	s_setprio 0
	s_setprio 1
	v_mfma_f32_16x16x32_bf16 v[30:33], v[198:201], v[214:217], v[30:33]
	v_mfma_f32_16x16x32_bf16 v[26:29], v[206:209], v[214:217], v[26:29]
	v_mfma_f32_16x16x32_bf16 v[22:25], v[198:201], v[222:225], v[22:25]
	v_mfma_f32_16x16x32_bf16 v[18:21], v[206:209], v[222:225], v[18:21]
	v_mfma_f32_16x16x32_bf16 v[14:17], v[198:201], v[230:233], v[14:17]
	v_mfma_f32_16x16x32_bf16 v[10:13], v[206:209], v[230:233], v[10:13]
	v_mfma_f32_16x16x32_bf16 v[6:9], v[198:201], v[238:241], v[6:9]
	v_mfma_f32_16x16x32_bf16 v[0:3], v[206:209], v[238:241], v[0:3]
	v_mfma_f32_16x16x32_bf16 v[30:33], v[202:205], v[218:221], v[30:33]
	v_mfma_f32_16x16x32_bf16 v[26:29], v[210:213], v[218:221], v[26:29]
	v_mfma_f32_16x16x32_bf16 v[22:25], v[202:205], v[226:229], v[22:25]
	v_mfma_f32_16x16x32_bf16 v[18:21], v[210:213], v[226:229], v[18:21]
	v_mfma_f32_16x16x32_bf16 v[14:17], v[202:205], v[234:237], v[14:17]
	v_mfma_f32_16x16x32_bf16 v[10:13], v[210:213], v[234:237], v[10:13]
	v_mfma_f32_16x16x32_bf16 v[6:9], v[202:205], v[242:245], v[6:9]
	v_mfma_f32_16x16x32_bf16 v[0:3], v[210:213], v[242:245], v[0:3]
	s_setprio 0
	s_barrier
	s_add_i32 s24, s24, 2
	s_add_u32 s22, s22, 0x100
	s_addc_u32 s23, s23, 0
	s_add_u32 s9, s9, 0x100
	s_addc_u32 s10, s10, 0
	s_cmp_gt_u32 s24, 13
	s_cbranch_scc0 .LBB0_205
	s_and_b64 vcc, exec, s[46:47]
	s_cbranch_vccz .LBB0_208
	s_barrier

.LBB0_227:
	s_ashr_i32 s47, s46, 31
	s_lshl_b64 s[2:3], s[46:47], 19
	v_readlane_b32 s4, v253, 25
	v_readlane_b32 s5, v253, 26
	s_add_u32 s82, s4, s2
	s_addc_u32 s83, s5, s3
	s_and_b64 s[2:3], s[40:41], exec
	s_cselect_b32 s2, s83, s15
	s_cselect_b32 s8, s82, s14
	s_add_u32 s22, s0, 0x40080
	s_addc_u32 s23, s1, 0
	s_add_u32 s9, s14, 0x100
	v_mov_b32_e32 v0, 0
	s_addc_u32 s10, s15, 0
	s_mov_b32 s24, -2
	v_mov_b32_e32 v1, v0
	v_mov_b32_e32 v2, v0
	v_mov_b32_e32 v3, v0
	v_mov_b32_e32 v6, v0
	v_mov_b32_e32 v7, v0
	v_mov_b32_e32 v8, v0
	v_mov_b32_e32 v9, v0
	v_mov_b32_e32 v10, v0
	v_mov_b32_e32 v11, v0
	v_mov_b32_e32 v12, v0
	v_mov_b32_e32 v13, v0
	v_mov_b32_e32 v14, v0
	v_mov_b32_e32 v15, v0
	v_mov_b32_e32 v16, v0
	v_mov_b32_e32 v17, v0
	v_mov_b32_e32 v18, v0
	v_mov_b32_e32 v19, v0
	v_mov_b32_e32 v20, v0
	v_mov_b32_e32 v21, v0
	v_mov_b32_e32 v22, v0
	v_mov_b32_e32 v23, v0
	v_mov_b32_e32 v24, v0
	v_mov_b32_e32 v25, v0
	v_mov_b32_e32 v26, v0
	v_mov_b32_e32 v27, v0
	v_mov_b32_e32 v28, v0
	v_mov_b32_e32 v29, v0
	v_mov_b32_e32 v30, v0
	v_mov_b32_e32 v31, v0
	v_mov_b32_e32 v32, v0
	v_mov_b32_e32 v33, v0
	v_mov_b32_e32 v62, v0
	v_mov_b32_e32 v63, v0
	v_mov_b32_e32 v64, v0
	v_mov_b32_e32 v65, v0
	v_mov_b32_e32 v70, v0
	v_mov_b32_e32 v71, v0
	v_mov_b32_e32 v72, v0
	v_mov_b32_e32 v73, v0
	v_mov_b32_e32 v74, v0
	v_mov_b32_e32 v75, v0
	v_mov_b32_e32 v76, v0
	v_mov_b32_e32 v77, v0
	v_mov_b32_e32 v78, v0
	v_mov_b32_e32 v79, v0
	v_mov_b32_e32 v80, v0
	v_mov_b32_e32 v81, v0
	v_mov_b32_e32 v82, v0
	v_mov_b32_e32 v83, v0
	v_mov_b32_e32 v84, v0
	v_mov_b32_e32 v85, v0
	v_mov_b32_e32 v86, v0
	v_mov_b32_e32 v87, v0
	v_mov_b32_e32 v88, v0
	v_mov_b32_e32 v89, v0
	v_mov_b32_e32 v90, v0
	v_mov_b32_e32 v91, v0
	v_mov_b32_e32 v92, v0
	v_mov_b32_e32 v93, v0
	v_mov_b32_e32 v94, v0
	v_mov_b32_e32 v95, v0
	v_mov_b32_e32 v96, v0
	v_mov_b32_e32 v97, v0
	v_mov_b32_e32 v34, v0
	v_mov_b32_e32 v35, v0
	v_mov_b32_e32 v36, v0
	v_mov_b32_e32 v37, v0
	v_mov_b32_e32 v38, v0
	v_mov_b32_e32 v39, v0
	v_mov_b32_e32 v40, v0
	v_mov_b32_e32 v41, v0
	v_mov_b32_e32 v42, v0
	v_mov_b32_e32 v43, v0
	v_mov_b32_e32 v44, v0
	v_mov_b32_e32 v45, v0
	v_mov_b32_e32 v46, v0
	v_mov_b32_e32 v47, v0
	v_mov_b32_e32 v48, v0
	v_mov_b32_e32 v49, v0
	v_mov_b32_e32 v50, v0
	v_mov_b32_e32 v51, v0
	v_mov_b32_e32 v52, v0
	v_mov_b32_e32 v53, v0
	v_mov_b32_e32 v54, v0
	v_mov_b32_e32 v55, v0
	v_mov_b32_e32 v56, v0
	v_mov_b32_e32 v57, v0
	v_mov_b32_e32 v58, v0
	v_mov_b32_e32 v59, v0
	v_mov_b32_e32 v60, v0
	v_mov_b32_e32 v61, v0
	v_mov_b32_e32 v66, v0
	v_mov_b32_e32 v67, v0
	v_mov_b32_e32 v68, v0
	v_mov_b32_e32 v69, v0
	v_mov_b32_e32 v98, v0
	v_mov_b32_e32 v99, v0
	v_mov_b32_e32 v100, v0
	v_mov_b32_e32 v101, v0
	v_mov_b32_e32 v102, v0
	v_mov_b32_e32 v103, v0
	v_mov_b32_e32 v104, v0
	v_mov_b32_e32 v105, v0
	v_mov_b32_e32 v106, v0
	v_mov_b32_e32 v107, v0
	v_mov_b32_e32 v108, v0
	v_mov_b32_e32 v109, v0
	v_mov_b32_e32 v110, v0
	v_mov_b32_e32 v111, v0
	v_mov_b32_e32 v112, v0
	v_mov_b32_e32 v113, v0
	v_mov_b32_e32 v114, v0
	v_mov_b32_e32 v115, v0
	v_mov_b32_e32 v116, v0
	v_mov_b32_e32 v117, v0
	v_mov_b32_e32 v118, v0
	v_mov_b32_e32 v119, v0
	v_mov_b32_e32 v120, v0
	v_mov_b32_e32 v121, v0
	v_mov_b32_e32 v122, v0
	v_mov_b32_e32 v123, v0
	v_mov_b32_e32 v124, v0
	v_mov_b32_e32 v125, v0
	v_mov_b32_e32 v126, v0
	v_mov_b32_e32 v127, v0
	v_mov_b32_e32 v128, v0
	v_mov_b32_e32 v129, v0
	s_cmp_eq_u32 s37, 1
	s_cbranch_scc1 .LBB0_228
	s_add_u32 s0, s22, 0xfffc0080
	s_addc_u32 s1, s23, -1
	s_add_i32 s3, 0, 0x10000
	s_cmp_eq_u32 s24, 12
	s_cselect_b32 s15, s49, s1
	s_cselect_b32 s14, s48, s0
	v_add_u32_e32 v162, s3, v149
	s_cselect_b32 s1, s2, s10
	s_cselect_b32 s0, s8, s9
	s_add_i32 s6, 0, 0x14000
	ds_read_b128 v[140:143], v162
	ds_read_b128 v[144:147], v162 offset:1024
	ds_read_b128 v[172:175], v162 offset:2048
	ds_read_b128 v[190:193], v162 offset:3072
	v_add_u32_e32 v162, s6, v149
	ds_read_b128 v[194:197], v162
	ds_read_b128 v[198:201], v162 offset:1024
	ds_read_b128 v[202:205], v162 offset:2048
	ds_read_b128 v[206:209], v162 offset:3072
	s_add_i32 m0, s27, 0xc000
	ds_read_b128 v[210:213], v151
	ds_read_b128 v[214:217], v151 offset:1024
	ds_read_b128 v[218:221], v151 offset:2048
	ds_read_b128 v[222:225], v151 offset:3072
	ds_read_b128 v[226:229], v151 offset:4096
	ds_read_b128 v[230:233], v151 offset:5120
	ds_read_b128 v[234:237], v151 offset:6144
	ds_read_b128 v[238:241], v151 offset:7168
	global_load_lds_dwordx4 v136, s[22:23]
	s_add_i32 m0, s27, 0xe000
	s_nop 0
	global_load_lds_dwordx4 v138, s[22:23]
	s_waitcnt vmcnt(24)
	s_waitcnt lgkmcnt(0)
	s_barrier
	s_setprio 1
	s_waitcnt lgkmcnt(0)
	v_mfma_f32_16x16x32_bf16 v[126:129], v[140:143], v[210:213], v[126:129]
	v_mfma_f32_16x16x32_bf16 v[122:125], v[172:175], v[210:213], v[122:125]
	v_mfma_f32_16x16x32_bf16 v[118:121], v[140:143], v[218:221], v[118:121]
	v_mfma_f32_16x16x32_bf16 v[114:117], v[172:175], v[218:221], v[114:117]
	v_mfma_f32_16x16x32_bf16 v[110:113], v[140:143], v[226:229], v[110:113]
	v_mfma_f32_16x16x32_bf16 v[106:109], v[172:175], v[226:229], v[106:109]
	v_mfma_f32_16x16x32_bf16 v[102:105], v[140:143], v[234:237], v[102:105]
	v_mfma_f32_16x16x32_bf16 v[98:101], v[172:175], v[234:237], v[98:101]
	v_mfma_f32_16x16x32_bf16 v[126:129], v[144:147], v[214:217], v[126:129]
	v_mfma_f32_16x16x32_bf16 v[122:125], v[190:193], v[214:217], v[122:125]
	v_mfma_f32_16x16x32_bf16 v[118:121], v[144:147], v[222:225], v[118:121]
	v_mfma_f32_16x16x32_bf16 v[114:117], v[190:193], v[222:225], v[114:117]
	v_mfma_f32_16x16x32_bf16 v[110:113], v[144:147], v[230:233], v[110:113]
	v_mfma_f32_16x16x32_bf16 v[106:109], v[190:193], v[230:233], v[106:109]
	v_mfma_f32_16x16x32_bf16 v[102:105], v[144:147], v[238:241], v[102:105]
	v_mfma_f32_16x16x32_bf16 v[98:101], v[190:193], v[238:241], v[98:101]
	s_setprio 0
	s_setprio 1
	v_mfma_f32_16x16x32_bf16 v[66:69], v[194:197], v[210:213], v[66:69]
	v_mfma_f32_16x16x32_bf16 v[58:61], v[202:205], v[210:213], v[58:61]
	v_mfma_f32_16x16x32_bf16 v[54:57], v[194:197], v[218:221], v[54:57]
	v_mfma_f32_16x16x32_bf16 v[50:53], v[202:205], v[218:221], v[50:53]
	v_mfma_f32_16x16x32_bf16 v[46:49], v[194:197], v[226:229], v[46:49]
	v_mfma_f32_16x16x32_bf16 v[42:45], v[202:205], v[226:229], v[42:45]
	v_mfma_f32_16x16x32_bf16 v[38:41], v[194:197], v[234:237], v[38:41]
	v_mfma_f32_16x16x32_bf16 v[34:37], v[202:205], v[234:237], v[34:37]
	v_mfma_f32_16x16x32_bf16 v[66:69], v[198:201], v[214:217], v[66:69]
	v_mfma_f32_16x16x32_bf16 v[58:61], v[206:209], v[214:217], v[58:61]
	v_mfma_f32_16x16x32_bf16 v[54:57], v[198:201], v[222:225], v[54:57]
	v_mfma_f32_16x16x32_bf16 v[50:53], v[206:209], v[222:225], v[50:53]
	v_mfma_f32_16x16x32_bf16 v[46:49], v[198:201], v[230:233], v[46:49]
	v_mfma_f32_16x16x32_bf16 v[42:45], v[206:209], v[230:233], v[42:45]
	v_mfma_f32_16x16x32_bf16 v[38:41], v[198:201], v[238:241], v[38:41]
	v_mfma_f32_16x16x32_bf16 v[34:37], v[206:209], v[238:241], v[34:37]
	s_setprio 0
	s_barrier
	s_add_i32 s3, s3, s26
	v_lshl_add_u64 v[162:163], s[0:1], 0, v[4:5]
	s_mov_b32 m0, s3
	ds_read_b128 v[210:213], v151 offset:16384
	ds_read_b128 v[214:217], v151 offset:17408
	ds_read_b128 v[218:221], v151 offset:18432
	ds_read_b128 v[222:225], v151 offset:19456
	ds_read_b128 v[226:229], v151 offset:20480
	ds_read_b128 v[230:233], v151 offset:21504
	ds_read_b128 v[234:237], v151 offset:22528
	ds_read_b128 v[238:241], v151 offset:23552
	global_load_lds_dwordx4 v4, s[0:1]
	s_add_i32 m0, s3, 0x2000
	s_add_u32 s4, s0, 0x40000
	v_lshl_add_u64 v[166:167], s[0:1], 0, v[134:135]
	s_addc_u32 s5, s1, 0
	s_add_i32 s3, s6, s26
	global_load_lds_dwordx4 v134, s[0:1]
	s_mov_b32 m0, s3
	v_lshl_add_u64 v[180:181], s[14:15], 0, v[132:133]
	global_load_lds_dwordx4 v4, s[4:5]
	s_add_i32 m0, s3, 0x2000
	s_nop 0
	global_load_lds_dwordx4 v134, s[4:5]
	v_lshl_add_u64 v[176:177], s[14:15], 0, v[130:131]
	s_mov_b32 m0, s27
	s_nop 0
	global_load_lds_dwordx4 v130, s[14:15]
	s_mov_b32 m0, s30
	s_nop 0
	global_load_lds_dwordx4 v132, s[14:15]
	s_waitcnt vmcnt(24)
	s_waitcnt lgkmcnt(0)
	s_barrier
	s_setprio 1
	s_waitcnt lgkmcnt(0)
	v_mfma_f32_16x16x32_bf16 v[94:97], v[140:143], v[210:213], v[94:97]
	v_mfma_f32_16x16x32_bf16 v[90:93], v[172:175], v[210:213], v[90:93]
	v_mfma_f32_16x16x32_bf16 v[86:89], v[140:143], v[218:221], v[86:89]
	v_mfma_f32_16x16x32_bf16 v[82:85], v[172:175], v[218:221], v[82:85]
	v_mfma_f32_16x16x32_bf16 v[78:81], v[140:143], v[226:229], v[78:81]
	v_mfma_f32_16x16x32_bf16 v[74:77], v[172:175], v[226:229], v[74:77]
	v_mfma_f32_16x16x32_bf16 v[70:73], v[140:143], v[234:237], v[70:73]
	v_mfma_f32_16x16x32_bf16 v[62:65], v[172:175], v[234:237], v[62:65]
	v_mfma_f32_16x16x32_bf16 v[94:97], v[144:147], v[214:217], v[94:97]
	v_mfma_f32_16x16x32_bf16 v[90:93], v[190:193], v[214:217], v[90:93]
	v_mfma_f32_16x16x32_bf16 v[86:89], v[144:147], v[222:225], v[86:89]
	v_mfma_f32_16x16x32_bf16 v[82:85], v[190:193], v[222:225], v[82:85]
	v_mfma_f32_16x16x32_bf16 v[78:81], v[144:147], v[230:233], v[78:81]
	v_mfma_f32_16x16x32_bf16 v[74:77], v[190:193], v[230:233], v[74:77]
	v_mfma_f32_16x16x32_bf16 v[70:73], v[144:147], v[238:241], v[70:73]
	v_mfma_f32_16x16x32_bf16 v[62:65], v[190:193], v[238:241], v[62:65]
	s_setprio 0
	s_setprio 1
	v_mfma_f32_16x16x32_bf16 v[30:33], v[194:197], v[210:213], v[30:33]
	v_mfma_f32_16x16x32_bf16 v[26:29], v[202:205], v[210:213], v[26:29]
	v_mfma_f32_16x16x32_bf16 v[22:25], v[194:197], v[218:221], v[22:25]
	v_mfma_f32_16x16x32_bf16 v[18:21], v[202:205], v[218:221], v[18:21]
	v_mfma_f32_16x16x32_bf16 v[14:17], v[194:197], v[226:229], v[14:17]
	v_mfma_f32_16x16x32_bf16 v[10:13], v[202:205], v[226:229], v[10:13]
	v_mfma_f32_16x16x32_bf16 v[6:9], v[194:197], v[234:237], v[6:9]
	v_mfma_f32_16x16x32_bf16 v[0:3], v[202:205], v[234:237], v[0:3]
	v_mfma_f32_16x16x32_bf16 v[30:33], v[198:201], v[214:217], v[30:33]
	v_mfma_f32_16x16x32_bf16 v[26:29], v[206:209], v[214:217], v[26:29]
	v_mfma_f32_16x16x32_bf16 v[22:25], v[198:201], v[222:225], v[22:25]
	v_mfma_f32_16x16x32_bf16 v[18:21], v[206:209], v[222:225], v[18:21]
	v_mfma_f32_16x16x32_bf16 v[14:17], v[198:201], v[230:233], v[14:17]
	v_mfma_f32_16x16x32_bf16 v[10:13], v[206:209], v[230:233], v[10:13]
	v_mfma_f32_16x16x32_bf16 v[6:9], v[198:201], v[238:241], v[6:9]
	v_mfma_f32_16x16x32_bf16 v[0:3], v[206:209], v[238:241], v[0:3]
	s_setprio 0
	s_barrier
	s_branch .Lpeelmid_228
.LBB0_228:
	s_add_u32 s0, s22, 0xfffc0080
	s_addc_u32 s1, s23, -1
	s_add_i32 s3, 0, 0x10000
	s_cmp_eq_u32 s24, 12
	s_cselect_b32 s15, s49, s1
	s_cselect_b32 s14, s48, s0
	v_add_u32_e32 v162, s3, v149
	s_cselect_b32 s1, s2, s10
	s_cselect_b32 s0, s8, s9
	s_add_i32 s6, 0, 0x14000
	ds_read_b128 v[140:143], v162
	ds_read_b128 v[144:147], v162 offset:1024
	ds_read_b128 v[172:175], v162 offset:2048
	ds_read_b128 v[190:193], v162 offset:3072
	v_add_u32_e32 v162, s6, v149
	ds_read_b128 v[194:197], v162
	ds_read_b128 v[198:201], v162 offset:1024
	ds_read_b128 v[202:205], v162 offset:2048
	ds_read_b128 v[206:209], v162 offset:3072
	s_add_i32 m0, s27, 0xc000
	ds_read_b128 v[210:213], v151
	ds_read_b128 v[214:217], v151 offset:1024
	ds_read_b128 v[218:221], v151 offset:2048
	ds_read_b128 v[222:225], v151 offset:3072
	ds_read_b128 v[226:229], v151 offset:4096
	ds_read_b128 v[230:233], v151 offset:5120
	ds_read_b128 v[234:237], v151 offset:6144
	ds_read_b128 v[238:241], v151 offset:7168
	global_load_lds_dwordx4 v136, s[22:23]
	s_add_i32 m0, s27, 0xe000
	s_nop 0
	global_load_lds_dwordx4 v138, s[22:23]
	s_waitcnt vmcnt(8)
	s_waitcnt lgkmcnt(0)
	s_barrier
	s_setprio 1
	s_waitcnt lgkmcnt(0)
	v_mfma_f32_16x16x32_bf16 v[126:129], v[140:143], v[210:213], v[126:129]
	v_mfma_f32_16x16x32_bf16 v[122:125], v[172:175], v[210:213], v[122:125]
	v_mfma_f32_16x16x32_bf16 v[118:121], v[140:143], v[218:221], v[118:121]
	v_mfma_f32_16x16x32_bf16 v[114:117], v[172:175], v[218:221], v[114:117]
	v_mfma_f32_16x16x32_bf16 v[110:113], v[140:143], v[226:229], v[110:113]
	v_mfma_f32_16x16x32_bf16 v[106:109], v[172:175], v[226:229], v[106:109]
	v_mfma_f32_16x16x32_bf16 v[102:105], v[140:143], v[234:237], v[102:105]
	v_mfma_f32_16x16x32_bf16 v[98:101], v[172:175], v[234:237], v[98:101]
	v_mfma_f32_16x16x32_bf16 v[126:129], v[144:147], v[214:217], v[126:129]
	v_mfma_f32_16x16x32_bf16 v[122:125], v[190:193], v[214:217], v[122:125]
	v_mfma_f32_16x16x32_bf16 v[118:121], v[144:147], v[222:225], v[118:121]
	v_mfma_f32_16x16x32_bf16 v[114:117], v[190:193], v[222:225], v[114:117]
	v_mfma_f32_16x16x32_bf16 v[110:113], v[144:147], v[230:233], v[110:113]
	v_mfma_f32_16x16x32_bf16 v[106:109], v[190:193], v[230:233], v[106:109]
	v_mfma_f32_16x16x32_bf16 v[102:105], v[144:147], v[238:241], v[102:105]
	v_mfma_f32_16x16x32_bf16 v[98:101], v[190:193], v[238:241], v[98:101]
	s_setprio 0
	s_setprio 1
	v_mfma_f32_16x16x32_bf16 v[66:69], v[194:197], v[210:213], v[66:69]
	v_mfma_f32_16x16x32_bf16 v[58:61], v[202:205], v[210:213], v[58:61]
	v_mfma_f32_16x16x32_bf16 v[54:57], v[194:197], v[218:221], v[54:57]
	v_mfma_f32_16x16x32_bf16 v[50:53], v[202:205], v[218:221], v[50:53]
	v_mfma_f32_16x16x32_bf16 v[46:49], v[194:197], v[226:229], v[46:49]
	v_mfma_f32_16x16x32_bf16 v[42:45], v[202:205], v[226:229], v[42:45]
	v_mfma_f32_16x16x32_bf16 v[38:41], v[194:197], v[234:237], v[38:41]
	v_mfma_f32_16x16x32_bf16 v[34:37], v[202:205], v[234:237], v[34:37]
	v_mfma_f32_16x16x32_bf16 v[66:69], v[198:201], v[214:217], v[66:69]
	v_mfma_f32_16x16x32_bf16 v[58:61], v[206:209], v[214:217], v[58:61]
	v_mfma_f32_16x16x32_bf16 v[54:57], v[198:201], v[222:225], v[54:57]
	v_mfma_f32_16x16x32_bf16 v[50:53], v[206:209], v[222:225], v[50:53]
	v_mfma_f32_16x16x32_bf16 v[46:49], v[198:201], v[230:233], v[46:49]
	v_mfma_f32_16x16x32_bf16 v[42:45], v[206:209], v[230:233], v[42:45]
	v_mfma_f32_16x16x32_bf16 v[38:41], v[198:201], v[238:241], v[38:41]
	v_mfma_f32_16x16x32_bf16 v[34:37], v[206:209], v[238:241], v[34:37]
	s_setprio 0
	s_barrier
	s_add_i32 s3, s3, s26
	v_lshl_add_u64 v[162:163], s[0:1], 0, v[4:5]
	s_mov_b32 m0, s3
	ds_read_b128 v[210:213], v151 offset:16384
	ds_read_b128 v[214:217], v151 offset:17408
	ds_read_b128 v[218:221], v151 offset:18432
	ds_read_b128 v[222:225], v151 offset:19456
	ds_read_b128 v[226:229], v151 offset:20480
	ds_read_b128 v[230:233], v151 offset:21504
	ds_read_b128 v[234:237], v151 offset:22528
	ds_read_b128 v[238:241], v151 offset:23552
	global_load_lds_dwordx4 v4, s[0:1]
	s_add_i32 m0, s3, 0x2000
	s_add_u32 s4, s0, 0x40000
	v_lshl_add_u64 v[166:167], s[0:1], 0, v[134:135]
	s_addc_u32 s5, s1, 0
	s_add_i32 s3, s6, s26
	global_load_lds_dwordx4 v134, s[0:1]
	s_mov_b32 m0, s3
	v_lshl_add_u64 v[180:181], s[14:15], 0, v[132:133]
	global_load_lds_dwordx4 v4, s[4:5]
	s_add_i32 m0, s3, 0x2000
	s_nop 0
	global_load_lds_dwordx4 v134, s[4:5]
	v_lshl_add_u64 v[176:177], s[14:15], 0, v[130:131]
	s_mov_b32 m0, s27
	s_nop 0
	global_load_lds_dwordx4 v130, s[14:15]
	s_mov_b32 m0, s30
	s_nop 0
	global_load_lds_dwordx4 v132, s[14:15]
	s_waitcnt vmcnt(8)
	s_waitcnt lgkmcnt(0)
	s_barrier
	s_setprio 1
	s_waitcnt lgkmcnt(0)
	v_mfma_f32_16x16x32_bf16 v[94:97], v[140:143], v[210:213], v[94:97]
	v_mfma_f32_16x16x32_bf16 v[90:93], v[172:175], v[210:213], v[90:93]
	v_mfma_f32_16x16x32_bf16 v[86:89], v[140:143], v[218:221], v[86:89]
	v_mfma_f32_16x16x32_bf16 v[82:85], v[172:175], v[218:221], v[82:85]
	v_mfma_f32_16x16x32_bf16 v[78:81], v[140:143], v[226:229], v[78:81]
	v_mfma_f32_16x16x32_bf16 v[74:77], v[172:175], v[226:229], v[74:77]
	v_mfma_f32_16x16x32_bf16 v[70:73], v[140:143], v[234:237], v[70:73]
	v_mfma_f32_16x16x32_bf16 v[62:65], v[172:175], v[234:237], v[62:65]
	v_mfma_f32_16x16x32_bf16 v[94:97], v[144:147], v[214:217], v[94:97]
	v_mfma_f32_16x16x32_bf16 v[90:93], v[190:193], v[214:217], v[90:93]
	v_mfma_f32_16x16x32_bf16 v[86:89], v[144:147], v[222:225], v[86:89]
	v_mfma_f32_16x16x32_bf16 v[82:85], v[190:193], v[222:225], v[82:85]
	v_mfma_f32_16x16x32_bf16 v[78:81], v[144:147], v[230:233], v[78:81]
	v_mfma_f32_16x16x32_bf16 v[74:77], v[190:193], v[230:233], v[74:77]
	v_mfma_f32_16x16x32_bf16 v[70:73], v[144:147], v[238:241], v[70:73]
	v_mfma_f32_16x16x32_bf16 v[62:65], v[190:193], v[238:241], v[62:65]
	s_setprio 0
	s_setprio 1
	v_mfma_f32_16x16x32_bf16 v[30:33], v[194:197], v[210:213], v[30:33]
	v_mfma_f32_16x16x32_bf16 v[26:29], v[202:205], v[210:213], v[26:29]
	v_mfma_f32_16x16x32_bf16 v[22:25], v[194:197], v[218:221], v[22:25]
	v_mfma_f32_16x16x32_bf16 v[18:21], v[202:205], v[218:221], v[18:21]
	v_mfma_f32_16x16x32_bf16 v[14:17], v[194:197], v[226:229], v[14:17]
	v_mfma_f32_16x16x32_bf16 v[10:13], v[202:205], v[226:229], v[10:13]
	v_mfma_f32_16x16x32_bf16 v[6:9], v[194:197], v[234:237], v[6:9]
	v_mfma_f32_16x16x32_bf16 v[0:3], v[202:205], v[234:237], v[0:3]
	v_mfma_f32_16x16x32_bf16 v[30:33], v[198:201], v[214:217], v[30:33]
	v_mfma_f32_16x16x32_bf16 v[26:29], v[206:209], v[214:217], v[26:29]
	v_mfma_f32_16x16x32_bf16 v[22:25], v[198:201], v[222:225], v[22:25]
	v_mfma_f32_16x16x32_bf16 v[18:21], v[206:209], v[222:225], v[18:21]
	v_mfma_f32_16x16x32_bf16 v[14:17], v[198:201], v[230:233], v[14:17]
	v_mfma_f32_16x16x32_bf16 v[10:13], v[206:209], v[230:233], v[10:13]
	v_mfma_f32_16x16x32_bf16 v[6:9], v[198:201], v[238:241], v[6:9]
	v_mfma_f32_16x16x32_bf16 v[0:3], v[206:209], v[238:241], v[0:3]
	s_setprio 0
	s_barrier
.Lpeelmid_228:
	s_add_i32 s3, 0, 0x18000
	v_add_u32_e32 v164, s3, v149
	s_add_i32 s6, 0, 0x1c000
	ds_read_b128 v[140:143], v164
	ds_read_b128 v[144:147], v164 offset:1024
	ds_read_b128 v[172:175], v164 offset:2048
	ds_read_b128 v[190:193], v164 offset:3072
	v_add_u32_e32 v164, s6, v149
	ds_read_b128 v[194:197], v164
	ds_read_b128 v[198:201], v164 offset:1024
	ds_read_b128 v[202:205], v164 offset:2048
	ds_read_b128 v[206:209], v164 offset:3072
	s_add_u32 s4, s14, 0x40000
	s_addc_u32 s5, s15, 0
	s_mov_b32 m0, s31
	ds_read_b128 v[210:213], v151 offset:32768
	ds_read_b128 v[214:217], v151 offset:33792
	ds_read_b128 v[218:221], v151 offset:34816
	ds_read_b128 v[222:225], v151 offset:35840
	ds_read_b128 v[226:229], v151 offset:36864
	ds_read_b128 v[230:233], v151 offset:37888
	ds_read_b128 v[234:237], v151 offset:38912
	ds_read_b128 v[238:241], v151 offset:39936
	global_load_lds_dwordx4 v130, s[4:5]
	v_lshl_add_u64 v[242:243], s[4:5], 0, v[132:133]
	s_mov_b32 m0, s34
	s_nop 0
	global_load_lds_dwordx4 v132, s[4:5]
	s_waitcnt vmcnt(8)
	s_waitcnt lgkmcnt(0)
	s_barrier
	s_setprio 1
	s_waitcnt lgkmcnt(0)
	v_mfma_f32_16x16x32_bf16 v[126:129], v[140:143], v[210:213], v[126:129]
	v_mfma_f32_16x16x32_bf16 v[122:125], v[172:175], v[210:213], v[122:125]
	v_mfma_f32_16x16x32_bf16 v[118:121], v[140:143], v[218:221], v[118:121]
	v_mfma_f32_16x16x32_bf16 v[114:117], v[172:175], v[218:221], v[114:117]
	v_mfma_f32_16x16x32_bf16 v[110:113], v[140:143], v[226:229], v[110:113]
	v_mfma_f32_16x16x32_bf16 v[106:109], v[172:175], v[226:229], v[106:109]
	v_mfma_f32_16x16x32_bf16 v[102:105], v[140:143], v[234:237], v[102:105]
	v_mfma_f32_16x16x32_bf16 v[98:101], v[172:175], v[234:237], v[98:101]
	v_mfma_f32_16x16x32_bf16 v[126:129], v[144:147], v[214:217], v[126:129]
	v_mfma_f32_16x16x32_bf16 v[122:125], v[190:193], v[214:217], v[122:125]
	v_mfma_f32_16x16x32_bf16 v[118:121], v[144:147], v[222:225], v[118:121]
	v_mfma_f32_16x16x32_bf16 v[114:117], v[190:193], v[222:225], v[114:117]
	v_mfma_f32_16x16x32_bf16 v[110:113], v[144:147], v[230:233], v[110:113]
	v_mfma_f32_16x16x32_bf16 v[106:109], v[190:193], v[230:233], v[106:109]
	v_mfma_f32_16x16x32_bf16 v[102:105], v[144:147], v[238:241], v[102:105]
	v_mfma_f32_16x16x32_bf16 v[98:101], v[190:193], v[238:241], v[98:101]
	s_setprio 0
	s_setprio 1
	v_mfma_f32_16x16x32_bf16 v[66:69], v[194:197], v[210:213], v[66:69]
	v_mfma_f32_16x16x32_bf16 v[58:61], v[202:205], v[210:213], v[58:61]
	v_mfma_f32_16x16x32_bf16 v[54:57], v[194:197], v[218:221], v[54:57]
	v_mfma_f32_16x16x32_bf16 v[50:53], v[202:205], v[218:221], v[50:53]
	v_mfma_f32_16x16x32_bf16 v[46:49], v[194:197], v[226:229], v[46:49]
	v_mfma_f32_16x16x32_bf16 v[42:45], v[202:205], v[226:229], v[42:45]
	v_mfma_f32_16x16x32_bf16 v[38:41], v[194:197], v[234:237], v[38:41]
	v_mfma_f32_16x16x32_bf16 v[34:37], v[202:205], v[234:237], v[34:37]
	v_mfma_f32_16x16x32_bf16 v[66:69], v[198:201], v[214:217], v[66:69]
	v_mfma_f32_16x16x32_bf16 v[58:61], v[206:209], v[214:217], v[58:61]
	v_mfma_f32_16x16x32_bf16 v[54:57], v[198:201], v[222:225], v[54:57]
	v_mfma_f32_16x16x32_bf16 v[50:53], v[206:209], v[222:225], v[50:53]
	v_mfma_f32_16x16x32_bf16 v[46:49], v[198:201], v[230:233], v[46:49]
	v_mfma_f32_16x16x32_bf16 v[42:45], v[206:209], v[230:233], v[42:45]
	v_mfma_f32_16x16x32_bf16 v[38:41], v[198:201], v[238:241], v[38:41]
	v_mfma_f32_16x16x32_bf16 v[34:37], v[206:209], v[238:241], v[34:37]
	s_setprio 0
	s_barrier
	s_add_i32 s3, s3, s26
	v_lshl_add_u64 v[162:163], v[162:163], 0, s[70:71]
	s_mov_b32 m0, s3
	ds_read_b128 v[210:213], v151 offset:49152
	ds_read_b128 v[214:217], v151 offset:50176
	ds_read_b128 v[218:221], v151 offset:51200
	ds_read_b128 v[222:225], v151 offset:52224
	ds_read_b128 v[226:229], v151 offset:53248
	ds_read_b128 v[230:233], v151 offset:54272
	ds_read_b128 v[234:237], v151 offset:55296
	ds_read_b128 v[238:241], v151 offset:56320
	global_load_lds_dwordx4 v[162:163], off
	s_add_i32 m0, s3, 0x2000
	s_add_u32 s0, s0, 0x40080
	v_lshl_add_u64 v[162:163], v[166:167], 0, s[70:71]
	s_addc_u32 s1, s1, 0
	s_add_i32 s3, s6, s26
	global_load_lds_dwordx4 v[162:163], off
	s_mov_b32 m0, s3
	s_nop 0
	global_load_lds_dwordx4 v4, s[0:1]
	s_add_i32 m0, s3, 0x2000
	s_nop 0
	global_load_lds_dwordx4 v134, s[0:1]
	v_lshl_add_u64 v[162:163], v[176:177], 0, s[70:71]
	s_mov_b32 m0, s35
	s_nop 0
	global_load_lds_dwordx4 v[162:163], off
	v_lshl_add_u64 v[162:163], v[180:181], 0, s[70:71]
	s_mov_b32 m0, s36
	s_nop 0
	global_load_lds_dwordx4 v[162:163], off
	s_waitcnt vmcnt(8)
	s_waitcnt lgkmcnt(0)
	s_barrier
	s_setprio 1
	s_waitcnt lgkmcnt(0)
	v_mfma_f32_16x16x32_bf16 v[94:97], v[140:143], v[210:213], v[94:97]
	v_mfma_f32_16x16x32_bf16 v[90:93], v[172:175], v[210:213], v[90:93]
	v_mfma_f32_16x16x32_bf16 v[86:89], v[140:143], v[218:221], v[86:89]
	v_mfma_f32_16x16x32_bf16 v[82:85], v[172:175], v[218:221], v[82:85]
	v_mfma_f32_16x16x32_bf16 v[78:81], v[140:143], v[226:229], v[78:81]
	v_mfma_f32_16x16x32_bf16 v[74:77], v[172:175], v[226:229], v[74:77]
	v_mfma_f32_16x16x32_bf16 v[70:73], v[140:143], v[234:237], v[70:73]
	v_mfma_f32_16x16x32_bf16 v[62:65], v[172:175], v[234:237], v[62:65]
	v_mfma_f32_16x16x32_bf16 v[94:97], v[144:147], v[214:217], v[94:97]
	v_mfma_f32_16x16x32_bf16 v[90:93], v[190:193], v[214:217], v[90:93]
	v_mfma_f32_16x16x32_bf16 v[86:89], v[144:147], v[222:225], v[86:89]
	v_mfma_f32_16x16x32_bf16 v[82:85], v[190:193], v[222:225], v[82:85]
	v_mfma_f32_16x16x32_bf16 v[78:81], v[144:147], v[230:233], v[78:81]
	v_mfma_f32_16x16x32_bf16 v[74:77], v[190:193], v[230:233], v[74:77]
	v_mfma_f32_16x16x32_bf16 v[70:73], v[144:147], v[238:241], v[70:73]
	v_mfma_f32_16x16x32_bf16 v[62:65], v[190:193], v[238:241], v[62:65]
	s_setprio 0
	s_setprio 1
	v_mfma_f32_16x16x32_bf16 v[30:33], v[194:197], v[210:213], v[30:33]
	v_mfma_f32_16x16x32_bf16 v[26:29], v[202:205], v[210:213], v[26:29]
	v_mfma_f32_16x16x32_bf16 v[22:25], v[194:197], v[218:221], v[22:25]
	v_mfma_f32_16x16x32_bf16 v[18:21], v[202:205], v[218:221], v[18:21]
	v_mfma_f32_16x16x32_bf16 v[14:17], v[194:197], v[226:229], v[14:17]
	v_mfma_f32_16x16x32_bf16 v[10:13], v[202:205], v[226:229], v[10:13]
	v_mfma_f32_16x16x32_bf16 v[6:9], v[194:197], v[234:237], v[6:9]
	v_mfma_f32_16x16x32_bf16 v[0:3], v[202:205], v[234:237], v[0:3]
	v_mfma_f32_16x16x32_bf16 v[30:33], v[198:201], v[214:217], v[30:33]
	v_mfma_f32_16x16x32_bf16 v[26:29], v[206:209], v[214:217], v[26:29]
	v_mfma_f32_16x16x32_bf16 v[22:25], v[198:201], v[222:225], v[22:25]
	v_mfma_f32_16x16x32_bf16 v[18:21], v[206:209], v[222:225], v[18:21]
	v_mfma_f32_16x16x32_bf16 v[14:17], v[198:201], v[230:233], v[14:17]
	v_mfma_f32_16x16x32_bf16 v[10:13], v[206:209], v[230:233], v[10:13]
	v_mfma_f32_16x16x32_bf16 v[6:9], v[198:201], v[238:241], v[6:9]
	v_mfma_f32_16x16x32_bf16 v[0:3], v[206:209], v[238:241], v[0:3]
	s_setprio 0
	s_barrier
	s_add_i32 s24, s24, 2
	s_add_u32 s22, s22, 0x100
	s_addc_u32 s23, s23, 0
	s_add_u32 s9, s9, 0x100
	s_addc_u32 s10, s10, 0
	s_cmp_gt_u32 s24, 13
	s_cbranch_scc0 .LBB0_228
	s_and_b64 vcc, exec, s[44:45]
	s_cbranch_vccz .LBB0_231
	s_barrier

.LBB0_251:
	s_ashr_i32 s47, s46, 31
	s_lshl_b64 s[2:3], s[46:47], 20
	v_readlane_b32 s4, v253, 36
	s_add_u32 s82, s4, s2
	v_readlane_b32 s2, v253, 37
	s_addc_u32 s83, s2, s3
	s_and_b64 s[2:3], s[40:41], exec
	s_cselect_b32 s2, s83, s15
	s_cselect_b32 s8, s82, s14
	s_add_u32 s22, s0, 0x80080
	s_addc_u32 s23, s1, 0
	s_add_u32 s9, s14, 0x100
	v_mov_b32_e32 v0, 0
	s_addc_u32 s10, s15, 0
	s_mov_b32 s24, -2
	v_mov_b32_e32 v1, v0
	v_mov_b32_e32 v2, v0
	v_mov_b32_e32 v3, v0
	v_mov_b32_e32 v6, v0
	v_mov_b32_e32 v7, v0
	v_mov_b32_e32 v8, v0
	v_mov_b32_e32 v9, v0
	v_mov_b32_e32 v10, v0
	v_mov_b32_e32 v11, v0
	v_mov_b32_e32 v12, v0
	v_mov_b32_e32 v13, v0
	v_mov_b32_e32 v14, v0
	v_mov_b32_e32 v15, v0
	v_mov_b32_e32 v16, v0
	v_mov_b32_e32 v17, v0
	v_mov_b32_e32 v18, v0
	v_mov_b32_e32 v19, v0
	v_mov_b32_e32 v20, v0
	v_mov_b32_e32 v21, v0
	v_mov_b32_e32 v22, v0
	v_mov_b32_e32 v23, v0
	v_mov_b32_e32 v24, v0
	v_mov_b32_e32 v25, v0
	v_mov_b32_e32 v26, v0
	v_mov_b32_e32 v27, v0
	v_mov_b32_e32 v28, v0
	v_mov_b32_e32 v29, v0
	v_mov_b32_e32 v30, v0
	v_mov_b32_e32 v31, v0
	v_mov_b32_e32 v32, v0
	v_mov_b32_e32 v33, v0
	v_mov_b32_e32 v62, v0
	v_mov_b32_e32 v63, v0
	v_mov_b32_e32 v64, v0
	v_mov_b32_e32 v65, v0
	v_mov_b32_e32 v70, v0
	v_mov_b32_e32 v71, v0
	v_mov_b32_e32 v72, v0
	v_mov_b32_e32 v73, v0
	v_mov_b32_e32 v74, v0
	v_mov_b32_e32 v75, v0
	v_mov_b32_e32 v76, v0
	v_mov_b32_e32 v77, v0
	v_mov_b32_e32 v78, v0
	v_mov_b32_e32 v79, v0
	v_mov_b32_e32 v80, v0
	v_mov_b32_e32 v81, v0
	v_mov_b32_e32 v82, v0
	v_mov_b32_e32 v83, v0
	v_mov_b32_e32 v84, v0
	v_mov_b32_e32 v85, v0
	v_mov_b32_e32 v86, v0
	v_mov_b32_e32 v87, v0
	v_mov_b32_e32 v88, v0
	v_mov_b32_e32 v89, v0
	v_mov_b32_e32 v90, v0
	v_mov_b32_e32 v91, v0
	v_mov_b32_e32 v92, v0
	v_mov_b32_e32 v93, v0
	v_mov_b32_e32 v94, v0
	v_mov_b32_e32 v95, v0
	v_mov_b32_e32 v96, v0
	v_mov_b32_e32 v97, v0
	v_mov_b32_e32 v34, v0
	v_mov_b32_e32 v35, v0
	v_mov_b32_e32 v36, v0
	v_mov_b32_e32 v37, v0
	v_mov_b32_e32 v38, v0
	v_mov_b32_e32 v39, v0
	v_mov_b32_e32 v40, v0
	v_mov_b32_e32 v41, v0
	v_mov_b32_e32 v42, v0
	v_mov_b32_e32 v43, v0
	v_mov_b32_e32 v44, v0
	v_mov_b32_e32 v45, v0
	v_mov_b32_e32 v46, v0
	v_mov_b32_e32 v47, v0
	v_mov_b32_e32 v48, v0
	v_mov_b32_e32 v49, v0
	v_mov_b32_e32 v50, v0
	v_mov_b32_e32 v51, v0
	v_mov_b32_e32 v52, v0
	v_mov_b32_e32 v53, v0
	v_mov_b32_e32 v54, v0
	v_mov_b32_e32 v55, v0
	v_mov_b32_e32 v56, v0
	v_mov_b32_e32 v57, v0
	v_mov_b32_e32 v58, v0
	v_mov_b32_e32 v59, v0
	v_mov_b32_e32 v60, v0
	v_mov_b32_e32 v61, v0
	v_mov_b32_e32 v66, v0
	v_mov_b32_e32 v67, v0
	v_mov_b32_e32 v68, v0
	v_mov_b32_e32 v69, v0
	v_mov_b32_e32 v98, v0
	v_mov_b32_e32 v99, v0
	v_mov_b32_e32 v100, v0
	v_mov_b32_e32 v101, v0
	v_mov_b32_e32 v102, v0
	v_mov_b32_e32 v103, v0
	v_mov_b32_e32 v104, v0
	v_mov_b32_e32 v105, v0
	v_mov_b32_e32 v106, v0
	v_mov_b32_e32 v107, v0
	v_mov_b32_e32 v108, v0
	v_mov_b32_e32 v109, v0
	v_mov_b32_e32 v110, v0
	v_mov_b32_e32 v111, v0
	v_mov_b32_e32 v112, v0
	v_mov_b32_e32 v113, v0
	v_mov_b32_e32 v114, v0
	v_mov_b32_e32 v115, v0
	v_mov_b32_e32 v116, v0
	v_mov_b32_e32 v117, v0
	v_mov_b32_e32 v118, v0
	v_mov_b32_e32 v119, v0
	v_mov_b32_e32 v120, v0
	v_mov_b32_e32 v121, v0
	v_mov_b32_e32 v122, v0
	v_mov_b32_e32 v123, v0
	v_mov_b32_e32 v124, v0
	v_mov_b32_e32 v125, v0
	v_mov_b32_e32 v126, v0
	v_mov_b32_e32 v127, v0
	v_mov_b32_e32 v128, v0
	v_mov_b32_e32 v129, v0
	s_cmp_eq_u32 s37, 1
	s_cbranch_scc1 .LBB0_252
	s_add_u32 s0, s22, 0xfff80080
	s_addc_u32 s1, s23, -1
	s_add_i32 s3, 0, 0x10000
	s_cmp_eq_u32 s24, 28
	s_cselect_b32 s15, s49, s1
	s_cselect_b32 s14, s48, s0
	v_add_u32_e32 v162, s3, v141
	s_cselect_b32 s1, s2, s10
	s_cselect_b32 s0, s8, s9
	s_add_i32 s6, 0, 0x14000
	ds_read_b128 v[144:147], v162
	ds_read_b128 v[148:151], v162 offset:1024
	ds_read_b128 v[172:175], v162 offset:2048
	ds_read_b128 v[190:193], v162 offset:3072
	v_add_u32_e32 v162, s6, v141
	ds_read_b128 v[194:197], v162
	ds_read_b128 v[198:201], v162 offset:1024
	ds_read_b128 v[202:205], v162 offset:2048
	ds_read_b128 v[206:209], v162 offset:3072
	s_add_i32 m0, s27, 0xc000
	ds_read_b128 v[210:213], v143
	ds_read_b128 v[214:217], v143 offset:1024
	ds_read_b128 v[218:221], v143 offset:2048
	ds_read_b128 v[222:225], v143 offset:3072
	ds_read_b128 v[226:229], v143 offset:4096
	ds_read_b128 v[230:233], v143 offset:5120
	ds_read_b128 v[234:237], v143 offset:6144
	ds_read_b128 v[238:241], v143 offset:7168
	global_load_lds_dwordx4 v136, s[22:23]
	s_add_i32 m0, s27, 0xe000
	s_nop 0
	global_load_lds_dwordx4 v138, s[22:23]
	s_waitcnt vmcnt(24)
	s_waitcnt lgkmcnt(0)
	s_barrier
	s_setprio 1
	s_waitcnt lgkmcnt(0)
	v_mfma_f32_16x16x32_bf16 v[126:129], v[144:147], v[210:213], v[126:129]
	v_mfma_f32_16x16x32_bf16 v[122:125], v[172:175], v[210:213], v[122:125]
	v_mfma_f32_16x16x32_bf16 v[118:121], v[144:147], v[218:221], v[118:121]
	v_mfma_f32_16x16x32_bf16 v[114:117], v[172:175], v[218:221], v[114:117]
	v_mfma_f32_16x16x32_bf16 v[110:113], v[144:147], v[226:229], v[110:113]
	v_mfma_f32_16x16x32_bf16 v[106:109], v[172:175], v[226:229], v[106:109]
	v_mfma_f32_16x16x32_bf16 v[102:105], v[144:147], v[234:237], v[102:105]
	v_mfma_f32_16x16x32_bf16 v[98:101], v[172:175], v[234:237], v[98:101]
	v_mfma_f32_16x16x32_bf16 v[126:129], v[148:151], v[214:217], v[126:129]
	v_mfma_f32_16x16x32_bf16 v[122:125], v[190:193], v[214:217], v[122:125]
	v_mfma_f32_16x16x32_bf16 v[118:121], v[148:151], v[222:225], v[118:121]
	v_mfma_f32_16x16x32_bf16 v[114:117], v[190:193], v[222:225], v[114:117]
	v_mfma_f32_16x16x32_bf16 v[110:113], v[148:151], v[230:233], v[110:113]
	v_mfma_f32_16x16x32_bf16 v[106:109], v[190:193], v[230:233], v[106:109]
	v_mfma_f32_16x16x32_bf16 v[102:105], v[148:151], v[238:241], v[102:105]
	v_mfma_f32_16x16x32_bf16 v[98:101], v[190:193], v[238:241], v[98:101]
	s_setprio 0
	s_setprio 1
	v_mfma_f32_16x16x32_bf16 v[66:69], v[194:197], v[210:213], v[66:69]
	v_mfma_f32_16x16x32_bf16 v[58:61], v[202:205], v[210:213], v[58:61]
	v_mfma_f32_16x16x32_bf16 v[54:57], v[194:197], v[218:221], v[54:57]
	v_mfma_f32_16x16x32_bf16 v[50:53], v[202:205], v[218:221], v[50:53]
	v_mfma_f32_16x16x32_bf16 v[46:49], v[194:197], v[226:229], v[46:49]
	v_mfma_f32_16x16x32_bf16 v[42:45], v[202:205], v[226:229], v[42:45]
	v_mfma_f32_16x16x32_bf16 v[38:41], v[194:197], v[234:237], v[38:41]
	v_mfma_f32_16x16x32_bf16 v[34:37], v[202:205], v[234:237], v[34:37]
	v_mfma_f32_16x16x32_bf16 v[66:69], v[198:201], v[214:217], v[66:69]
	v_mfma_f32_16x16x32_bf16 v[58:61], v[206:209], v[214:217], v[58:61]
	v_mfma_f32_16x16x32_bf16 v[54:57], v[198:201], v[222:225], v[54:57]
	v_mfma_f32_16x16x32_bf16 v[50:53], v[206:209], v[222:225], v[50:53]
	v_mfma_f32_16x16x32_bf16 v[46:49], v[198:201], v[230:233], v[46:49]
	v_mfma_f32_16x16x32_bf16 v[42:45], v[206:209], v[230:233], v[42:45]
	v_mfma_f32_16x16x32_bf16 v[38:41], v[198:201], v[238:241], v[38:41]
	v_mfma_f32_16x16x32_bf16 v[34:37], v[206:209], v[238:241], v[34:37]
	s_setprio 0
	s_barrier
	s_add_i32 s3, s3, s26
	v_lshl_add_u64 v[162:163], s[0:1], 0, v[4:5]
	s_mov_b32 m0, s3
	ds_read_b128 v[210:213], v143 offset:16384
	ds_read_b128 v[214:217], v143 offset:17408
	ds_read_b128 v[218:221], v143 offset:18432
	ds_read_b128 v[222:225], v143 offset:19456
	ds_read_b128 v[226:229], v143 offset:20480
	ds_read_b128 v[230:233], v143 offset:21504
	ds_read_b128 v[234:237], v143 offset:22528
	ds_read_b128 v[238:241], v143 offset:23552
	global_load_lds_dwordx4 v4, s[0:1]
	s_add_i32 m0, s3, 0x2000
	s_add_u32 s4, s0, 0x80000
	v_lshl_add_u64 v[166:167], s[0:1], 0, v[130:131]
	s_addc_u32 s5, s1, 0
	s_add_i32 s3, s6, s26
	global_load_lds_dwordx4 v130, s[0:1]
	s_mov_b32 m0, s3
	v_lshl_add_u64 v[242:243], s[14:15], 0, v[132:133]
	global_load_lds_dwordx4 v4, s[4:5]
	s_add_i32 m0, s3, 0x2000
	s_nop 0
	global_load_lds_dwordx4 v130, s[4:5]
	v_lshl_add_u64 v[176:177], s[14:15], 0, v[134:135]
	s_mov_b32 m0, s27
	s_nop 0
	global_load_lds_dwordx4 v134, s[14:15]
	s_mov_b32 m0, s30
	s_nop 0
	global_load_lds_dwordx4 v132, s[14:15]
	s_waitcnt vmcnt(24)
	s_waitcnt lgkmcnt(0)
	s_barrier
	s_setprio 1
	s_waitcnt lgkmcnt(0)
	v_mfma_f32_16x16x32_bf16 v[94:97], v[144:147], v[210:213], v[94:97]
	v_mfma_f32_16x16x32_bf16 v[90:93], v[172:175], v[210:213], v[90:93]
	v_mfma_f32_16x16x32_bf16 v[86:89], v[144:147], v[218:221], v[86:89]
	v_mfma_f32_16x16x32_bf16 v[82:85], v[172:175], v[218:221], v[82:85]
	v_mfma_f32_16x16x32_bf16 v[78:81], v[144:147], v[226:229], v[78:81]
	v_mfma_f32_16x16x32_bf16 v[74:77], v[172:175], v[226:229], v[74:77]
	v_mfma_f32_16x16x32_bf16 v[70:73], v[144:147], v[234:237], v[70:73]
	v_mfma_f32_16x16x32_bf16 v[62:65], v[172:175], v[234:237], v[62:65]
	v_mfma_f32_16x16x32_bf16 v[94:97], v[148:151], v[214:217], v[94:97]
	v_mfma_f32_16x16x32_bf16 v[90:93], v[190:193], v[214:217], v[90:93]
	v_mfma_f32_16x16x32_bf16 v[86:89], v[148:151], v[222:225], v[86:89]
	v_mfma_f32_16x16x32_bf16 v[82:85], v[190:193], v[222:225], v[82:85]
	v_mfma_f32_16x16x32_bf16 v[78:81], v[148:151], v[230:233], v[78:81]
	v_mfma_f32_16x16x32_bf16 v[74:77], v[190:193], v[230:233], v[74:77]
	v_mfma_f32_16x16x32_bf16 v[70:73], v[148:151], v[238:241], v[70:73]
	v_mfma_f32_16x16x32_bf16 v[62:65], v[190:193], v[238:241], v[62:65]
	s_setprio 0
	s_setprio 1
	v_mfma_f32_16x16x32_bf16 v[30:33], v[194:197], v[210:213], v[30:33]
	v_mfma_f32_16x16x32_bf16 v[26:29], v[202:205], v[210:213], v[26:29]
	v_mfma_f32_16x16x32_bf16 v[22:25], v[194:197], v[218:221], v[22:25]
	v_mfma_f32_16x16x32_bf16 v[18:21], v[202:205], v[218:221], v[18:21]
	v_mfma_f32_16x16x32_bf16 v[14:17], v[194:197], v[226:229], v[14:17]
	v_mfma_f32_16x16x32_bf16 v[10:13], v[202:205], v[226:229], v[10:13]
	v_mfma_f32_16x16x32_bf16 v[6:9], v[194:197], v[234:237], v[6:9]
	v_mfma_f32_16x16x32_bf16 v[0:3], v[202:205], v[234:237], v[0:3]
	v_mfma_f32_16x16x32_bf16 v[30:33], v[198:201], v[214:217], v[30:33]
	v_mfma_f32_16x16x32_bf16 v[26:29], v[206:209], v[214:217], v[26:29]
	v_mfma_f32_16x16x32_bf16 v[22:25], v[198:201], v[222:225], v[22:25]
	v_mfma_f32_16x16x32_bf16 v[18:21], v[206:209], v[222:225], v[18:21]
	v_mfma_f32_16x16x32_bf16 v[14:17], v[198:201], v[230:233], v[14:17]
	v_mfma_f32_16x16x32_bf16 v[10:13], v[206:209], v[230:233], v[10:13]
	v_mfma_f32_16x16x32_bf16 v[6:9], v[198:201], v[238:241], v[6:9]
	v_mfma_f32_16x16x32_bf16 v[0:3], v[206:209], v[238:241], v[0:3]
	s_setprio 0
	s_barrier
	s_branch .Lpeelmid_252
.LBB0_252:
	s_add_u32 s0, s22, 0xfff80080
	s_addc_u32 s1, s23, -1
	s_add_i32 s3, 0, 0x10000
	s_cmp_eq_u32 s24, 28
	s_cselect_b32 s15, s49, s1
	s_cselect_b32 s14, s48, s0
	v_add_u32_e32 v162, s3, v141
	s_cselect_b32 s1, s2, s10
	s_cselect_b32 s0, s8, s9
	s_add_i32 s6, 0, 0x14000
	ds_read_b128 v[144:147], v162
	ds_read_b128 v[148:151], v162 offset:1024
	ds_read_b128 v[172:175], v162 offset:2048
	ds_read_b128 v[190:193], v162 offset:3072
	v_add_u32_e32 v162, s6, v141
	ds_read_b128 v[194:197], v162
	ds_read_b128 v[198:201], v162 offset:1024
	ds_read_b128 v[202:205], v162 offset:2048
	ds_read_b128 v[206:209], v162 offset:3072
	s_add_i32 m0, s27, 0xc000
	ds_read_b128 v[210:213], v143
	ds_read_b128 v[214:217], v143 offset:1024
	ds_read_b128 v[218:221], v143 offset:2048
	ds_read_b128 v[222:225], v143 offset:3072
	ds_read_b128 v[226:229], v143 offset:4096
	ds_read_b128 v[230:233], v143 offset:5120
	ds_read_b128 v[234:237], v143 offset:6144
	ds_read_b128 v[238:241], v143 offset:7168
	global_load_lds_dwordx4 v136, s[22:23]
	s_add_i32 m0, s27, 0xe000
	s_nop 0
	global_load_lds_dwordx4 v138, s[22:23]
	s_waitcnt vmcnt(8)
	s_waitcnt lgkmcnt(0)
	s_barrier
	s_setprio 1
	s_waitcnt lgkmcnt(0)
	v_mfma_f32_16x16x32_bf16 v[126:129], v[144:147], v[210:213], v[126:129]
	v_mfma_f32_16x16x32_bf16 v[122:125], v[172:175], v[210:213], v[122:125]
	v_mfma_f32_16x16x32_bf16 v[118:121], v[144:147], v[218:221], v[118:121]
	v_mfma_f32_16x16x32_bf16 v[114:117], v[172:175], v[218:221], v[114:117]
	v_mfma_f32_16x16x32_bf16 v[110:113], v[144:147], v[226:229], v[110:113]
	v_mfma_f32_16x16x32_bf16 v[106:109], v[172:175], v[226:229], v[106:109]
	v_mfma_f32_16x16x32_bf16 v[102:105], v[144:147], v[234:237], v[102:105]
	v_mfma_f32_16x16x32_bf16 v[98:101], v[172:175], v[234:237], v[98:101]
	v_mfma_f32_16x16x32_bf16 v[126:129], v[148:151], v[214:217], v[126:129]
	v_mfma_f32_16x16x32_bf16 v[122:125], v[190:193], v[214:217], v[122:125]
	v_mfma_f32_16x16x32_bf16 v[118:121], v[148:151], v[222:225], v[118:121]
	v_mfma_f32_16x16x32_bf16 v[114:117], v[190:193], v[222:225], v[114:117]
	v_mfma_f32_16x16x32_bf16 v[110:113], v[148:151], v[230:233], v[110:113]
	v_mfma_f32_16x16x32_bf16 v[106:109], v[190:193], v[230:233], v[106:109]
	v_mfma_f32_16x16x32_bf16 v[102:105], v[148:151], v[238:241], v[102:105]
	v_mfma_f32_16x16x32_bf16 v[98:101], v[190:193], v[238:241], v[98:101]
	s_setprio 0
	s_setprio 1
	v_mfma_f32_16x16x32_bf16 v[66:69], v[194:197], v[210:213], v[66:69]
	v_mfma_f32_16x16x32_bf16 v[58:61], v[202:205], v[210:213], v[58:61]
	v_mfma_f32_16x16x32_bf16 v[54:57], v[194:197], v[218:221], v[54:57]
	v_mfma_f32_16x16x32_bf16 v[50:53], v[202:205], v[218:221], v[50:53]
	v_mfma_f32_16x16x32_bf16 v[46:49], v[194:197], v[226:229], v[46:49]
	v_mfma_f32_16x16x32_bf16 v[42:45], v[202:205], v[226:229], v[42:45]
	v_mfma_f32_16x16x32_bf16 v[38:41], v[194:197], v[234:237], v[38:41]
	v_mfma_f32_16x16x32_bf16 v[34:37], v[202:205], v[234:237], v[34:37]
	v_mfma_f32_16x16x32_bf16 v[66:69], v[198:201], v[214:217], v[66:69]
	v_mfma_f32_16x16x32_bf16 v[58:61], v[206:209], v[214:217], v[58:61]
	v_mfma_f32_16x16x32_bf16 v[54:57], v[198:201], v[222:225], v[54:57]
	v_mfma_f32_16x16x32_bf16 v[50:53], v[206:209], v[222:225], v[50:53]
	v_mfma_f32_16x16x32_bf16 v[46:49], v[198:201], v[230:233], v[46:49]
	v_mfma_f32_16x16x32_bf16 v[42:45], v[206:209], v[230:233], v[42:45]
	v_mfma_f32_16x16x32_bf16 v[38:41], v[198:201], v[238:241], v[38:41]
	v_mfma_f32_16x16x32_bf16 v[34:37], v[206:209], v[238:241], v[34:37]
	s_setprio 0
	s_barrier
	s_add_i32 s3, s3, s26
	v_lshl_add_u64 v[162:163], s[0:1], 0, v[4:5]
	s_mov_b32 m0, s3
	ds_read_b128 v[210:213], v143 offset:16384
	ds_read_b128 v[214:217], v143 offset:17408
	ds_read_b128 v[218:221], v143 offset:18432
	ds_read_b128 v[222:225], v143 offset:19456
	ds_read_b128 v[226:229], v143 offset:20480
	ds_read_b128 v[230:233], v143 offset:21504
	ds_read_b128 v[234:237], v143 offset:22528
	ds_read_b128 v[238:241], v143 offset:23552
	global_load_lds_dwordx4 v4, s[0:1]
	s_add_i32 m0, s3, 0x2000
	s_add_u32 s4, s0, 0x80000
	v_lshl_add_u64 v[166:167], s[0:1], 0, v[130:131]
	s_addc_u32 s5, s1, 0
	s_add_i32 s3, s6, s26
	global_load_lds_dwordx4 v130, s[0:1]
	s_mov_b32 m0, s3
	v_lshl_add_u64 v[242:243], s[14:15], 0, v[132:133]
	global_load_lds_dwordx4 v4, s[4:5]
	s_add_i32 m0, s3, 0x2000
	s_nop 0
	global_load_lds_dwordx4 v130, s[4:5]
	v_lshl_add_u64 v[176:177], s[14:15], 0, v[134:135]
	s_mov_b32 m0, s27
	s_nop 0
	global_load_lds_dwordx4 v134, s[14:15]
	s_mov_b32 m0, s30
	s_nop 0
	global_load_lds_dwordx4 v132, s[14:15]
	s_waitcnt vmcnt(8)
	s_waitcnt lgkmcnt(0)
	s_barrier
	s_setprio 1
	s_waitcnt lgkmcnt(0)
	v_mfma_f32_16x16x32_bf16 v[94:97], v[144:147], v[210:213], v[94:97]
	v_mfma_f32_16x16x32_bf16 v[90:93], v[172:175], v[210:213], v[90:93]
	v_mfma_f32_16x16x32_bf16 v[86:89], v[144:147], v[218:221], v[86:89]
	v_mfma_f32_16x16x32_bf16 v[82:85], v[172:175], v[218:221], v[82:85]
	v_mfma_f32_16x16x32_bf16 v[78:81], v[144:147], v[226:229], v[78:81]
	v_mfma_f32_16x16x32_bf16 v[74:77], v[172:175], v[226:229], v[74:77]
	v_mfma_f32_16x16x32_bf16 v[70:73], v[144:147], v[234:237], v[70:73]
	v_mfma_f32_16x16x32_bf16 v[62:65], v[172:175], v[234:237], v[62:65]
	v_mfma_f32_16x16x32_bf16 v[94:97], v[148:151], v[214:217], v[94:97]
	v_mfma_f32_16x16x32_bf16 v[90:93], v[190:193], v[214:217], v[90:93]
	v_mfma_f32_16x16x32_bf16 v[86:89], v[148:151], v[222:225], v[86:89]
	v_mfma_f32_16x16x32_bf16 v[82:85], v[190:193], v[222:225], v[82:85]
	v_mfma_f32_16x16x32_bf16 v[78:81], v[148:151], v[230:233], v[78:81]
	v_mfma_f32_16x16x32_bf16 v[74:77], v[190:193], v[230:233], v[74:77]
	v_mfma_f32_16x16x32_bf16 v[70:73], v[148:151], v[238:241], v[70:73]
	v_mfma_f32_16x16x32_bf16 v[62:65], v[190:193], v[238:241], v[62:65]
	s_setprio 0
	s_setprio 1
	v_mfma_f32_16x16x32_bf16 v[30:33], v[194:197], v[210:213], v[30:33]
	v_mfma_f32_16x16x32_bf16 v[26:29], v[202:205], v[210:213], v[26:29]
	v_mfma_f32_16x16x32_bf16 v[22:25], v[194:197], v[218:221], v[22:25]
	v_mfma_f32_16x16x32_bf16 v[18:21], v[202:205], v[218:221], v[18:21]
	v_mfma_f32_16x16x32_bf16 v[14:17], v[194:197], v[226:229], v[14:17]
	v_mfma_f32_16x16x32_bf16 v[10:13], v[202:205], v[226:229], v[10:13]
	v_mfma_f32_16x16x32_bf16 v[6:9], v[194:197], v[234:237], v[6:9]
	v_mfma_f32_16x16x32_bf16 v[0:3], v[202:205], v[234:237], v[0:3]
	v_mfma_f32_16x16x32_bf16 v[30:33], v[198:201], v[214:217], v[30:33]
	v_mfma_f32_16x16x32_bf16 v[26:29], v[206:209], v[214:217], v[26:29]
	v_mfma_f32_16x16x32_bf16 v[22:25], v[198:201], v[222:225], v[22:25]
	v_mfma_f32_16x16x32_bf16 v[18:21], v[206:209], v[222:225], v[18:21]
	v_mfma_f32_16x16x32_bf16 v[14:17], v[198:201], v[230:233], v[14:17]
	v_mfma_f32_16x16x32_bf16 v[10:13], v[206:209], v[230:233], v[10:13]
	v_mfma_f32_16x16x32_bf16 v[6:9], v[198:201], v[238:241], v[6:9]
	v_mfma_f32_16x16x32_bf16 v[0:3], v[206:209], v[238:241], v[0:3]
	s_setprio 0
	s_barrier
.Lpeelmid_252:
	s_add_i32 s3, 0, 0x18000
	v_add_u32_e32 v164, s3, v141
	s_add_i32 s6, 0, 0x1c000
	ds_read_b128 v[144:147], v164
	ds_read_b128 v[148:151], v164 offset:1024
	ds_read_b128 v[172:175], v164 offset:2048
	ds_read_b128 v[190:193], v164 offset:3072
	v_add_u32_e32 v164, s6, v141
	ds_read_b128 v[194:197], v164
	ds_read_b128 v[198:201], v164 offset:1024
	ds_read_b128 v[202:205], v164 offset:2048
	ds_read_b128 v[206:209], v164 offset:3072
	s_add_u32 s4, s14, 0x80000
	s_addc_u32 s5, s15, 0
	s_mov_b32 m0, s31
	ds_read_b128 v[210:213], v143 offset:32768
	ds_read_b128 v[214:217], v143 offset:33792
	ds_read_b128 v[218:221], v143 offset:34816
	ds_read_b128 v[222:225], v143 offset:35840
	ds_read_b128 v[226:229], v143 offset:36864
	ds_read_b128 v[230:233], v143 offset:37888
	ds_read_b128 v[234:237], v143 offset:38912
	ds_read_b128 v[238:241], v143 offset:39936
	global_load_lds_dwordx4 v134, s[4:5]
	v_lshl_add_u64 v[244:245], s[4:5], 0, v[132:133]
	s_mov_b32 m0, s34
	s_nop 0
	global_load_lds_dwordx4 v132, s[4:5]
	s_waitcnt vmcnt(8)
	s_waitcnt lgkmcnt(0)
	s_barrier
	s_setprio 1
	s_waitcnt lgkmcnt(0)
	v_mfma_f32_16x16x32_bf16 v[126:129], v[144:147], v[210:213], v[126:129]
	v_mfma_f32_16x16x32_bf16 v[122:125], v[172:175], v[210:213], v[122:125]
	v_mfma_f32_16x16x32_bf16 v[118:121], v[144:147], v[218:221], v[118:121]
	v_mfma_f32_16x16x32_bf16 v[114:117], v[172:175], v[218:221], v[114:117]
	v_mfma_f32_16x16x32_bf16 v[110:113], v[144:147], v[226:229], v[110:113]
	v_mfma_f32_16x16x32_bf16 v[106:109], v[172:175], v[226:229], v[106:109]
	v_mfma_f32_16x16x32_bf16 v[102:105], v[144:147], v[234:237], v[102:105]
	v_mfma_f32_16x16x32_bf16 v[98:101], v[172:175], v[234:237], v[98:101]
	v_mfma_f32_16x16x32_bf16 v[126:129], v[148:151], v[214:217], v[126:129]
	v_mfma_f32_16x16x32_bf16 v[122:125], v[190:193], v[214:217], v[122:125]
	v_mfma_f32_16x16x32_bf16 v[118:121], v[148:151], v[222:225], v[118:121]
	v_mfma_f32_16x16x32_bf16 v[114:117], v[190:193], v[222:225], v[114:117]
	v_mfma_f32_16x16x32_bf16 v[110:113], v[148:151], v[230:233], v[110:113]
	v_mfma_f32_16x16x32_bf16 v[106:109], v[190:193], v[230:233], v[106:109]
	v_mfma_f32_16x16x32_bf16 v[102:105], v[148:151], v[238:241], v[102:105]
	v_mfma_f32_16x16x32_bf16 v[98:101], v[190:193], v[238:241], v[98:101]
	s_setprio 0
	s_setprio 1
	v_mfma_f32_16x16x32_bf16 v[66:69], v[194:197], v[210:213], v[66:69]
	v_mfma_f32_16x16x32_bf16 v[58:61], v[202:205], v[210:213], v[58:61]
	v_mfma_f32_16x16x32_bf16 v[54:57], v[194:197], v[218:221], v[54:57]
	v_mfma_f32_16x16x32_bf16 v[50:53], v[202:205], v[218:221], v[50:53]
	v_mfma_f32_16x16x32_bf16 v[46:49], v[194:197], v[226:229], v[46:49]
	v_mfma_f32_16x16x32_bf16 v[42:45], v[202:205], v[226:229], v[42:45]
	v_mfma_f32_16x16x32_bf16 v[38:41], v[194:197], v[234:237], v[38:41]
	v_mfma_f32_16x16x32_bf16 v[34:37], v[202:205], v[234:237], v[34:37]
	v_mfma_f32_16x16x32_bf16 v[66:69], v[198:201], v[214:217], v[66:69]
	v_mfma_f32_16x16x32_bf16 v[58:61], v[206:209], v[214:217], v[58:61]
	v_mfma_f32_16x16x32_bf16 v[54:57], v[198:201], v[222:225], v[54:57]
	v_mfma_f32_16x16x32_bf16 v[50:53], v[206:209], v[222:225], v[50:53]
	v_mfma_f32_16x16x32_bf16 v[46:49], v[198:201], v[230:233], v[46:49]
	v_mfma_f32_16x16x32_bf16 v[42:45], v[206:209], v[230:233], v[42:45]
	v_mfma_f32_16x16x32_bf16 v[38:41], v[198:201], v[238:241], v[38:41]
	v_mfma_f32_16x16x32_bf16 v[34:37], v[206:209], v[238:241], v[34:37]
	s_setprio 0
	s_barrier
	s_add_i32 s3, s3, s26
	v_lshl_add_u64 v[162:163], v[162:163], 0, s[70:71]
	s_mov_b32 m0, s3
	ds_read_b128 v[210:213], v143 offset:49152
	ds_read_b128 v[214:217], v143 offset:50176
	ds_read_b128 v[218:221], v143 offset:51200
	ds_read_b128 v[222:225], v143 offset:52224
	ds_read_b128 v[226:229], v143 offset:53248
	ds_read_b128 v[230:233], v143 offset:54272
	ds_read_b128 v[234:237], v143 offset:55296
	ds_read_b128 v[238:241], v143 offset:56320
	global_load_lds_dwordx4 v[162:163], off
	s_add_i32 m0, s3, 0x2000
	s_add_u32 s0, s0, 0x80080
	v_lshl_add_u64 v[162:163], v[166:167], 0, s[70:71]
	s_addc_u32 s1, s1, 0
	s_add_i32 s3, s6, s26
	global_load_lds_dwordx4 v[162:163], off
	s_mov_b32 m0, s3
	s_nop 0
	global_load_lds_dwordx4 v4, s[0:1]
	s_add_i32 m0, s3, 0x2000
	s_nop 0
	global_load_lds_dwordx4 v130, s[0:1]
	v_lshl_add_u64 v[162:163], v[176:177], 0, s[70:71]
	s_mov_b32 m0, s35
	s_nop 0
	global_load_lds_dwordx4 v[162:163], off
	v_lshl_add_u64 v[162:163], v[242:243], 0, s[70:71]
	s_mov_b32 m0, s36
	s_nop 0
	global_load_lds_dwordx4 v[162:163], off
	s_waitcnt vmcnt(8)
	s_waitcnt lgkmcnt(0)
	s_barrier
	s_setprio 1
	s_waitcnt lgkmcnt(0)
	v_mfma_f32_16x16x32_bf16 v[94:97], v[144:147], v[210:213], v[94:97]
	v_mfma_f32_16x16x32_bf16 v[90:93], v[172:175], v[210:213], v[90:93]
	v_mfma_f32_16x16x32_bf16 v[86:89], v[144:147], v[218:221], v[86:89]
	v_mfma_f32_16x16x32_bf16 v[82:85], v[172:175], v[218:221], v[82:85]
	v_mfma_f32_16x16x32_bf16 v[78:81], v[144:147], v[226:229], v[78:81]
	v_mfma_f32_16x16x32_bf16 v[74:77], v[172:175], v[226:229], v[74:77]
	v_mfma_f32_16x16x32_bf16 v[70:73], v[144:147], v[234:237], v[70:73]
	v_mfma_f32_16x16x32_bf16 v[62:65], v[172:175], v[234:237], v[62:65]
	v_mfma_f32_16x16x32_bf16 v[94:97], v[148:151], v[214:217], v[94:97]
	v_mfma_f32_16x16x32_bf16 v[90:93], v[190:193], v[214:217], v[90:93]
	v_mfma_f32_16x16x32_bf16 v[86:89], v[148:151], v[222:225], v[86:89]
	v_mfma_f32_16x16x32_bf16 v[82:85], v[190:193], v[222:225], v[82:85]
	v_mfma_f32_16x16x32_bf16 v[78:81], v[148:151], v[230:233], v[78:81]
	v_mfma_f32_16x16x32_bf16 v[74:77], v[190:193], v[230:233], v[74:77]
	v_mfma_f32_16x16x32_bf16 v[70:73], v[148:151], v[238:241], v[70:73]
	v_mfma_f32_16x16x32_bf16 v[62:65], v[190:193], v[238:241], v[62:65]
	s_setprio 0
	s_setprio 1
	v_mfma_f32_16x16x32_bf16 v[30:33], v[194:197], v[210:213], v[30:33]
	v_mfma_f32_16x16x32_bf16 v[26:29], v[202:205], v[210:213], v[26:29]
	v_mfma_f32_16x16x32_bf16 v[22:25], v[194:197], v[218:221], v[22:25]
	v_mfma_f32_16x16x32_bf16 v[18:21], v[202:205], v[218:221], v[18:21]
	v_mfma_f32_16x16x32_bf16 v[14:17], v[194:197], v[226:229], v[14:17]
	v_mfma_f32_16x16x32_bf16 v[10:13], v[202:205], v[226:229], v[10:13]
	v_mfma_f32_16x16x32_bf16 v[6:9], v[194:197], v[234:237], v[6:9]
	v_mfma_f32_16x16x32_bf16 v[0:3], v[202:205], v[234:237], v[0:3]
	v_mfma_f32_16x16x32_bf16 v[30:33], v[198:201], v[214:217], v[30:33]
	v_mfma_f32_16x16x32_bf16 v[26:29], v[206:209], v[214:217], v[26:29]
	v_mfma_f32_16x16x32_bf16 v[22:25], v[198:201], v[222:225], v[22:25]
	v_mfma_f32_16x16x32_bf16 v[18:21], v[206:209], v[222:225], v[18:21]
	v_mfma_f32_16x16x32_bf16 v[14:17], v[198:201], v[230:233], v[14:17]
	v_mfma_f32_16x16x32_bf16 v[10:13], v[206:209], v[230:233], v[10:13]
	v_mfma_f32_16x16x32_bf16 v[6:9], v[198:201], v[238:241], v[6:9]
	v_mfma_f32_16x16x32_bf16 v[0:3], v[206:209], v[238:241], v[0:3]
	s_setprio 0
	s_barrier
	s_add_i32 s24, s24, 2
	s_add_u32 s22, s22, 0x100
	s_addc_u32 s23, s23, 0
	s_add_u32 s9, s9, 0x100
	s_addc_u32 s10, s10, 0
	s_cmp_gt_u32 s24, 29
	s_cbranch_scc0 .LBB0_252
	s_and_b64 vcc, exec, s[44:45]
	s_cbranch_vccz .LBB0_255
	s_barrier

.LBB0_851:
	s_ashr_i32 s3, s37, 24
	s_lshl_b32 s2, s37, 8
	s_andn2_b32 s3, s3, 63
	s_add_i32 s2, s3, s2
	s_ashr_i32 s3, s2, 31
	s_lshl_b64 s[2:3], s[2:3], 12
	v_readlane_b32 s4, v252, 6
	v_readlane_b32 s5, v252, 7
	s_add_u32 s76, s4, s2
	s_addc_u32 s77, s5, s3
	s_and_b64 s[2:3], s[38:39], exec
	s_cselect_b32 s2, s77, s15
	s_cselect_b32 s8, s76, s14
	s_ashr_i32 s59, s58, 31
	s_lshl_b64 s[4:5], s[58:59], 20
	v_readlane_b32 s6, v252, 4
	v_readlane_b32 s7, v252, 5
	s_add_u32 s78, s6, s4
	s_addc_u32 s79, s7, s5
	s_and_b64 s[4:5], s[38:39], exec
	s_cselect_b32 s10, s79, s1
	s_cselect_b32 s24, s78, s0
	s_add_u32 s22, s14, 0x80080
	s_addc_u32 s23, s15, 0
	s_add_u32 s9, s0, 0x100
	v_mov_b32_e32 v0, 0
	s_addc_u32 s25, s1, 0
	s_mov_b32 s28, -2
	v_mov_b32_e32 v1, v0
	v_mov_b32_e32 v2, v0
	v_mov_b32_e32 v3, v0
	v_mov_b32_e32 v6, v0
	v_mov_b32_e32 v7, v0
	v_mov_b32_e32 v8, v0
	v_mov_b32_e32 v9, v0
	v_mov_b32_e32 v10, v0
	v_mov_b32_e32 v11, v0
	v_mov_b32_e32 v12, v0
	v_mov_b32_e32 v13, v0
	v_mov_b32_e32 v14, v0
	v_mov_b32_e32 v15, v0
	v_mov_b32_e32 v16, v0
	v_mov_b32_e32 v17, v0
	v_mov_b32_e32 v18, v0
	v_mov_b32_e32 v19, v0
	v_mov_b32_e32 v20, v0
	v_mov_b32_e32 v21, v0
	v_mov_b32_e32 v22, v0
	v_mov_b32_e32 v23, v0
	v_mov_b32_e32 v24, v0
	v_mov_b32_e32 v25, v0
	v_mov_b32_e32 v26, v0
	v_mov_b32_e32 v27, v0
	v_mov_b32_e32 v28, v0
	v_mov_b32_e32 v29, v0
	v_mov_b32_e32 v30, v0
	v_mov_b32_e32 v31, v0
	v_mov_b32_e32 v32, v0
	v_mov_b32_e32 v33, v0
	v_mov_b32_e32 v66, v0
	v_mov_b32_e32 v67, v0
	v_mov_b32_e32 v68, v0
	v_mov_b32_e32 v69, v0
	v_mov_b32_e32 v70, v0
	v_mov_b32_e32 v71, v0
	v_mov_b32_e32 v72, v0
	v_mov_b32_e32 v73, v0
	v_mov_b32_e32 v74, v0
	v_mov_b32_e32 v75, v0
	v_mov_b32_e32 v76, v0
	v_mov_b32_e32 v77, v0
	v_mov_b32_e32 v78, v0
	v_mov_b32_e32 v79, v0
	v_mov_b32_e32 v80, v0
	v_mov_b32_e32 v81, v0
	v_mov_b32_e32 v82, v0
	v_mov_b32_e32 v83, v0
	v_mov_b32_e32 v84, v0
	v_mov_b32_e32 v85, v0
	v_mov_b32_e32 v86, v0
	v_mov_b32_e32 v87, v0
	v_mov_b32_e32 v88, v0
	v_mov_b32_e32 v89, v0
	v_mov_b32_e32 v90, v0
	v_mov_b32_e32 v91, v0
	v_mov_b32_e32 v92, v0
	v_mov_b32_e32 v93, v0
	v_mov_b32_e32 v94, v0
	v_mov_b32_e32 v95, v0
	v_mov_b32_e32 v96, v0
	v_mov_b32_e32 v97, v0
	v_mov_b32_e32 v34, v0
	v_mov_b32_e32 v35, v0
	v_mov_b32_e32 v36, v0
	v_mov_b32_e32 v37, v0
	v_mov_b32_e32 v38, v0
	v_mov_b32_e32 v39, v0
	v_mov_b32_e32 v40, v0
	v_mov_b32_e32 v41, v0
	v_mov_b32_e32 v42, v0
	v_mov_b32_e32 v43, v0
	v_mov_b32_e32 v44, v0
	v_mov_b32_e32 v45, v0
	v_mov_b32_e32 v46, v0
	v_mov_b32_e32 v47, v0
	v_mov_b32_e32 v48, v0
	v_mov_b32_e32 v49, v0
	v_mov_b32_e32 v50, v0
	v_mov_b32_e32 v51, v0
	v_mov_b32_e32 v52, v0
	v_mov_b32_e32 v53, v0
	v_mov_b32_e32 v54, v0
	v_mov_b32_e32 v55, v0
	v_mov_b32_e32 v56, v0
	v_mov_b32_e32 v57, v0
	v_mov_b32_e32 v58, v0
	v_mov_b32_e32 v59, v0
	v_mov_b32_e32 v60, v0
	v_mov_b32_e32 v61, v0
	v_mov_b32_e32 v62, v0
	v_mov_b32_e32 v63, v0
	v_mov_b32_e32 v64, v0
	v_mov_b32_e32 v65, v0
	v_mov_b32_e32 v98, v0
	v_mov_b32_e32 v99, v0
	v_mov_b32_e32 v100, v0
	v_mov_b32_e32 v101, v0
	v_mov_b32_e32 v102, v0
	v_mov_b32_e32 v103, v0
	v_mov_b32_e32 v104, v0
	v_mov_b32_e32 v105, v0
	v_mov_b32_e32 v106, v0
	v_mov_b32_e32 v107, v0
	v_mov_b32_e32 v108, v0
	v_mov_b32_e32 v109, v0
	v_mov_b32_e32 v110, v0
	v_mov_b32_e32 v111, v0
	v_mov_b32_e32 v112, v0
	v_mov_b32_e32 v113, v0
	v_mov_b32_e32 v114, v0
	v_mov_b32_e32 v115, v0
	v_mov_b32_e32 v116, v0
	v_mov_b32_e32 v117, v0
	v_mov_b32_e32 v118, v0
	v_mov_b32_e32 v119, v0
	v_mov_b32_e32 v120, v0
	v_mov_b32_e32 v121, v0
	v_mov_b32_e32 v122, v0
	v_mov_b32_e32 v123, v0
	v_mov_b32_e32 v124, v0
	v_mov_b32_e32 v125, v0
	v_mov_b32_e32 v126, v0
	v_mov_b32_e32 v127, v0
	v_mov_b32_e32 v128, v0
	v_mov_b32_e32 v129, v0
	s_cmp_eq_u32 s36, 1
	s_cbranch_scc1 .LBB0_852
	s_add_u32 s0, s22, 0xfff80080
	s_addc_u32 s1, s23, -1
	s_add_i32 s3, 0, 0x10000
	s_cmp_eq_u32 s28, 28
	s_cselect_b32 s15, s2, s1
	s_cselect_b32 s14, s8, s0
	v_add_u32_e32 v167, s3, v163
	s_cselect_b32 s1, s10, s25
	s_cselect_b32 s0, s24, s9
	s_add_i32 s6, 0, 0x14000
	ds_read_b128 v[140:143], v167
	ds_read_b128 v[144:147], v167 offset:1024
	ds_read_b128 v[148:151], v167 offset:2048
	ds_read_b128 v[172:175], v167 offset:3072
	v_add_u32_e32 v167, s6, v163
	ds_read_b128 v[190:193], v167
	ds_read_b128 v[194:197], v167 offset:1024
	ds_read_b128 v[198:201], v167 offset:2048
	ds_read_b128 v[202:205], v167 offset:3072
	s_add_i32 m0, s26, 0xc000
	ds_read_b128 v[206:209], v166
	ds_read_b128 v[210:213], v166 offset:1024
	ds_read_b128 v[214:217], v166 offset:2048
	ds_read_b128 v[218:221], v166 offset:3072
	ds_read_b128 v[222:225], v166 offset:4096
	ds_read_b128 v[226:229], v166 offset:5120
	ds_read_b128 v[230:233], v166 offset:6144
	ds_read_b128 v[234:237], v166 offset:7168
	global_load_lds_dwordx4 v136, s[22:23]
	s_add_i32 m0, s26, 0xe000
	s_nop 0
	global_load_lds_dwordx4 v138, s[22:23]
	s_waitcnt vmcnt(24)
	s_waitcnt lgkmcnt(0)
	s_barrier
	s_setprio 1
	s_waitcnt lgkmcnt(0)
	v_mfma_f32_16x16x32_bf16 v[126:129], v[140:143], v[206:209], v[126:129]
	v_mfma_f32_16x16x32_bf16 v[122:125], v[148:151], v[206:209], v[122:125]
	v_mfma_f32_16x16x32_bf16 v[118:121], v[140:143], v[214:217], v[118:121]
	v_mfma_f32_16x16x32_bf16 v[114:117], v[148:151], v[214:217], v[114:117]
	v_mfma_f32_16x16x32_bf16 v[110:113], v[140:143], v[222:225], v[110:113]
	v_mfma_f32_16x16x32_bf16 v[106:109], v[148:151], v[222:225], v[106:109]
	v_mfma_f32_16x16x32_bf16 v[102:105], v[140:143], v[230:233], v[102:105]
	v_mfma_f32_16x16x32_bf16 v[98:101], v[148:151], v[230:233], v[98:101]
	v_mfma_f32_16x16x32_bf16 v[126:129], v[144:147], v[210:213], v[126:129]
	v_mfma_f32_16x16x32_bf16 v[122:125], v[172:175], v[210:213], v[122:125]
	v_mfma_f32_16x16x32_bf16 v[118:121], v[144:147], v[218:221], v[118:121]
	v_mfma_f32_16x16x32_bf16 v[114:117], v[172:175], v[218:221], v[114:117]
	v_mfma_f32_16x16x32_bf16 v[110:113], v[144:147], v[226:229], v[110:113]
	v_mfma_f32_16x16x32_bf16 v[106:109], v[172:175], v[226:229], v[106:109]
	v_mfma_f32_16x16x32_bf16 v[102:105], v[144:147], v[234:237], v[102:105]
	v_mfma_f32_16x16x32_bf16 v[98:101], v[172:175], v[234:237], v[98:101]
	s_setprio 0
	s_setprio 1
	v_mfma_f32_16x16x32_bf16 v[62:65], v[190:193], v[206:209], v[62:65]
	v_mfma_f32_16x16x32_bf16 v[58:61], v[198:201], v[206:209], v[58:61]
	v_mfma_f32_16x16x32_bf16 v[54:57], v[190:193], v[214:217], v[54:57]
	v_mfma_f32_16x16x32_bf16 v[50:53], v[198:201], v[214:217], v[50:53]
	v_mfma_f32_16x16x32_bf16 v[46:49], v[190:193], v[222:225], v[46:49]
	v_mfma_f32_16x16x32_bf16 v[42:45], v[198:201], v[222:225], v[42:45]
	v_mfma_f32_16x16x32_bf16 v[38:41], v[190:193], v[230:233], v[38:41]
	v_mfma_f32_16x16x32_bf16 v[34:37], v[198:201], v[230:233], v[34:37]
	v_mfma_f32_16x16x32_bf16 v[62:65], v[194:197], v[210:213], v[62:65]
	v_mfma_f32_16x16x32_bf16 v[58:61], v[202:205], v[210:213], v[58:61]
	v_mfma_f32_16x16x32_bf16 v[54:57], v[194:197], v[218:221], v[54:57]
	v_mfma_f32_16x16x32_bf16 v[50:53], v[202:205], v[218:221], v[50:53]
	v_mfma_f32_16x16x32_bf16 v[46:49], v[194:197], v[226:229], v[46:49]
	v_mfma_f32_16x16x32_bf16 v[42:45], v[202:205], v[226:229], v[42:45]
	v_mfma_f32_16x16x32_bf16 v[38:41], v[194:197], v[234:237], v[38:41]
	v_mfma_f32_16x16x32_bf16 v[34:37], v[202:205], v[234:237], v[34:37]
	s_setprio 0
	s_barrier
	s_add_i32 s3, s3, s11
	v_lshl_add_u64 v[176:177], s[0:1], 0, v[4:5]
	s_mov_b32 m0, s3
	ds_read_b128 v[206:209], v166 offset:16384
	ds_read_b128 v[210:213], v166 offset:17408
	ds_read_b128 v[214:217], v166 offset:18432
	ds_read_b128 v[218:221], v166 offset:19456
	ds_read_b128 v[222:225], v166 offset:20480
	ds_read_b128 v[226:229], v166 offset:21504
	ds_read_b128 v[230:233], v166 offset:22528
	ds_read_b128 v[234:237], v166 offset:23552
	global_load_lds_dwordx4 v4, s[0:1]
	s_add_i32 m0, s3, 0x2000
	s_add_u32 s4, s0, 0x80000
	v_lshl_add_u64 v[238:239], s[0:1], 0, v[134:135]
	s_addc_u32 s5, s1, 0
	s_add_i32 s3, s6, s11
	global_load_lds_dwordx4 v134, s[0:1]
	s_mov_b32 m0, s3
	v_lshl_add_u64 v[242:243], s[14:15], 0, v[132:133]
	global_load_lds_dwordx4 v4, s[4:5]
	s_add_i32 m0, s3, 0x2000
	s_nop 0
	global_load_lds_dwordx4 v134, s[4:5]
	v_lshl_add_u64 v[240:241], s[14:15], 0, v[130:131]
	s_mov_b32 m0, s26
	s_nop 0
	global_load_lds_dwordx4 v130, s[14:15]
	s_mov_b32 m0, s27
	s_nop 0
	global_load_lds_dwordx4 v132, s[14:15]
	s_waitcnt vmcnt(24)
	s_waitcnt lgkmcnt(0)
	s_barrier
	s_setprio 1
	s_waitcnt lgkmcnt(0)
	v_mfma_f32_16x16x32_bf16 v[94:97], v[140:143], v[206:209], v[94:97]
	v_mfma_f32_16x16x32_bf16 v[90:93], v[148:151], v[206:209], v[90:93]
	v_mfma_f32_16x16x32_bf16 v[86:89], v[140:143], v[214:217], v[86:89]
	v_mfma_f32_16x16x32_bf16 v[82:85], v[148:151], v[214:217], v[82:85]
	v_mfma_f32_16x16x32_bf16 v[78:81], v[140:143], v[222:225], v[78:81]
	v_mfma_f32_16x16x32_bf16 v[74:77], v[148:151], v[222:225], v[74:77]
	v_mfma_f32_16x16x32_bf16 v[70:73], v[140:143], v[230:233], v[70:73]
	v_mfma_f32_16x16x32_bf16 v[66:69], v[148:151], v[230:233], v[66:69]
	v_mfma_f32_16x16x32_bf16 v[94:97], v[144:147], v[210:213], v[94:97]
	v_mfma_f32_16x16x32_bf16 v[90:93], v[172:175], v[210:213], v[90:93]
	v_mfma_f32_16x16x32_bf16 v[86:89], v[144:147], v[218:221], v[86:89]
	v_mfma_f32_16x16x32_bf16 v[82:85], v[172:175], v[218:221], v[82:85]
	v_mfma_f32_16x16x32_bf16 v[78:81], v[144:147], v[226:229], v[78:81]
	v_mfma_f32_16x16x32_bf16 v[74:77], v[172:175], v[226:229], v[74:77]
	v_mfma_f32_16x16x32_bf16 v[70:73], v[144:147], v[234:237], v[70:73]
	v_mfma_f32_16x16x32_bf16 v[66:69], v[172:175], v[234:237], v[66:69]
	s_setprio 0
	s_setprio 1
	v_mfma_f32_16x16x32_bf16 v[30:33], v[190:193], v[206:209], v[30:33]
	v_mfma_f32_16x16x32_bf16 v[26:29], v[198:201], v[206:209], v[26:29]
	v_mfma_f32_16x16x32_bf16 v[22:25], v[190:193], v[214:217], v[22:25]
	v_mfma_f32_16x16x32_bf16 v[18:21], v[198:201], v[214:217], v[18:21]
	v_mfma_f32_16x16x32_bf16 v[14:17], v[190:193], v[222:225], v[14:17]
	v_mfma_f32_16x16x32_bf16 v[10:13], v[198:201], v[222:225], v[10:13]
	v_mfma_f32_16x16x32_bf16 v[6:9], v[190:193], v[230:233], v[6:9]
	v_mfma_f32_16x16x32_bf16 v[0:3], v[198:201], v[230:233], v[0:3]
	v_mfma_f32_16x16x32_bf16 v[30:33], v[194:197], v[210:213], v[30:33]
	v_mfma_f32_16x16x32_bf16 v[26:29], v[202:205], v[210:213], v[26:29]
	v_mfma_f32_16x16x32_bf16 v[22:25], v[194:197], v[218:221], v[22:25]
	v_mfma_f32_16x16x32_bf16 v[18:21], v[202:205], v[218:221], v[18:21]
	v_mfma_f32_16x16x32_bf16 v[14:17], v[194:197], v[226:229], v[14:17]
	v_mfma_f32_16x16x32_bf16 v[10:13], v[202:205], v[226:229], v[10:13]
	v_mfma_f32_16x16x32_bf16 v[6:9], v[194:197], v[234:237], v[6:9]
	v_mfma_f32_16x16x32_bf16 v[0:3], v[202:205], v[234:237], v[0:3]
	s_setprio 0
	s_barrier
	s_branch .Lpeelmid_852
.LBB0_852:
	s_add_u32 s0, s22, 0xfff80080
	s_addc_u32 s1, s23, -1
	s_add_i32 s3, 0, 0x10000
	s_cmp_eq_u32 s28, 28
	s_cselect_b32 s15, s2, s1
	s_cselect_b32 s14, s8, s0
	v_add_u32_e32 v167, s3, v163
	s_cselect_b32 s1, s10, s25
	s_cselect_b32 s0, s24, s9
	s_add_i32 s6, 0, 0x14000
	ds_read_b128 v[140:143], v167
	ds_read_b128 v[144:147], v167 offset:1024
	ds_read_b128 v[148:151], v167 offset:2048
	ds_read_b128 v[172:175], v167 offset:3072
	v_add_u32_e32 v167, s6, v163
	ds_read_b128 v[190:193], v167
	ds_read_b128 v[194:197], v167 offset:1024
	ds_read_b128 v[198:201], v167 offset:2048
	ds_read_b128 v[202:205], v167 offset:3072
	s_add_i32 m0, s26, 0xc000
	ds_read_b128 v[206:209], v166
	ds_read_b128 v[210:213], v166 offset:1024
	ds_read_b128 v[214:217], v166 offset:2048
	ds_read_b128 v[218:221], v166 offset:3072
	ds_read_b128 v[222:225], v166 offset:4096
	ds_read_b128 v[226:229], v166 offset:5120
	ds_read_b128 v[230:233], v166 offset:6144
	ds_read_b128 v[234:237], v166 offset:7168
	global_load_lds_dwordx4 v136, s[22:23]
	s_add_i32 m0, s26, 0xe000
	s_nop 0
	global_load_lds_dwordx4 v138, s[22:23]
	s_waitcnt vmcnt(8)
	s_waitcnt lgkmcnt(0)
	s_barrier
	s_setprio 1
	s_waitcnt lgkmcnt(0)
	v_mfma_f32_16x16x32_bf16 v[126:129], v[140:143], v[206:209], v[126:129]
	v_mfma_f32_16x16x32_bf16 v[122:125], v[148:151], v[206:209], v[122:125]
	v_mfma_f32_16x16x32_bf16 v[118:121], v[140:143], v[214:217], v[118:121]
	v_mfma_f32_16x16x32_bf16 v[114:117], v[148:151], v[214:217], v[114:117]
	v_mfma_f32_16x16x32_bf16 v[110:113], v[140:143], v[222:225], v[110:113]
	v_mfma_f32_16x16x32_bf16 v[106:109], v[148:151], v[222:225], v[106:109]
	v_mfma_f32_16x16x32_bf16 v[102:105], v[140:143], v[230:233], v[102:105]
	v_mfma_f32_16x16x32_bf16 v[98:101], v[148:151], v[230:233], v[98:101]
	v_mfma_f32_16x16x32_bf16 v[126:129], v[144:147], v[210:213], v[126:129]
	v_mfma_f32_16x16x32_bf16 v[122:125], v[172:175], v[210:213], v[122:125]
	v_mfma_f32_16x16x32_bf16 v[118:121], v[144:147], v[218:221], v[118:121]
	v_mfma_f32_16x16x32_bf16 v[114:117], v[172:175], v[218:221], v[114:117]
	v_mfma_f32_16x16x32_bf16 v[110:113], v[144:147], v[226:229], v[110:113]
	v_mfma_f32_16x16x32_bf16 v[106:109], v[172:175], v[226:229], v[106:109]
	v_mfma_f32_16x16x32_bf16 v[102:105], v[144:147], v[234:237], v[102:105]
	v_mfma_f32_16x16x32_bf16 v[98:101], v[172:175], v[234:237], v[98:101]
	s_setprio 0
	s_setprio 1
	v_mfma_f32_16x16x32_bf16 v[62:65], v[190:193], v[206:209], v[62:65]
	v_mfma_f32_16x16x32_bf16 v[58:61], v[198:201], v[206:209], v[58:61]
	v_mfma_f32_16x16x32_bf16 v[54:57], v[190:193], v[214:217], v[54:57]
	v_mfma_f32_16x16x32_bf16 v[50:53], v[198:201], v[214:217], v[50:53]
	v_mfma_f32_16x16x32_bf16 v[46:49], v[190:193], v[222:225], v[46:49]
	v_mfma_f32_16x16x32_bf16 v[42:45], v[198:201], v[222:225], v[42:45]
	v_mfma_f32_16x16x32_bf16 v[38:41], v[190:193], v[230:233], v[38:41]
	v_mfma_f32_16x16x32_bf16 v[34:37], v[198:201], v[230:233], v[34:37]
	v_mfma_f32_16x16x32_bf16 v[62:65], v[194:197], v[210:213], v[62:65]
	v_mfma_f32_16x16x32_bf16 v[58:61], v[202:205], v[210:213], v[58:61]
	v_mfma_f32_16x16x32_bf16 v[54:57], v[194:197], v[218:221], v[54:57]
	v_mfma_f32_16x16x32_bf16 v[50:53], v[202:205], v[218:221], v[50:53]
	v_mfma_f32_16x16x32_bf16 v[46:49], v[194:197], v[226:229], v[46:49]
	v_mfma_f32_16x16x32_bf16 v[42:45], v[202:205], v[226:229], v[42:45]
	v_mfma_f32_16x16x32_bf16 v[38:41], v[194:197], v[234:237], v[38:41]
	v_mfma_f32_16x16x32_bf16 v[34:37], v[202:205], v[234:237], v[34:37]
	s_setprio 0
	s_barrier
	s_add_i32 s3, s3, s11
	v_lshl_add_u64 v[176:177], s[0:1], 0, v[4:5]
	s_mov_b32 m0, s3
	ds_read_b128 v[206:209], v166 offset:16384
	ds_read_b128 v[210:213], v166 offset:17408
	ds_read_b128 v[214:217], v166 offset:18432
	ds_read_b128 v[218:221], v166 offset:19456
	ds_read_b128 v[222:225], v166 offset:20480
	ds_read_b128 v[226:229], v166 offset:21504
	ds_read_b128 v[230:233], v166 offset:22528
	ds_read_b128 v[234:237], v166 offset:23552
	global_load_lds_dwordx4 v4, s[0:1]
	s_add_i32 m0, s3, 0x2000
	s_add_u32 s4, s0, 0x80000
	v_lshl_add_u64 v[238:239], s[0:1], 0, v[134:135]
	s_addc_u32 s5, s1, 0
	s_add_i32 s3, s6, s11
	global_load_lds_dwordx4 v134, s[0:1]
	s_mov_b32 m0, s3
	v_lshl_add_u64 v[242:243], s[14:15], 0, v[132:133]
	global_load_lds_dwordx4 v4, s[4:5]
	s_add_i32 m0, s3, 0x2000
	s_nop 0
	global_load_lds_dwordx4 v134, s[4:5]
	v_lshl_add_u64 v[240:241], s[14:15], 0, v[130:131]
	s_mov_b32 m0, s26
	s_nop 0
	global_load_lds_dwordx4 v130, s[14:15]
	s_mov_b32 m0, s27
	s_nop 0
	global_load_lds_dwordx4 v132, s[14:15]
	s_waitcnt vmcnt(8)
	s_waitcnt lgkmcnt(0)
	s_barrier
	s_setprio 1
	s_waitcnt lgkmcnt(0)
	v_mfma_f32_16x16x32_bf16 v[94:97], v[140:143], v[206:209], v[94:97]
	v_mfma_f32_16x16x32_bf16 v[90:93], v[148:151], v[206:209], v[90:93]
	v_mfma_f32_16x16x32_bf16 v[86:89], v[140:143], v[214:217], v[86:89]
	v_mfma_f32_16x16x32_bf16 v[82:85], v[148:151], v[214:217], v[82:85]
	v_mfma_f32_16x16x32_bf16 v[78:81], v[140:143], v[222:225], v[78:81]
	v_mfma_f32_16x16x32_bf16 v[74:77], v[148:151], v[222:225], v[74:77]
	v_mfma_f32_16x16x32_bf16 v[70:73], v[140:143], v[230:233], v[70:73]
	v_mfma_f32_16x16x32_bf16 v[66:69], v[148:151], v[230:233], v[66:69]
	v_mfma_f32_16x16x32_bf16 v[94:97], v[144:147], v[210:213], v[94:97]
	v_mfma_f32_16x16x32_bf16 v[90:93], v[172:175], v[210:213], v[90:93]
	v_mfma_f32_16x16x32_bf16 v[86:89], v[144:147], v[218:221], v[86:89]
	v_mfma_f32_16x16x32_bf16 v[82:85], v[172:175], v[218:221], v[82:85]
	v_mfma_f32_16x16x32_bf16 v[78:81], v[144:147], v[226:229], v[78:81]
	v_mfma_f32_16x16x32_bf16 v[74:77], v[172:175], v[226:229], v[74:77]
	v_mfma_f32_16x16x32_bf16 v[70:73], v[144:147], v[234:237], v[70:73]
	v_mfma_f32_16x16x32_bf16 v[66:69], v[172:175], v[234:237], v[66:69]
	s_setprio 0
	s_setprio 1
	v_mfma_f32_16x16x32_bf16 v[30:33], v[190:193], v[206:209], v[30:33]
	v_mfma_f32_16x16x32_bf16 v[26:29], v[198:201], v[206:209], v[26:29]
	v_mfma_f32_16x16x32_bf16 v[22:25], v[190:193], v[214:217], v[22:25]
	v_mfma_f32_16x16x32_bf16 v[18:21], v[198:201], v[214:217], v[18:21]
	v_mfma_f32_16x16x32_bf16 v[14:17], v[190:193], v[222:225], v[14:17]
	v_mfma_f32_16x16x32_bf16 v[10:13], v[198:201], v[222:225], v[10:13]
	v_mfma_f32_16x16x32_bf16 v[6:9], v[190:193], v[230:233], v[6:9]
	v_mfma_f32_16x16x32_bf16 v[0:3], v[198:201], v[230:233], v[0:3]
	v_mfma_f32_16x16x32_bf16 v[30:33], v[194:197], v[210:213], v[30:33]
	v_mfma_f32_16x16x32_bf16 v[26:29], v[202:205], v[210:213], v[26:29]
	v_mfma_f32_16x16x32_bf16 v[22:25], v[194:197], v[218:221], v[22:25]
	v_mfma_f32_16x16x32_bf16 v[18:21], v[202:205], v[218:221], v[18:21]
	v_mfma_f32_16x16x32_bf16 v[14:17], v[194:197], v[226:229], v[14:17]
	v_mfma_f32_16x16x32_bf16 v[10:13], v[202:205], v[226:229], v[10:13]
	v_mfma_f32_16x16x32_bf16 v[6:9], v[194:197], v[234:237], v[6:9]
	v_mfma_f32_16x16x32_bf16 v[0:3], v[202:205], v[234:237], v[0:3]
	s_setprio 0
	s_barrier
.Lpeelmid_852:
	s_add_i32 s3, 0, 0x18000
	v_add_u32_e32 v167, s3, v163
	s_add_i32 s6, 0, 0x1c000
	ds_read_b128 v[140:143], v167
	ds_read_b128 v[144:147], v167 offset:1024
	ds_read_b128 v[148:151], v167 offset:2048
	ds_read_b128 v[172:175], v167 offset:3072
	v_add_u32_e32 v167, s6, v163
	ds_read_b128 v[190:193], v167
	ds_read_b128 v[194:197], v167 offset:1024
	ds_read_b128 v[198:201], v167 offset:2048
	ds_read_b128 v[202:205], v167 offset:3072
	s_add_u32 s4, s14, 0x80000
	s_addc_u32 s5, s15, 0
	s_mov_b32 m0, s30
	ds_read_b128 v[206:209], v166 offset:32768
	ds_read_b128 v[210:213], v166 offset:33792
	ds_read_b128 v[214:217], v166 offset:34816
	ds_read_b128 v[218:221], v166 offset:35840
	ds_read_b128 v[222:225], v166 offset:36864
	ds_read_b128 v[226:229], v166 offset:37888
	ds_read_b128 v[230:233], v166 offset:38912
	ds_read_b128 v[234:237], v166 offset:39936
	global_load_lds_dwordx4 v130, s[4:5]
	v_lshl_add_u64 v[244:245], s[4:5], 0, v[132:133]
	s_mov_b32 m0, s31
	s_nop 0
	global_load_lds_dwordx4 v132, s[4:5]
	s_waitcnt vmcnt(8)
	s_waitcnt lgkmcnt(0)
	s_barrier
	s_setprio 1
	s_waitcnt lgkmcnt(0)
	v_mfma_f32_16x16x32_bf16 v[126:129], v[140:143], v[206:209], v[126:129]
	v_mfma_f32_16x16x32_bf16 v[122:125], v[148:151], v[206:209], v[122:125]
	v_mfma_f32_16x16x32_bf16 v[118:121], v[140:143], v[214:217], v[118:121]
	v_mfma_f32_16x16x32_bf16 v[114:117], v[148:151], v[214:217], v[114:117]
	v_mfma_f32_16x16x32_bf16 v[110:113], v[140:143], v[222:225], v[110:113]
	v_mfma_f32_16x16x32_bf16 v[106:109], v[148:151], v[222:225], v[106:109]
	v_mfma_f32_16x16x32_bf16 v[102:105], v[140:143], v[230:233], v[102:105]
	v_mfma_f32_16x16x32_bf16 v[98:101], v[148:151], v[230:233], v[98:101]
	v_mfma_f32_16x16x32_bf16 v[126:129], v[144:147], v[210:213], v[126:129]
	v_mfma_f32_16x16x32_bf16 v[122:125], v[172:175], v[210:213], v[122:125]
	v_mfma_f32_16x16x32_bf16 v[118:121], v[144:147], v[218:221], v[118:121]
	v_mfma_f32_16x16x32_bf16 v[114:117], v[172:175], v[218:221], v[114:117]
	v_mfma_f32_16x16x32_bf16 v[110:113], v[144:147], v[226:229], v[110:113]
	v_mfma_f32_16x16x32_bf16 v[106:109], v[172:175], v[226:229], v[106:109]
	v_mfma_f32_16x16x32_bf16 v[102:105], v[144:147], v[234:237], v[102:105]
	v_mfma_f32_16x16x32_bf16 v[98:101], v[172:175], v[234:237], v[98:101]
	s_setprio 0
	s_setprio 1
	v_mfma_f32_16x16x32_bf16 v[62:65], v[190:193], v[206:209], v[62:65]
	v_mfma_f32_16x16x32_bf16 v[58:61], v[198:201], v[206:209], v[58:61]
	v_mfma_f32_16x16x32_bf16 v[54:57], v[190:193], v[214:217], v[54:57]
	v_mfma_f32_16x16x32_bf16 v[50:53], v[198:201], v[214:217], v[50:53]
	v_mfma_f32_16x16x32_bf16 v[46:49], v[190:193], v[222:225], v[46:49]
	v_mfma_f32_16x16x32_bf16 v[42:45], v[198:201], v[222:225], v[42:45]
	v_mfma_f32_16x16x32_bf16 v[38:41], v[190:193], v[230:233], v[38:41]
	v_mfma_f32_16x16x32_bf16 v[34:37], v[198:201], v[230:233], v[34:37]
	v_mfma_f32_16x16x32_bf16 v[62:65], v[194:197], v[210:213], v[62:65]
	v_mfma_f32_16x16x32_bf16 v[58:61], v[202:205], v[210:213], v[58:61]
	v_mfma_f32_16x16x32_bf16 v[54:57], v[194:197], v[218:221], v[54:57]
	v_mfma_f32_16x16x32_bf16 v[50:53], v[202:205], v[218:221], v[50:53]
	v_mfma_f32_16x16x32_bf16 v[46:49], v[194:197], v[226:229], v[46:49]
	v_mfma_f32_16x16x32_bf16 v[42:45], v[202:205], v[226:229], v[42:45]
	v_mfma_f32_16x16x32_bf16 v[38:41], v[194:197], v[234:237], v[38:41]
	v_mfma_f32_16x16x32_bf16 v[34:37], v[202:205], v[234:237], v[34:37]
	s_setprio 0
	s_barrier
	s_add_i32 s3, s3, s11
	v_lshl_add_u64 v[176:177], v[176:177], 0, s[70:71]
	s_mov_b32 m0, s3
	ds_read_b128 v[206:209], v166 offset:49152
	ds_read_b128 v[210:213], v166 offset:50176
	ds_read_b128 v[214:217], v166 offset:51200
	ds_read_b128 v[218:221], v166 offset:52224
	ds_read_b128 v[222:225], v166 offset:53248
	ds_read_b128 v[226:229], v166 offset:54272
	ds_read_b128 v[230:233], v166 offset:55296
	ds_read_b128 v[234:237], v166 offset:56320
	global_load_lds_dwordx4 v[176:177], off
	s_add_i32 m0, s3, 0x2000
	s_add_u32 s0, s0, 0x80080
	v_lshl_add_u64 v[176:177], v[238:239], 0, s[70:71]
	s_addc_u32 s1, s1, 0
	s_add_i32 s3, s6, s11
	global_load_lds_dwordx4 v[176:177], off
	s_mov_b32 m0, s3
	s_nop 0
	global_load_lds_dwordx4 v4, s[0:1]
	s_add_i32 m0, s3, 0x2000
	s_nop 0
	global_load_lds_dwordx4 v134, s[0:1]
	v_lshl_add_u64 v[176:177], v[240:241], 0, s[70:71]
	s_mov_b32 m0, s34
	s_nop 0
	global_load_lds_dwordx4 v[176:177], off
	v_lshl_add_u64 v[176:177], v[242:243], 0, s[70:71]
	s_mov_b32 m0, s35
	s_nop 0
	global_load_lds_dwordx4 v[176:177], off
	s_waitcnt vmcnt(8)
	s_waitcnt lgkmcnt(0)
	s_barrier
	s_setprio 1
	s_waitcnt lgkmcnt(0)
	v_mfma_f32_16x16x32_bf16 v[94:97], v[140:143], v[206:209], v[94:97]
	v_mfma_f32_16x16x32_bf16 v[90:93], v[148:151], v[206:209], v[90:93]
	v_mfma_f32_16x16x32_bf16 v[86:89], v[140:143], v[214:217], v[86:89]
	v_mfma_f32_16x16x32_bf16 v[82:85], v[148:151], v[214:217], v[82:85]
	v_mfma_f32_16x16x32_bf16 v[78:81], v[140:143], v[222:225], v[78:81]
	v_mfma_f32_16x16x32_bf16 v[74:77], v[148:151], v[222:225], v[74:77]
	v_mfma_f32_16x16x32_bf16 v[70:73], v[140:143], v[230:233], v[70:73]
	v_mfma_f32_16x16x32_bf16 v[66:69], v[148:151], v[230:233], v[66:69]
	v_mfma_f32_16x16x32_bf16 v[94:97], v[144:147], v[210:213], v[94:97]
	v_mfma_f32_16x16x32_bf16 v[90:93], v[172:175], v[210:213], v[90:93]
	v_mfma_f32_16x16x32_bf16 v[86:89], v[144:147], v[218:221], v[86:89]
	v_mfma_f32_16x16x32_bf16 v[82:85], v[172:175], v[218:221], v[82:85]
	v_mfma_f32_16x16x32_bf16 v[78:81], v[144:147], v[226:229], v[78:81]
	v_mfma_f32_16x16x32_bf16 v[74:77], v[172:175], v[226:229], v[74:77]
	v_mfma_f32_16x16x32_bf16 v[70:73], v[144:147], v[234:237], v[70:73]
	v_mfma_f32_16x16x32_bf16 v[66:69], v[172:175], v[234:237], v[66:69]
	s_setprio 0
	s_setprio 1
	v_mfma_f32_16x16x32_bf16 v[30:33], v[190:193], v[206:209], v[30:33]
	v_mfma_f32_16x16x32_bf16 v[26:29], v[198:201], v[206:209], v[26:29]
	v_mfma_f32_16x16x32_bf16 v[22:25], v[190:193], v[214:217], v[22:25]
	v_mfma_f32_16x16x32_bf16 v[18:21], v[198:201], v[214:217], v[18:21]
	v_mfma_f32_16x16x32_bf16 v[14:17], v[190:193], v[222:225], v[14:17]
	v_mfma_f32_16x16x32_bf16 v[10:13], v[198:201], v[222:225], v[10:13]
	v_mfma_f32_16x16x32_bf16 v[6:9], v[190:193], v[230:233], v[6:9]
	v_mfma_f32_16x16x32_bf16 v[0:3], v[198:201], v[230:233], v[0:3]
	v_mfma_f32_16x16x32_bf16 v[30:33], v[194:197], v[210:213], v[30:33]
	v_mfma_f32_16x16x32_bf16 v[26:29], v[202:205], v[210:213], v[26:29]
	v_mfma_f32_16x16x32_bf16 v[22:25], v[194:197], v[218:221], v[22:25]
	v_mfma_f32_16x16x32_bf16 v[18:21], v[202:205], v[218:221], v[18:21]
	v_mfma_f32_16x16x32_bf16 v[14:17], v[194:197], v[226:229], v[14:17]
	v_mfma_f32_16x16x32_bf16 v[10:13], v[202:205], v[226:229], v[10:13]
	v_mfma_f32_16x16x32_bf16 v[6:9], v[194:197], v[234:237], v[6:9]
	v_mfma_f32_16x16x32_bf16 v[0:3], v[202:205], v[234:237], v[0:3]
	s_setprio 0
	s_barrier
	s_add_i32 s28, s28, 2
	s_add_u32 s22, s22, 0x100
	s_addc_u32 s23, s23, 0
	s_add_u32 s9, s9, 0x100
	s_addc_u32 s25, s25, 0
	s_cmp_gt_u32 s28, 29
	s_cbranch_scc0 .LBB0_852
	s_and_b64 vcc, exec, s[48:49]
	s_cbranch_vccz .LBB0_855
	s_barrier
